# both GEMM tiles: MFMA operands swapped so each lane holds four consecutive columns, accumulators staged with 16 ds_write_b128 instead of 64 ds_write_b32
# speedup vs baseline: 1.0039x; 1.0039x over previous
.Lip_prdone:
	s_barrier
	s_add_i32 m0, s81, 0
	s_nop 0
	global_load_lds_dwordx4 v240, s[76:77]
	s_add_i32 m0, s81, 4096
	s_nop 0
	global_load_lds_dwordx4 v241, s[76:77]
	s_add_i32 m0, s81, 8192
	s_nop 0
	global_load_lds_dwordx4 v242, s[76:77]
	s_add_i32 m0, s81, 12288
	s_nop 0
	global_load_lds_dwordx4 v243, s[76:77]
	s_add_i32 m0, s81, 16384
	s_nop 0
	global_load_lds_dwordx4 v240, s[78:79]
	s_add_i32 m0, s81, 20480
	s_nop 0
	global_load_lds_dwordx4 v241, s[78:79]
	s_add_i32 m0, s81, 24576
	s_nop 0
	global_load_lds_dwordx4 v242, s[78:79]
	s_add_i32 m0, s81, 28672
	s_nop 0
	global_load_lds_dwordx4 v243, s[78:79]
	s_add_u32 s76, s76, 0x80
	s_addc_u32 s77, s77, 0
	s_add_u32 s78, s78, 0x80
	s_addc_u32 s79, s79, 0
	v_and_b32_e32 v100, 15, v138
	v_bfe_u32 v101, v138, 4, 2
	v_lshrrev_b32_e32 v102, 1, v100
	v_xor_b32_e32 v102, v102, v101
	v_lshlrev_b32_e32 v102, 4, v102
	v_lshrrev_b32_e32 v103, 1, v99
	v_and_b32_e32 v99, 1, v99
	v_lshl_add_u32 v96, v103, 6, v100
	v_lshl_add_u32 v244, v96, 7, v102
	v_xor_b32_e32 v245, 64, v244
	v_lshl_add_u32 v96, v99, 6, v100
	v_lshl_add_u32 v246, v96, 7, v102
	v_add_u32_e32 v246, 0x4000, v246
	v_xor_b32_e32 v247, 64, v246
	v_lshl_add_u32 v96, v103, 6, v100
	s_movk_i32 s0, 0x210
	v_mul_lo_u32 v96, v96, s0
	v_lshlrev_b32_e32 v97, 6, v99
	v_lshl_add_u32 v97, v101, 2, v97
	v_lshl_add_u32 v248, v97, 2, v96
	s_movk_i32 s82, 7
	s_waitcnt vmcnt(0)
	s_barrier
	ds_read_b128 v[64:67], v244 offset:0
	ds_read_b128 v[80:83], v246 offset:0
	ds_read_b128 v[84:87], v246 offset:2048
	ds_read_b128 v[88:91], v246 offset:4096
	ds_read_b128 v[92:95], v246 offset:6144
	ds_read_b128 v[68:71], v244 offset:2048
	ds_read_b128 v[72:75], v244 offset:4096
	ds_read_b128 v[76:79], v244 offset:6144
	s_waitcnt lgkmcnt(6)
	v_mfma_f32_16x16x32_bf16 v[0:3], v[80:83], v[64:67], 0
	ds_read_b128 v[208:211], v245 offset:0
	s_add_i32 m0, s81, 32768
	s_waitcnt lgkmcnt(6)
	v_mfma_f32_16x16x32_bf16 v[4:7], v[84:87], v[64:67], 0
	ds_read_b128 v[224:227], v247 offset:0
	global_load_lds_dwordx4 v240, s[76:77]
	s_waitcnt lgkmcnt(6)
	v_mfma_f32_16x16x32_bf16 v[8:11], v[88:91], v[64:67], 0
	ds_read_b128 v[228:231], v247 offset:2048
	s_add_i32 m0, s81, 36864
	s_waitcnt lgkmcnt(6)
	v_mfma_f32_16x16x32_bf16 v[12:15], v[92:95], v[64:67], 0
	ds_read_b128 v[232:235], v247 offset:4096
	global_load_lds_dwordx4 v241, s[76:77]
	s_waitcnt lgkmcnt(6)
	v_mfma_f32_16x16x32_bf16 v[16:19], v[80:83], v[68:71], 0
	ds_read_b128 v[236:239], v247 offset:6144
	s_add_i32 m0, s81, 40960
	v_mfma_f32_16x16x32_bf16 v[20:23], v[84:87], v[68:71], 0
	ds_read_b128 v[212:215], v245 offset:2048
	global_load_lds_dwordx4 v242, s[76:77]
	v_mfma_f32_16x16x32_bf16 v[24:27], v[88:91], v[68:71], 0
	ds_read_b128 v[216:219], v245 offset:4096
	s_add_i32 m0, s81, 45056
	v_mfma_f32_16x16x32_bf16 v[28:31], v[92:95], v[68:71], 0
	ds_read_b128 v[220:223], v245 offset:6144
	global_load_lds_dwordx4 v243, s[76:77]
	s_waitcnt lgkmcnt(9)
	v_mfma_f32_16x16x32_bf16 v[32:35], v[80:83], v[72:75], 0
	s_add_i32 m0, s81, 49152
	v_mfma_f32_16x16x32_bf16 v[36:39], v[84:87], v[72:75], 0
	global_load_lds_dwordx4 v240, s[78:79]
	v_mfma_f32_16x16x32_bf16 v[40:43], v[88:91], v[72:75], 0
	s_add_i32 m0, s81, 53248
	v_mfma_f32_16x16x32_bf16 v[44:47], v[92:95], v[72:75], 0
	global_load_lds_dwordx4 v241, s[78:79]
	s_waitcnt lgkmcnt(8)
	v_mfma_f32_16x16x32_bf16 v[48:51], v[80:83], v[76:79], 0
	s_add_i32 m0, s81, 57344
	v_mfma_f32_16x16x32_bf16 v[52:55], v[84:87], v[76:79], 0
	global_load_lds_dwordx4 v242, s[78:79]
	v_mfma_f32_16x16x32_bf16 v[56:59], v[88:91], v[76:79], 0
	s_add_i32 m0, s81, 61440
	v_mfma_f32_16x16x32_bf16 v[60:63], v[92:95], v[76:79], 0
	global_load_lds_dwordx4 v243, s[78:79]
	s_waitcnt lgkmcnt(6)
	v_mfma_f32_16x16x32_bf16 v[0:3], v[224:227], v[208:211], v[0:3]
	s_add_u32 s76, s76, 0x80
	s_addc_u32 s77, s77, 0
	s_waitcnt lgkmcnt(5)
	v_mfma_f32_16x16x32_bf16 v[4:7], v[228:231], v[208:211], v[4:7]
	s_waitcnt lgkmcnt(4)
	v_mfma_f32_16x16x32_bf16 v[8:11], v[232:235], v[208:211], v[8:11]
	s_add_u32 s78, s78, 0x80
	s_addc_u32 s79, s79, 0
	s_waitcnt lgkmcnt(3)
	v_mfma_f32_16x16x32_bf16 v[12:15], v[236:239], v[208:211], v[12:15]
	s_waitcnt lgkmcnt(2)
	v_mfma_f32_16x16x32_bf16 v[16:19], v[224:227], v[212:215], v[16:19]
	v_mfma_f32_16x16x32_bf16 v[20:23], v[228:231], v[212:215], v[20:23]
	v_mfma_f32_16x16x32_bf16 v[24:27], v[232:235], v[212:215], v[24:27]
	v_mfma_f32_16x16x32_bf16 v[28:31], v[236:239], v[212:215], v[28:31]
	s_waitcnt lgkmcnt(1)
	v_mfma_f32_16x16x32_bf16 v[32:35], v[224:227], v[216:219], v[32:35]
	v_mfma_f32_16x16x32_bf16 v[36:39], v[228:231], v[216:219], v[36:39]
	v_mfma_f32_16x16x32_bf16 v[40:43], v[232:235], v[216:219], v[40:43]
	v_mfma_f32_16x16x32_bf16 v[44:47], v[236:239], v[216:219], v[44:47]
	s_waitcnt lgkmcnt(0)
	v_mfma_f32_16x16x32_bf16 v[48:51], v[224:227], v[220:223], v[48:51]
	v_mfma_f32_16x16x32_bf16 v[52:55], v[228:231], v[220:223], v[52:55]
	v_mfma_f32_16x16x32_bf16 v[56:59], v[232:235], v[220:223], v[56:59]
	v_mfma_f32_16x16x32_bf16 v[60:63], v[236:239], v[220:223], v[60:63]
	s_waitcnt vmcnt(0)
	s_barrier
	ds_read_b128 v[64:67], v244 offset:32768
	ds_read_b128 v[80:83], v246 offset:32768
	ds_read_b128 v[84:87], v246 offset:34816
	ds_read_b128 v[88:91], v246 offset:36864
	ds_read_b128 v[92:95], v246 offset:38912
	ds_read_b128 v[68:71], v244 offset:34816
	ds_read_b128 v[72:75], v244 offset:36864
	ds_read_b128 v[76:79], v244 offset:38912
	s_waitcnt lgkmcnt(6)
	v_mfma_f32_16x16x32_bf16 v[0:3], v[80:83], v[64:67], v[0:3]
	ds_read_b128 v[208:211], v245 offset:32768
	s_add_i32 m0, s81, 0
	s_waitcnt lgkmcnt(6)
	v_mfma_f32_16x16x32_bf16 v[4:7], v[84:87], v[64:67], v[4:7]
	ds_read_b128 v[224:227], v247 offset:32768
	global_load_lds_dwordx4 v240, s[76:77]
	s_waitcnt lgkmcnt(6)
	v_mfma_f32_16x16x32_bf16 v[8:11], v[88:91], v[64:67], v[8:11]
	ds_read_b128 v[228:231], v247 offset:34816
	s_add_i32 m0, s81, 4096
	s_waitcnt lgkmcnt(6)
	v_mfma_f32_16x16x32_bf16 v[12:15], v[92:95], v[64:67], v[12:15]
	ds_read_b128 v[232:235], v247 offset:36864
	global_load_lds_dwordx4 v241, s[76:77]
	s_waitcnt lgkmcnt(6)
	v_mfma_f32_16x16x32_bf16 v[16:19], v[80:83], v[68:71], v[16:19]
	ds_read_b128 v[236:239], v247 offset:38912
	s_add_i32 m0, s81, 8192
	v_mfma_f32_16x16x32_bf16 v[20:23], v[84:87], v[68:71], v[20:23]
	ds_read_b128 v[212:215], v245 offset:34816
	global_load_lds_dwordx4 v242, s[76:77]
	v_mfma_f32_16x16x32_bf16 v[24:27], v[88:91], v[68:71], v[24:27]
	ds_read_b128 v[216:219], v245 offset:36864
	s_add_i32 m0, s81, 12288
	v_mfma_f32_16x16x32_bf16 v[28:31], v[92:95], v[68:71], v[28:31]
	ds_read_b128 v[220:223], v245 offset:38912
	global_load_lds_dwordx4 v243, s[76:77]
	s_waitcnt lgkmcnt(9)
	v_mfma_f32_16x16x32_bf16 v[32:35], v[80:83], v[72:75], v[32:35]
	s_add_i32 m0, s81, 16384
	v_mfma_f32_16x16x32_bf16 v[36:39], v[84:87], v[72:75], v[36:39]
	global_load_lds_dwordx4 v240, s[78:79]
	v_mfma_f32_16x16x32_bf16 v[40:43], v[88:91], v[72:75], v[40:43]
	s_add_i32 m0, s81, 20480
	v_mfma_f32_16x16x32_bf16 v[44:47], v[92:95], v[72:75], v[44:47]
	global_load_lds_dwordx4 v241, s[78:79]
	s_waitcnt lgkmcnt(8)
	v_mfma_f32_16x16x32_bf16 v[48:51], v[80:83], v[76:79], v[48:51]
	s_add_i32 m0, s81, 24576
	v_mfma_f32_16x16x32_bf16 v[52:55], v[84:87], v[76:79], v[52:55]
	global_load_lds_dwordx4 v242, s[78:79]
	v_mfma_f32_16x16x32_bf16 v[56:59], v[88:91], v[76:79], v[56:59]
	s_add_i32 m0, s81, 28672
	v_mfma_f32_16x16x32_bf16 v[60:63], v[92:95], v[76:79], v[60:63]
	global_load_lds_dwordx4 v243, s[78:79]
	s_waitcnt lgkmcnt(6)
	v_mfma_f32_16x16x32_bf16 v[0:3], v[224:227], v[208:211], v[0:3]
	s_add_u32 s76, s76, 0x80
	s_addc_u32 s77, s77, 0
	s_waitcnt lgkmcnt(5)
	v_mfma_f32_16x16x32_bf16 v[4:7], v[228:231], v[208:211], v[4:7]
	s_waitcnt lgkmcnt(4)
	v_mfma_f32_16x16x32_bf16 v[8:11], v[232:235], v[208:211], v[8:11]
	s_add_u32 s78, s78, 0x80
	s_addc_u32 s79, s79, 0
	s_waitcnt lgkmcnt(3)
	v_mfma_f32_16x16x32_bf16 v[12:15], v[236:239], v[208:211], v[12:15]
	s_waitcnt lgkmcnt(2)
	v_mfma_f32_16x16x32_bf16 v[16:19], v[224:227], v[212:215], v[16:19]
	v_mfma_f32_16x16x32_bf16 v[20:23], v[228:231], v[212:215], v[20:23]
	v_mfma_f32_16x16x32_bf16 v[24:27], v[232:235], v[212:215], v[24:27]
	v_mfma_f32_16x16x32_bf16 v[28:31], v[236:239], v[212:215], v[28:31]
	s_waitcnt lgkmcnt(1)
	v_mfma_f32_16x16x32_bf16 v[32:35], v[224:227], v[216:219], v[32:35]
	v_mfma_f32_16x16x32_bf16 v[36:39], v[228:231], v[216:219], v[36:39]
	v_mfma_f32_16x16x32_bf16 v[40:43], v[232:235], v[216:219], v[40:43]
	v_mfma_f32_16x16x32_bf16 v[44:47], v[236:239], v[216:219], v[44:47]
	s_waitcnt lgkmcnt(0)
	v_mfma_f32_16x16x32_bf16 v[48:51], v[224:227], v[220:223], v[48:51]
	v_mfma_f32_16x16x32_bf16 v[52:55], v[228:231], v[220:223], v[52:55]
	v_mfma_f32_16x16x32_bf16 v[56:59], v[232:235], v[220:223], v[56:59]
	v_mfma_f32_16x16x32_bf16 v[60:63], v[236:239], v[220:223], v[60:63]
	s_movk_i32 s82, 6
.Lip_loop:
	s_waitcnt vmcnt(0)
	s_barrier
	ds_read_b128 v[64:67], v244 offset:0
	ds_read_b128 v[80:83], v246 offset:0
	ds_read_b128 v[84:87], v246 offset:2048
	ds_read_b128 v[88:91], v246 offset:4096
	ds_read_b128 v[92:95], v246 offset:6144
	ds_read_b128 v[68:71], v244 offset:2048
	ds_read_b128 v[72:75], v244 offset:4096
	ds_read_b128 v[76:79], v244 offset:6144
	s_waitcnt lgkmcnt(6)
	v_mfma_f32_16x16x32_bf16 v[0:3], v[80:83], v[64:67], v[0:3]
	ds_read_b128 v[208:211], v245 offset:0
	s_add_i32 m0, s81, 32768
	s_waitcnt lgkmcnt(6)
	v_mfma_f32_16x16x32_bf16 v[4:7], v[84:87], v[64:67], v[4:7]
	ds_read_b128 v[224:227], v247 offset:0
	global_load_lds_dwordx4 v240, s[76:77]
	s_waitcnt lgkmcnt(6)
	v_mfma_f32_16x16x32_bf16 v[8:11], v[88:91], v[64:67], v[8:11]
	ds_read_b128 v[228:231], v247 offset:2048
	s_add_i32 m0, s81, 36864
	s_waitcnt lgkmcnt(6)
	v_mfma_f32_16x16x32_bf16 v[12:15], v[92:95], v[64:67], v[12:15]
	ds_read_b128 v[232:235], v247 offset:4096
	global_load_lds_dwordx4 v241, s[76:77]
	s_waitcnt lgkmcnt(6)
	v_mfma_f32_16x16x32_bf16 v[16:19], v[80:83], v[68:71], v[16:19]
	ds_read_b128 v[236:239], v247 offset:6144
	s_add_i32 m0, s81, 40960
	v_mfma_f32_16x16x32_bf16 v[20:23], v[84:87], v[68:71], v[20:23]
	ds_read_b128 v[212:215], v245 offset:2048
	global_load_lds_dwordx4 v242, s[76:77]
	v_mfma_f32_16x16x32_bf16 v[24:27], v[88:91], v[68:71], v[24:27]
	ds_read_b128 v[216:219], v245 offset:4096
	s_add_i32 m0, s81, 45056
	v_mfma_f32_16x16x32_bf16 v[28:31], v[92:95], v[68:71], v[28:31]
	ds_read_b128 v[220:223], v245 offset:6144
	global_load_lds_dwordx4 v243, s[76:77]
	s_waitcnt lgkmcnt(9)
	v_mfma_f32_16x16x32_bf16 v[32:35], v[80:83], v[72:75], v[32:35]
	s_add_i32 m0, s81, 49152
	v_mfma_f32_16x16x32_bf16 v[36:39], v[84:87], v[72:75], v[36:39]
	global_load_lds_dwordx4 v240, s[78:79]
	v_mfma_f32_16x16x32_bf16 v[40:43], v[88:91], v[72:75], v[40:43]
	s_add_i32 m0, s81, 53248
	v_mfma_f32_16x16x32_bf16 v[44:47], v[92:95], v[72:75], v[44:47]
	global_load_lds_dwordx4 v241, s[78:79]
	s_waitcnt lgkmcnt(8)
	v_mfma_f32_16x16x32_bf16 v[48:51], v[80:83], v[76:79], v[48:51]
	s_add_i32 m0, s81, 57344
	v_mfma_f32_16x16x32_bf16 v[52:55], v[84:87], v[76:79], v[52:55]
	global_load_lds_dwordx4 v242, s[78:79]
	v_mfma_f32_16x16x32_bf16 v[56:59], v[88:91], v[76:79], v[56:59]
	s_add_i32 m0, s81, 61440
	v_mfma_f32_16x16x32_bf16 v[60:63], v[92:95], v[76:79], v[60:63]
	global_load_lds_dwordx4 v243, s[78:79]
	s_waitcnt lgkmcnt(6)
	v_mfma_f32_16x16x32_bf16 v[0:3], v[224:227], v[208:211], v[0:3]
	s_add_u32 s76, s76, 0x80
	s_addc_u32 s77, s77, 0
	s_waitcnt lgkmcnt(5)
	v_mfma_f32_16x16x32_bf16 v[4:7], v[228:231], v[208:211], v[4:7]
	s_waitcnt lgkmcnt(4)
	v_mfma_f32_16x16x32_bf16 v[8:11], v[232:235], v[208:211], v[8:11]
	s_add_u32 s78, s78, 0x80
	s_addc_u32 s79, s79, 0
	s_waitcnt lgkmcnt(3)
	v_mfma_f32_16x16x32_bf16 v[12:15], v[236:239], v[208:211], v[12:15]
	s_waitcnt lgkmcnt(2)
	v_mfma_f32_16x16x32_bf16 v[16:19], v[224:227], v[212:215], v[16:19]
	v_mfma_f32_16x16x32_bf16 v[20:23], v[228:231], v[212:215], v[20:23]
	v_mfma_f32_16x16x32_bf16 v[24:27], v[232:235], v[212:215], v[24:27]
	v_mfma_f32_16x16x32_bf16 v[28:31], v[236:239], v[212:215], v[28:31]
	s_waitcnt lgkmcnt(1)
	v_mfma_f32_16x16x32_bf16 v[32:35], v[224:227], v[216:219], v[32:35]
	v_mfma_f32_16x16x32_bf16 v[36:39], v[228:231], v[216:219], v[36:39]
	v_mfma_f32_16x16x32_bf16 v[40:43], v[232:235], v[216:219], v[40:43]
	v_mfma_f32_16x16x32_bf16 v[44:47], v[236:239], v[216:219], v[44:47]
	s_waitcnt lgkmcnt(0)
	v_mfma_f32_16x16x32_bf16 v[48:51], v[224:227], v[220:223], v[48:51]
	v_mfma_f32_16x16x32_bf16 v[52:55], v[228:231], v[220:223], v[52:55]
	v_mfma_f32_16x16x32_bf16 v[56:59], v[232:235], v[220:223], v[56:59]
	v_mfma_f32_16x16x32_bf16 v[60:63], v[236:239], v[220:223], v[60:63]
	s_waitcnt vmcnt(0)
	s_barrier
	ds_read_b128 v[64:67], v244 offset:32768
	ds_read_b128 v[80:83], v246 offset:32768
	ds_read_b128 v[84:87], v246 offset:34816
	ds_read_b128 v[88:91], v246 offset:36864
	ds_read_b128 v[92:95], v246 offset:38912
	ds_read_b128 v[68:71], v244 offset:34816
	ds_read_b128 v[72:75], v244 offset:36864
	ds_read_b128 v[76:79], v244 offset:38912
	s_waitcnt lgkmcnt(6)
	v_mfma_f32_16x16x32_bf16 v[0:3], v[80:83], v[64:67], v[0:3]
	ds_read_b128 v[208:211], v245 offset:32768
	s_add_i32 m0, s81, 0
	s_waitcnt lgkmcnt(6)
	v_mfma_f32_16x16x32_bf16 v[4:7], v[84:87], v[64:67], v[4:7]
	ds_read_b128 v[224:227], v247 offset:32768
	global_load_lds_dwordx4 v240, s[76:77]
	s_waitcnt lgkmcnt(6)
	v_mfma_f32_16x16x32_bf16 v[8:11], v[88:91], v[64:67], v[8:11]
	ds_read_b128 v[228:231], v247 offset:34816
	s_add_i32 m0, s81, 4096
	s_waitcnt lgkmcnt(6)
	v_mfma_f32_16x16x32_bf16 v[12:15], v[92:95], v[64:67], v[12:15]
	ds_read_b128 v[232:235], v247 offset:36864
	global_load_lds_dwordx4 v241, s[76:77]
	s_waitcnt lgkmcnt(6)
	v_mfma_f32_16x16x32_bf16 v[16:19], v[80:83], v[68:71], v[16:19]
	ds_read_b128 v[236:239], v247 offset:38912
	s_add_i32 m0, s81, 8192
	v_mfma_f32_16x16x32_bf16 v[20:23], v[84:87], v[68:71], v[20:23]
	ds_read_b128 v[212:215], v245 offset:34816
	global_load_lds_dwordx4 v242, s[76:77]
	v_mfma_f32_16x16x32_bf16 v[24:27], v[88:91], v[68:71], v[24:27]
	ds_read_b128 v[216:219], v245 offset:36864
	s_add_i32 m0, s81, 12288
	v_mfma_f32_16x16x32_bf16 v[28:31], v[92:95], v[68:71], v[28:31]
	ds_read_b128 v[220:223], v245 offset:38912
	global_load_lds_dwordx4 v243, s[76:77]
	s_waitcnt lgkmcnt(9)
	v_mfma_f32_16x16x32_bf16 v[32:35], v[80:83], v[72:75], v[32:35]
	s_add_i32 m0, s81, 16384
	v_mfma_f32_16x16x32_bf16 v[36:39], v[84:87], v[72:75], v[36:39]
	global_load_lds_dwordx4 v240, s[78:79]
	v_mfma_f32_16x16x32_bf16 v[40:43], v[88:91], v[72:75], v[40:43]
	s_add_i32 m0, s81, 20480
	v_mfma_f32_16x16x32_bf16 v[44:47], v[92:95], v[72:75], v[44:47]
	global_load_lds_dwordx4 v241, s[78:79]
	s_waitcnt lgkmcnt(8)
	v_mfma_f32_16x16x32_bf16 v[48:51], v[80:83], v[76:79], v[48:51]
	s_add_i32 m0, s81, 24576
	v_mfma_f32_16x16x32_bf16 v[52:55], v[84:87], v[76:79], v[52:55]
	global_load_lds_dwordx4 v242, s[78:79]
	v_mfma_f32_16x16x32_bf16 v[56:59], v[88:91], v[76:79], v[56:59]
	s_add_i32 m0, s81, 28672
	v_mfma_f32_16x16x32_bf16 v[60:63], v[92:95], v[76:79], v[60:63]
	global_load_lds_dwordx4 v243, s[78:79]
	s_waitcnt lgkmcnt(6)
	v_mfma_f32_16x16x32_bf16 v[0:3], v[224:227], v[208:211], v[0:3]
	s_add_u32 s76, s76, 0x80
	s_addc_u32 s77, s77, 0
	s_waitcnt lgkmcnt(5)
	v_mfma_f32_16x16x32_bf16 v[4:7], v[228:231], v[208:211], v[4:7]
	s_waitcnt lgkmcnt(4)
	v_mfma_f32_16x16x32_bf16 v[8:11], v[232:235], v[208:211], v[8:11]
	s_add_u32 s78, s78, 0x80
	s_addc_u32 s79, s79, 0
	s_waitcnt lgkmcnt(3)
	v_mfma_f32_16x16x32_bf16 v[12:15], v[236:239], v[208:211], v[12:15]
	s_waitcnt lgkmcnt(2)
	v_mfma_f32_16x16x32_bf16 v[16:19], v[224:227], v[212:215], v[16:19]
	v_mfma_f32_16x16x32_bf16 v[20:23], v[228:231], v[212:215], v[20:23]
	v_mfma_f32_16x16x32_bf16 v[24:27], v[232:235], v[212:215], v[24:27]
	v_mfma_f32_16x16x32_bf16 v[28:31], v[236:239], v[212:215], v[28:31]
	s_waitcnt lgkmcnt(1)
	v_mfma_f32_16x16x32_bf16 v[32:35], v[224:227], v[216:219], v[32:35]
	v_mfma_f32_16x16x32_bf16 v[36:39], v[228:231], v[216:219], v[36:39]
	v_mfma_f32_16x16x32_bf16 v[40:43], v[232:235], v[216:219], v[40:43]
	v_mfma_f32_16x16x32_bf16 v[44:47], v[236:239], v[216:219], v[44:47]
	s_waitcnt lgkmcnt(0)
	v_mfma_f32_16x16x32_bf16 v[48:51], v[224:227], v[220:223], v[48:51]
	v_mfma_f32_16x16x32_bf16 v[52:55], v[228:231], v[220:223], v[52:55]
	v_mfma_f32_16x16x32_bf16 v[56:59], v[232:235], v[220:223], v[56:59]
	v_mfma_f32_16x16x32_bf16 v[60:63], v[236:239], v[220:223], v[60:63]
	s_sub_u32 s82, s82, 1
	s_cmp_lg_u32 s82, 0
	s_cbranch_scc1 .Lip_loop
	s_waitcnt vmcnt(0)
	s_barrier
	ds_read_b128 v[64:67], v244 offset:0
	ds_read_b128 v[80:83], v246 offset:0
	ds_read_b128 v[84:87], v246 offset:2048
	ds_read_b128 v[88:91], v246 offset:4096
	ds_read_b128 v[92:95], v246 offset:6144
	ds_read_b128 v[68:71], v244 offset:2048
	ds_read_b128 v[72:75], v244 offset:4096
	ds_read_b128 v[76:79], v244 offset:6144
	s_waitcnt lgkmcnt(6)
	v_mfma_f32_16x16x32_bf16 v[0:3], v[80:83], v[64:67], v[0:3]
	ds_read_b128 v[208:211], v245 offset:0
	s_add_i32 m0, s81, 32768
	s_waitcnt lgkmcnt(6)
	v_mfma_f32_16x16x32_bf16 v[4:7], v[84:87], v[64:67], v[4:7]
	ds_read_b128 v[224:227], v247 offset:0
	global_load_lds_dwordx4 v240, s[76:77]
	s_waitcnt lgkmcnt(6)
	v_mfma_f32_16x16x32_bf16 v[8:11], v[88:91], v[64:67], v[8:11]
	ds_read_b128 v[228:231], v247 offset:2048
	s_add_i32 m0, s81, 36864
	s_waitcnt lgkmcnt(6)
	v_mfma_f32_16x16x32_bf16 v[12:15], v[92:95], v[64:67], v[12:15]
	ds_read_b128 v[232:235], v247 offset:4096
	global_load_lds_dwordx4 v241, s[76:77]
	s_waitcnt lgkmcnt(6)
	v_mfma_f32_16x16x32_bf16 v[16:19], v[80:83], v[68:71], v[16:19]
	ds_read_b128 v[236:239], v247 offset:6144
	s_add_i32 m0, s81, 40960
	v_mfma_f32_16x16x32_bf16 v[20:23], v[84:87], v[68:71], v[20:23]
	ds_read_b128 v[212:215], v245 offset:2048
	global_load_lds_dwordx4 v242, s[76:77]
	v_mfma_f32_16x16x32_bf16 v[24:27], v[88:91], v[68:71], v[24:27]
	ds_read_b128 v[216:219], v245 offset:4096
	s_add_i32 m0, s81, 45056
	v_mfma_f32_16x16x32_bf16 v[28:31], v[92:95], v[68:71], v[28:31]
	ds_read_b128 v[220:223], v245 offset:6144
	global_load_lds_dwordx4 v243, s[76:77]
	s_waitcnt lgkmcnt(9)
	v_mfma_f32_16x16x32_bf16 v[32:35], v[80:83], v[72:75], v[32:35]
	s_add_i32 m0, s81, 49152
	v_mfma_f32_16x16x32_bf16 v[36:39], v[84:87], v[72:75], v[36:39]
	global_load_lds_dwordx4 v240, s[78:79]
	v_mfma_f32_16x16x32_bf16 v[40:43], v[88:91], v[72:75], v[40:43]
	s_add_i32 m0, s81, 53248
	v_mfma_f32_16x16x32_bf16 v[44:47], v[92:95], v[72:75], v[44:47]
	global_load_lds_dwordx4 v241, s[78:79]
	s_waitcnt lgkmcnt(8)
	v_mfma_f32_16x16x32_bf16 v[48:51], v[80:83], v[76:79], v[48:51]
	s_add_i32 m0, s81, 57344
	v_mfma_f32_16x16x32_bf16 v[52:55], v[84:87], v[76:79], v[52:55]
	global_load_lds_dwordx4 v242, s[78:79]
	v_mfma_f32_16x16x32_bf16 v[56:59], v[88:91], v[76:79], v[56:59]
	s_add_i32 m0, s81, 61440
	v_mfma_f32_16x16x32_bf16 v[60:63], v[92:95], v[76:79], v[60:63]
	global_load_lds_dwordx4 v243, s[78:79]
	s_waitcnt lgkmcnt(6)
	v_mfma_f32_16x16x32_bf16 v[0:3], v[224:227], v[208:211], v[0:3]
	s_add_u32 s76, s76, 0x80
	s_addc_u32 s77, s77, 0
	s_waitcnt lgkmcnt(5)
	v_mfma_f32_16x16x32_bf16 v[4:7], v[228:231], v[208:211], v[4:7]
	s_waitcnt lgkmcnt(4)
	v_mfma_f32_16x16x32_bf16 v[8:11], v[232:235], v[208:211], v[8:11]
	s_add_u32 s78, s78, 0x80
	s_addc_u32 s79, s79, 0
	s_waitcnt lgkmcnt(3)
	v_mfma_f32_16x16x32_bf16 v[12:15], v[236:239], v[208:211], v[12:15]
	s_waitcnt lgkmcnt(2)
	v_mfma_f32_16x16x32_bf16 v[16:19], v[224:227], v[212:215], v[16:19]
	v_mfma_f32_16x16x32_bf16 v[20:23], v[228:231], v[212:215], v[20:23]
	v_mfma_f32_16x16x32_bf16 v[24:27], v[232:235], v[212:215], v[24:27]
	v_mfma_f32_16x16x32_bf16 v[28:31], v[236:239], v[212:215], v[28:31]
	s_waitcnt lgkmcnt(1)
	v_mfma_f32_16x16x32_bf16 v[32:35], v[224:227], v[216:219], v[32:35]
	v_mfma_f32_16x16x32_bf16 v[36:39], v[228:231], v[216:219], v[36:39]
	v_mfma_f32_16x16x32_bf16 v[40:43], v[232:235], v[216:219], v[40:43]
	v_mfma_f32_16x16x32_bf16 v[44:47], v[236:239], v[216:219], v[44:47]
	s_waitcnt lgkmcnt(0)
	v_mfma_f32_16x16x32_bf16 v[48:51], v[224:227], v[220:223], v[48:51]
	v_mfma_f32_16x16x32_bf16 v[52:55], v[228:231], v[220:223], v[52:55]
	v_mfma_f32_16x16x32_bf16 v[56:59], v[232:235], v[220:223], v[56:59]
	v_mfma_f32_16x16x32_bf16 v[60:63], v[236:239], v[220:223], v[60:63]
	s_waitcnt vmcnt(0)
	s_barrier
	ds_read_b128 v[64:67], v244 offset:32768
	ds_read_b128 v[80:83], v246 offset:32768
	ds_read_b128 v[84:87], v246 offset:34816
	ds_read_b128 v[88:91], v246 offset:36864
	ds_read_b128 v[92:95], v246 offset:38912
	ds_read_b128 v[68:71], v244 offset:34816
	ds_read_b128 v[72:75], v244 offset:36864
	ds_read_b128 v[76:79], v244 offset:38912
	s_waitcnt lgkmcnt(6)
	v_mfma_f32_16x16x32_bf16 v[0:3], v[80:83], v[64:67], v[0:3]
	ds_read_b128 v[208:211], v245 offset:32768
	s_waitcnt lgkmcnt(6)
	v_mfma_f32_16x16x32_bf16 v[4:7], v[84:87], v[64:67], v[4:7]
	ds_read_b128 v[224:227], v247 offset:32768
	s_waitcnt lgkmcnt(6)
	v_mfma_f32_16x16x32_bf16 v[8:11], v[88:91], v[64:67], v[8:11]
	ds_read_b128 v[228:231], v247 offset:34816
	s_waitcnt lgkmcnt(6)
	v_mfma_f32_16x16x32_bf16 v[12:15], v[92:95], v[64:67], v[12:15]
	ds_read_b128 v[232:235], v247 offset:36864
	s_waitcnt lgkmcnt(6)
	v_mfma_f32_16x16x32_bf16 v[16:19], v[80:83], v[68:71], v[16:19]
	ds_read_b128 v[236:239], v247 offset:38912
	v_mfma_f32_16x16x32_bf16 v[20:23], v[84:87], v[68:71], v[20:23]
	ds_read_b128 v[212:215], v245 offset:34816
	v_mfma_f32_16x16x32_bf16 v[24:27], v[88:91], v[68:71], v[24:27]
	ds_read_b128 v[216:219], v245 offset:36864
	v_mfma_f32_16x16x32_bf16 v[28:31], v[92:95], v[68:71], v[28:31]
	ds_read_b128 v[220:223], v245 offset:38912
	s_waitcnt lgkmcnt(9)
	v_mfma_f32_16x16x32_bf16 v[32:35], v[80:83], v[72:75], v[32:35]
	v_mfma_f32_16x16x32_bf16 v[36:39], v[84:87], v[72:75], v[36:39]
	v_mfma_f32_16x16x32_bf16 v[40:43], v[88:91], v[72:75], v[40:43]
	v_mfma_f32_16x16x32_bf16 v[44:47], v[92:95], v[72:75], v[44:47]
	s_waitcnt lgkmcnt(8)
	v_mfma_f32_16x16x32_bf16 v[48:51], v[80:83], v[76:79], v[48:51]
	v_mfma_f32_16x16x32_bf16 v[52:55], v[84:87], v[76:79], v[52:55]
	v_mfma_f32_16x16x32_bf16 v[56:59], v[88:91], v[76:79], v[56:59]
	v_mfma_f32_16x16x32_bf16 v[60:63], v[92:95], v[76:79], v[60:63]
	s_waitcnt lgkmcnt(6)
	v_mfma_f32_16x16x32_bf16 v[0:3], v[224:227], v[208:211], v[0:3]
	s_waitcnt lgkmcnt(5)
	v_mfma_f32_16x16x32_bf16 v[4:7], v[228:231], v[208:211], v[4:7]
	s_waitcnt lgkmcnt(4)
	v_mfma_f32_16x16x32_bf16 v[8:11], v[232:235], v[208:211], v[8:11]
	s_waitcnt lgkmcnt(3)
	v_mfma_f32_16x16x32_bf16 v[12:15], v[236:239], v[208:211], v[12:15]
	s_waitcnt lgkmcnt(2)
	v_mfma_f32_16x16x32_bf16 v[16:19], v[224:227], v[212:215], v[16:19]
	v_mfma_f32_16x16x32_bf16 v[20:23], v[228:231], v[212:215], v[20:23]
	v_mfma_f32_16x16x32_bf16 v[24:27], v[232:235], v[212:215], v[24:27]
	v_mfma_f32_16x16x32_bf16 v[28:31], v[236:239], v[212:215], v[28:31]
	s_waitcnt lgkmcnt(1)
	v_mfma_f32_16x16x32_bf16 v[32:35], v[224:227], v[216:219], v[32:35]
	v_mfma_f32_16x16x32_bf16 v[36:39], v[228:231], v[216:219], v[36:39]
	v_mfma_f32_16x16x32_bf16 v[40:43], v[232:235], v[216:219], v[40:43]
	v_mfma_f32_16x16x32_bf16 v[44:47], v[236:239], v[216:219], v[44:47]
	s_waitcnt lgkmcnt(0)
	v_mfma_f32_16x16x32_bf16 v[48:51], v[224:227], v[220:223], v[48:51]
	v_mfma_f32_16x16x32_bf16 v[52:55], v[228:231], v[220:223], v[52:55]
	v_mfma_f32_16x16x32_bf16 v[56:59], v[232:235], v[220:223], v[56:59]
	v_mfma_f32_16x16x32_bf16 v[60:63], v[236:239], v[220:223], v[60:63]
	s_barrier
	ds_write_b128 v248, v[0:3] offset:0
	ds_write_b128 v248, v[4:7] offset:64
	ds_write_b128 v248, v[8:11] offset:128
	ds_write_b128 v248, v[12:15] offset:192
	ds_write_b128 v248, v[16:19] offset:8448
	ds_write_b128 v248, v[20:23] offset:8512
	ds_write_b128 v248, v[24:27] offset:8576
	ds_write_b128 v248, v[28:31] offset:8640
	ds_write_b128 v248, v[32:35] offset:16896
	ds_write_b128 v248, v[36:39] offset:16960
	ds_write_b128 v248, v[40:43] offset:17024
	ds_write_b128 v248, v[44:47] offset:17088
	ds_write_b128 v248, v[48:51] offset:25344
	ds_write_b128 v248, v[52:55] offset:25408
	ds_write_b128 v248, v[56:59] offset:25472
	ds_write_b128 v248, v[60:63] offset:25536
	v_mov_b32_e32 v26, v138
	s_lshl_b32 s57, s18, 7
	s_cmpk_lt_u32 s18, 0x80
	s_cselect_b64 s[16:17], -1, 0
	s_mov_b64 s[0:1], -1
	s_mov_b32 s2, 0x40000
	s_cmp_gt_u32 s42, 2
	s_waitcnt lgkmcnt(0)
	s_barrier
	s_cbranch_scc0 .LBB0_270
	s_cmp_lg_u32 s42, 3
	s_cbranch_scc0 .LBB0_272
	s_add_i32 s0, s42, -10
	s_cmp_gt_u32 s0, 7
	s_mov_b64 s[0:1], -1
	s_cbranch_scc0 .LBB0_251
	s_lshl_b32 s0, s42, 7
	s_cmp_lt_u32 s42, 10
	s_movk_i32 s1, 0xfe00
	s_cselect_b32 s1, s1, 0xfffffc00
	s_add_i32 s0, s1, s0
	s_mov_b32 s1, s19
	v_lshlrev_b32_e32 v0, 3, v26
	s_lshl_b64 s[0:1], s[0:1], 1
	v_readlane_b32 s2, v206, 43
	v_and_b32_e32 v1, 0x78, v0
	v_readlane_b32 s3, v206, 44
	s_add_u32 s0, s2, s0
	s_addc_u32 s1, s3, s1
	v_lshlrev_b32_e32 v134, 1, v1
	v_lshlrev_b32_e32 v0, 2, v1
	v_lshl_add_u64 v[2:3], s[0:1], 0, v[134:135]
	s_mov_b32 s0, 0

.LBB0_625:
	s_lshr_b32 s0, s41, 6
	s_and_b32 s1, s41, 63
	s_lshr_b32 s82, s1, 3
	s_and_b32 s1, s1, 7
	s_lshl_b32 s0, s0, 3
	s_or_b32 s83, s0, s1
	s_lshl_b32 s0, s83, 18
	s_add_u32 s0, s0, 0x1100000
	s_add_u32 s76, s94, s0
	s_addc_u32 s77, s95, 0
	s_lshl_b32 s0, s82, 18
	s_add_u32 s78, s38, s0
	s_addc_u32 s79, s39, 0
	v_lshrrev_b32_e32 v98, 3, v138
	v_bfe_u32 v99, v138, 4, 3
	v_and_b32_e32 v100, 7, v138
	v_xor_b32_e32 v99, v99, v100
	v_lshlrev_b32_e32 v99, 4, v99
	v_lshl_add_u32 v240, v98, 11, v99
	v_add_u32_e32 v241, 0x10000, v240
	v_add_u32_e32 v242, 0x20000, v240
	v_add_u32_e32 v243, 0x30000, v240
	v_lshrrev_b32_e32 v101, 6, v138
	s_nop 0
	v_readfirstlane_b32 s80, v101
	s_lshl_b32 s81, s80, 10
	s_barrier
	s_add_i32 m0, s81, 0
	s_nop 0
	global_load_lds_dwordx4 v240, s[76:77]
	s_add_i32 m0, s81, 4096
	s_nop 0
	global_load_lds_dwordx4 v241, s[76:77]
	s_add_i32 m0, s81, 8192
	s_nop 0
	global_load_lds_dwordx4 v242, s[76:77]
	s_add_i32 m0, s81, 12288
	s_nop 0
	global_load_lds_dwordx4 v243, s[76:77]
	s_add_i32 m0, s81, 16384
	s_nop 0
	global_load_lds_dwordx4 v240, s[78:79]
	s_add_i32 m0, s81, 20480
	s_nop 0
	global_load_lds_dwordx4 v241, s[78:79]
	s_add_i32 m0, s81, 24576
	s_nop 0
	global_load_lds_dwordx4 v242, s[78:79]
	s_add_i32 m0, s81, 28672
	s_nop 0
	global_load_lds_dwordx4 v243, s[78:79]
	s_add_u32 s76, s76, 0x80
	s_addc_u32 s77, s77, 0
	s_add_u32 s78, s78, 0x80
	s_addc_u32 s79, s79, 0
	v_and_b32_e32 v104, 15, v138
	v_bfe_u32 v105, v138, 4, 2
	v_lshrrev_b32_e32 v106, 1, v104
	v_xor_b32_e32 v106, v106, v105
	v_lshlrev_b32_e32 v106, 4, v106
	v_lshrrev_b32_e32 v107, 1, v101
	v_and_b32_e32 v101, 1, v101
	v_lshl_add_u32 v98, v107, 6, v104
	v_lshl_add_u32 v244, v98, 7, v106
	v_xor_b32_e32 v245, 64, v244
	v_lshl_add_u32 v98, v101, 6, v104
	v_lshl_add_u32 v246, v98, 7, v106
	v_add_u32_e32 v246, 0x4000, v246
	v_xor_b32_e32 v247, 64, v246
	v_lshl_add_u32 v98, v107, 6, v104
	s_movk_i32 s0, 0x210
	v_mul_lo_u32 v98, v98, s0
	v_lshlrev_b32_e32 v99, 6, v101
	v_lshl_add_u32 v99, v105, 2, v99
	v_lshl_add_u32 v248, v99, 2, v98
	v_lshrrev_b32_e32 v110, 4, v138
	v_and_b32_e32 v111, 15, v138
	v_lshlrev_b32_e32 v114, 5, v111
	v_lshl_add_u32 v102, v110, 12, v114
	v_lshlrev_b32_e32 v108, 4, v111
	v_lshl_add_u32 v108, v110, 11, v108
	v_mul_lo_u32 v124, v110, s0
	v_add_u32_e32 v124, v124, v114
	s_lshl_b32 s0, s83, 7
	s_lshl_b32 s1, s82, 7
	s_lshl_b32 s2, s0, 10
	s_add_u32 s2, s2, s1
	s_cmp_eq_u64 s[52:53], 0
	s_cbranch_scc0 .Lot_l1addr
	v_readlane_b32 s86, v207, 4
	v_readlane_b32 s87, v207, 5
	s_lshl_b32 s3, s2, 2
	s_add_u32 s86, s86, s3
	s_addc_u32 s87, s87, 0
	s_lshl_b32 s3, s2, 1
	s_add_u32 s3, s3, 0xa700000
	s_add_u32 s88, s94, s3
	s_addc_u32 s89, s95, 0
	s_branch .Lot_addr_done

.Lot_addr_done:
	s_lshr_b32 s2, s83, 6
	s_mul_i32 s2, s2, 0x3000
	s_lshl_b32 s3, s1, 2
	s_add_u32 s2, s2, s3
	s_add_u32 s2, s2, 0x2000
	s_add_u32 s90, s12, s2
	s_addc_u32 s91, s13, 0
	s_cmp_eq_u64 s[52:53], 0
	s_cbranch_scc0 .Lot_main_l1
	s_waitcnt vmcnt(0)
	s_barrier
	ds_read_b128 v[176:179], v244 offset:0
	ds_read_b128 v[80:83], v246 offset:0
	ds_read_b128 v[84:87], v246 offset:2048
	ds_read_b128 v[88:91], v246 offset:4096
	ds_read_b128 v[92:95], v246 offset:6144
	ds_read_b128 v[180:183], v244 offset:2048
	ds_read_b128 v[184:187], v244 offset:4096
	ds_read_b128 v[188:191], v244 offset:6144
	s_waitcnt lgkmcnt(6)
	v_mfma_f32_16x16x32_bf16 v[0:3], v[80:83], v[176:179], 0
	ds_read_b128 v[208:211], v245 offset:0
	s_add_i32 m0, s81, 32768
	s_waitcnt lgkmcnt(6)
	v_mfma_f32_16x16x32_bf16 v[4:7], v[84:87], v[176:179], 0
	ds_read_b128 v[224:227], v247 offset:0
	global_load_lds_dwordx4 v240, s[76:77]
	s_waitcnt lgkmcnt(6)
	v_mfma_f32_16x16x32_bf16 v[8:11], v[88:91], v[176:179], 0
	ds_read_b128 v[228:231], v247 offset:2048
	s_add_i32 m0, s81, 36864
	s_waitcnt lgkmcnt(6)
	v_mfma_f32_16x16x32_bf16 v[12:15], v[92:95], v[176:179], 0
	ds_read_b128 v[232:235], v247 offset:4096
	global_load_lds_dwordx4 v241, s[76:77]
	s_waitcnt lgkmcnt(6)
	v_mfma_f32_16x16x32_bf16 v[16:19], v[80:83], v[180:183], 0
	ds_read_b128 v[236:239], v247 offset:6144
	s_add_i32 m0, s81, 40960
	v_mfma_f32_16x16x32_bf16 v[20:23], v[84:87], v[180:183], 0
	ds_read_b128 v[212:215], v245 offset:2048
	global_load_lds_dwordx4 v242, s[76:77]
	v_mfma_f32_16x16x32_bf16 v[24:27], v[88:91], v[180:183], 0
	ds_read_b128 v[216:219], v245 offset:4096
	s_add_i32 m0, s81, 45056
	v_mfma_f32_16x16x32_bf16 v[28:31], v[92:95], v[180:183], 0
	ds_read_b128 v[220:223], v245 offset:6144
	global_load_lds_dwordx4 v243, s[76:77]
	s_waitcnt lgkmcnt(9)
	v_mfma_f32_16x16x32_bf16 v[32:35], v[80:83], v[184:187], 0
	s_add_i32 m0, s81, 49152
	v_mfma_f32_16x16x32_bf16 v[36:39], v[84:87], v[184:187], 0
	global_load_lds_dwordx4 v240, s[78:79]
	v_mfma_f32_16x16x32_bf16 v[40:43], v[88:91], v[184:187], 0
	s_add_i32 m0, s81, 53248
	v_mfma_f32_16x16x32_bf16 v[44:47], v[92:95], v[184:187], 0
	global_load_lds_dwordx4 v241, s[78:79]
	s_waitcnt lgkmcnt(8)
	v_mfma_f32_16x16x32_bf16 v[48:51], v[80:83], v[188:191], 0
	s_add_i32 m0, s81, 57344
	v_mfma_f32_16x16x32_bf16 v[52:55], v[84:87], v[188:191], 0
	global_load_lds_dwordx4 v242, s[78:79]
	v_mfma_f32_16x16x32_bf16 v[56:59], v[88:91], v[188:191], 0
	s_add_i32 m0, s81, 61440
	v_mfma_f32_16x16x32_bf16 v[60:63], v[92:95], v[188:191], 0
	global_load_lds_dwordx4 v243, s[78:79]
	s_waitcnt lgkmcnt(6)
	v_mfma_f32_16x16x32_bf16 v[0:3], v[224:227], v[208:211], v[0:3]
	s_add_u32 s76, s76, 0x80
	s_addc_u32 s77, s77, 0
	s_waitcnt lgkmcnt(5)
	v_mfma_f32_16x16x32_bf16 v[4:7], v[228:231], v[208:211], v[4:7]
	s_waitcnt lgkmcnt(4)
	v_mfma_f32_16x16x32_bf16 v[8:11], v[232:235], v[208:211], v[8:11]
	s_add_u32 s78, s78, 0x80
	s_addc_u32 s79, s79, 0
	s_waitcnt lgkmcnt(3)
	v_mfma_f32_16x16x32_bf16 v[12:15], v[236:239], v[208:211], v[12:15]
	s_waitcnt lgkmcnt(2)
	v_mfma_f32_16x16x32_bf16 v[16:19], v[224:227], v[212:215], v[16:19]
	v_mfma_f32_16x16x32_bf16 v[20:23], v[228:231], v[212:215], v[20:23]
	v_mfma_f32_16x16x32_bf16 v[24:27], v[232:235], v[212:215], v[24:27]
	v_mfma_f32_16x16x32_bf16 v[28:31], v[236:239], v[212:215], v[28:31]
	s_waitcnt lgkmcnt(1)
	v_mfma_f32_16x16x32_bf16 v[32:35], v[224:227], v[216:219], v[32:35]
	v_mfma_f32_16x16x32_bf16 v[36:39], v[228:231], v[216:219], v[36:39]
	v_mfma_f32_16x16x32_bf16 v[40:43], v[232:235], v[216:219], v[40:43]
	v_mfma_f32_16x16x32_bf16 v[44:47], v[236:239], v[216:219], v[44:47]
	s_waitcnt lgkmcnt(0)
	v_mfma_f32_16x16x32_bf16 v[48:51], v[224:227], v[220:223], v[48:51]
	v_mfma_f32_16x16x32_bf16 v[52:55], v[228:231], v[220:223], v[52:55]
	v_mfma_f32_16x16x32_bf16 v[56:59], v[232:235], v[220:223], v[56:59]
	v_mfma_f32_16x16x32_bf16 v[60:63], v[236:239], v[220:223], v[60:63]
	s_waitcnt vmcnt(0)
	s_barrier
	ds_read_b128 v[176:179], v244 offset:32768
	ds_read_b128 v[80:83], v246 offset:32768
	ds_read_b128 v[84:87], v246 offset:34816
	ds_read_b128 v[88:91], v246 offset:36864
	ds_read_b128 v[92:95], v246 offset:38912
	ds_read_b128 v[180:183], v244 offset:34816
	ds_read_b128 v[184:187], v244 offset:36864
	ds_read_b128 v[188:191], v244 offset:38912
	s_waitcnt lgkmcnt(6)
	v_mfma_f32_16x16x32_bf16 v[0:3], v[80:83], v[176:179], v[0:3]
	ds_read_b128 v[208:211], v245 offset:32768
	s_add_i32 m0, s81, 0
	s_waitcnt lgkmcnt(6)
	v_mfma_f32_16x16x32_bf16 v[4:7], v[84:87], v[176:179], v[4:7]
	ds_read_b128 v[224:227], v247 offset:32768
	global_load_lds_dwordx4 v240, s[76:77]
	s_waitcnt lgkmcnt(6)
	v_mfma_f32_16x16x32_bf16 v[8:11], v[88:91], v[176:179], v[8:11]
	ds_read_b128 v[228:231], v247 offset:34816
	s_add_i32 m0, s81, 4096
	s_waitcnt lgkmcnt(6)
	v_mfma_f32_16x16x32_bf16 v[12:15], v[92:95], v[176:179], v[12:15]
	ds_read_b128 v[232:235], v247 offset:36864
	global_load_lds_dwordx4 v241, s[76:77]
	s_waitcnt lgkmcnt(6)
	v_mfma_f32_16x16x32_bf16 v[16:19], v[80:83], v[180:183], v[16:19]
	ds_read_b128 v[236:239], v247 offset:38912
	s_add_i32 m0, s81, 8192
	v_mfma_f32_16x16x32_bf16 v[20:23], v[84:87], v[180:183], v[20:23]
	ds_read_b128 v[212:215], v245 offset:34816
	global_load_lds_dwordx4 v242, s[76:77]
	v_mfma_f32_16x16x32_bf16 v[24:27], v[88:91], v[180:183], v[24:27]
	ds_read_b128 v[216:219], v245 offset:36864
	s_add_i32 m0, s81, 12288
	v_mfma_f32_16x16x32_bf16 v[28:31], v[92:95], v[180:183], v[28:31]
	ds_read_b128 v[220:223], v245 offset:38912
	global_load_lds_dwordx4 v243, s[76:77]
	s_waitcnt lgkmcnt(9)
	v_mfma_f32_16x16x32_bf16 v[32:35], v[80:83], v[184:187], v[32:35]
	s_add_i32 m0, s81, 16384
	v_mfma_f32_16x16x32_bf16 v[36:39], v[84:87], v[184:187], v[36:39]
	global_load_lds_dwordx4 v240, s[78:79]
	v_mfma_f32_16x16x32_bf16 v[40:43], v[88:91], v[184:187], v[40:43]
	s_add_i32 m0, s81, 20480
	v_mfma_f32_16x16x32_bf16 v[44:47], v[92:95], v[184:187], v[44:47]
	global_load_lds_dwordx4 v241, s[78:79]
	s_waitcnt lgkmcnt(8)
	v_mfma_f32_16x16x32_bf16 v[48:51], v[80:83], v[188:191], v[48:51]
	s_add_i32 m0, s81, 24576
	v_mfma_f32_16x16x32_bf16 v[52:55], v[84:87], v[188:191], v[52:55]
	global_load_lds_dwordx4 v242, s[78:79]
	v_mfma_f32_16x16x32_bf16 v[56:59], v[88:91], v[188:191], v[56:59]
	s_add_i32 m0, s81, 28672
	v_mfma_f32_16x16x32_bf16 v[60:63], v[92:95], v[188:191], v[60:63]
	global_load_lds_dwordx4 v243, s[78:79]
	s_waitcnt lgkmcnt(6)
	v_mfma_f32_16x16x32_bf16 v[0:3], v[224:227], v[208:211], v[0:3]
	s_add_u32 s76, s76, 0x80
	s_addc_u32 s77, s77, 0
	s_waitcnt lgkmcnt(5)
	v_mfma_f32_16x16x32_bf16 v[4:7], v[228:231], v[208:211], v[4:7]
	s_waitcnt lgkmcnt(4)
	v_mfma_f32_16x16x32_bf16 v[8:11], v[232:235], v[208:211], v[8:11]
	s_add_u32 s78, s78, 0x80
	s_addc_u32 s79, s79, 0
	s_waitcnt lgkmcnt(3)
	v_mfma_f32_16x16x32_bf16 v[12:15], v[236:239], v[208:211], v[12:15]
	s_waitcnt lgkmcnt(2)
	v_mfma_f32_16x16x32_bf16 v[16:19], v[224:227], v[212:215], v[16:19]
	v_add_u32_e32 v96, 0x0, v102
	v_mfma_f32_16x16x32_bf16 v[20:23], v[228:231], v[212:215], v[20:23]
	global_load_dwordx4 v[64:67], v96, s[86:87] nt
	v_mfma_f32_16x16x32_bf16 v[24:27], v[232:235], v[212:215], v[24:27]
	v_mfma_f32_16x16x32_bf16 v[28:31], v[236:239], v[212:215], v[28:31]
	s_waitcnt lgkmcnt(1)
	v_mfma_f32_16x16x32_bf16 v[32:35], v[224:227], v[216:219], v[32:35]
	v_mfma_f32_16x16x32_bf16 v[36:39], v[228:231], v[216:219], v[36:39]
	v_mfma_f32_16x16x32_bf16 v[40:43], v[232:235], v[216:219], v[40:43]
	v_mfma_f32_16x16x32_bf16 v[44:47], v[236:239], v[216:219], v[44:47]
	s_waitcnt lgkmcnt(0)
	v_mfma_f32_16x16x32_bf16 v[48:51], v[224:227], v[220:223], v[48:51]
	v_mfma_f32_16x16x32_bf16 v[52:55], v[228:231], v[220:223], v[52:55]
	v_mfma_f32_16x16x32_bf16 v[56:59], v[232:235], v[220:223], v[56:59]
	v_mfma_f32_16x16x32_bf16 v[60:63], v[236:239], v[220:223], v[60:63]
	s_waitcnt vmcnt(1)
	s_barrier
	ds_read_b128 v[176:179], v244 offset:0
	ds_read_b128 v[80:83], v246 offset:0
	ds_read_b128 v[84:87], v246 offset:2048
	ds_read_b128 v[88:91], v246 offset:4096
	ds_read_b128 v[92:95], v246 offset:6144
	ds_read_b128 v[180:183], v244 offset:2048
	ds_read_b128 v[184:187], v244 offset:4096
	ds_read_b128 v[188:191], v244 offset:6144
	s_waitcnt lgkmcnt(6)
	v_mfma_f32_16x16x32_bf16 v[0:3], v[80:83], v[176:179], v[0:3]
	ds_read_b128 v[208:211], v245 offset:0
	s_add_i32 m0, s81, 32768
	s_waitcnt lgkmcnt(6)
	v_mfma_f32_16x16x32_bf16 v[4:7], v[84:87], v[176:179], v[4:7]
	ds_read_b128 v[224:227], v247 offset:0
	global_load_lds_dwordx4 v240, s[76:77]
	s_waitcnt lgkmcnt(6)
	v_mfma_f32_16x16x32_bf16 v[8:11], v[88:91], v[176:179], v[8:11]
	ds_read_b128 v[228:231], v247 offset:2048
	s_add_i32 m0, s81, 36864
	s_waitcnt lgkmcnt(6)
	v_mfma_f32_16x16x32_bf16 v[12:15], v[92:95], v[176:179], v[12:15]
	ds_read_b128 v[232:235], v247 offset:4096
	global_load_lds_dwordx4 v241, s[76:77]
	s_waitcnt lgkmcnt(6)
	v_mfma_f32_16x16x32_bf16 v[16:19], v[80:83], v[180:183], v[16:19]
	ds_read_b128 v[236:239], v247 offset:6144
	s_add_i32 m0, s81, 40960
	v_mfma_f32_16x16x32_bf16 v[20:23], v[84:87], v[180:183], v[20:23]
	ds_read_b128 v[212:215], v245 offset:2048
	global_load_lds_dwordx4 v242, s[76:77]
	v_mfma_f32_16x16x32_bf16 v[24:27], v[88:91], v[180:183], v[24:27]
	ds_read_b128 v[216:219], v245 offset:4096
	s_add_i32 m0, s81, 45056
	v_mfma_f32_16x16x32_bf16 v[28:31], v[92:95], v[180:183], v[28:31]
	ds_read_b128 v[220:223], v245 offset:6144
	global_load_lds_dwordx4 v243, s[76:77]
	s_waitcnt lgkmcnt(9)
	v_mfma_f32_16x16x32_bf16 v[32:35], v[80:83], v[184:187], v[32:35]
	s_add_i32 m0, s81, 49152
	v_mfma_f32_16x16x32_bf16 v[36:39], v[84:87], v[184:187], v[36:39]
	global_load_lds_dwordx4 v240, s[78:79]
	v_mfma_f32_16x16x32_bf16 v[40:43], v[88:91], v[184:187], v[40:43]
	s_add_i32 m0, s81, 53248
	v_mfma_f32_16x16x32_bf16 v[44:47], v[92:95], v[184:187], v[44:47]
	global_load_lds_dwordx4 v241, s[78:79]
	s_waitcnt lgkmcnt(8)
	v_mfma_f32_16x16x32_bf16 v[48:51], v[80:83], v[188:191], v[48:51]
	s_add_i32 m0, s81, 57344
	v_mfma_f32_16x16x32_bf16 v[52:55], v[84:87], v[188:191], v[52:55]
	global_load_lds_dwordx4 v242, s[78:79]
	v_mfma_f32_16x16x32_bf16 v[56:59], v[88:91], v[188:191], v[56:59]
	s_add_i32 m0, s81, 61440
	v_mfma_f32_16x16x32_bf16 v[60:63], v[92:95], v[188:191], v[60:63]
	global_load_lds_dwordx4 v243, s[78:79]
	s_waitcnt lgkmcnt(6)
	v_mfma_f32_16x16x32_bf16 v[0:3], v[224:227], v[208:211], v[0:3]
	s_add_u32 s76, s76, 0x80
	s_addc_u32 s77, s77, 0
	s_waitcnt lgkmcnt(5)
	v_mfma_f32_16x16x32_bf16 v[4:7], v[228:231], v[208:211], v[4:7]
	s_waitcnt lgkmcnt(4)
	v_mfma_f32_16x16x32_bf16 v[8:11], v[232:235], v[208:211], v[8:11]
	s_add_u32 s78, s78, 0x80
	s_addc_u32 s79, s79, 0
	s_waitcnt lgkmcnt(3)
	v_mfma_f32_16x16x32_bf16 v[12:15], v[236:239], v[208:211], v[12:15]
	s_waitcnt lgkmcnt(2)
	v_mfma_f32_16x16x32_bf16 v[16:19], v[224:227], v[212:215], v[16:19]
	v_add_u32_e32 v96, 0x0, v102
	v_mfma_f32_16x16x32_bf16 v[20:23], v[228:231], v[212:215], v[20:23]
	global_load_dwordx4 v[68:71], v96, s[86:87] offset:16 nt
	v_mfma_f32_16x16x32_bf16 v[24:27], v[232:235], v[212:215], v[24:27]
	v_mfma_f32_16x16x32_bf16 v[28:31], v[236:239], v[212:215], v[28:31]
	s_waitcnt lgkmcnt(1)
	v_mfma_f32_16x16x32_bf16 v[32:35], v[224:227], v[216:219], v[32:35]
	v_mfma_f32_16x16x32_bf16 v[36:39], v[228:231], v[216:219], v[36:39]
	v_mfma_f32_16x16x32_bf16 v[40:43], v[232:235], v[216:219], v[40:43]
	v_mfma_f32_16x16x32_bf16 v[44:47], v[236:239], v[216:219], v[44:47]
	s_waitcnt lgkmcnt(0)
	v_mfma_f32_16x16x32_bf16 v[48:51], v[224:227], v[220:223], v[48:51]
	v_mfma_f32_16x16x32_bf16 v[52:55], v[228:231], v[220:223], v[52:55]
	v_mfma_f32_16x16x32_bf16 v[56:59], v[232:235], v[220:223], v[56:59]
	v_mfma_f32_16x16x32_bf16 v[60:63], v[236:239], v[220:223], v[60:63]
	s_waitcnt vmcnt(1)
	s_barrier
	ds_read_b128 v[176:179], v244 offset:32768
	ds_read_b128 v[80:83], v246 offset:32768
	ds_read_b128 v[84:87], v246 offset:34816
	ds_read_b128 v[88:91], v246 offset:36864
	ds_read_b128 v[92:95], v246 offset:38912
	ds_read_b128 v[180:183], v244 offset:34816
	ds_read_b128 v[184:187], v244 offset:36864
	ds_read_b128 v[188:191], v244 offset:38912
	s_waitcnt lgkmcnt(6)
	v_mfma_f32_16x16x32_bf16 v[0:3], v[80:83], v[176:179], v[0:3]
	ds_read_b128 v[208:211], v245 offset:32768
	s_add_i32 m0, s81, 0
	s_waitcnt lgkmcnt(6)
	v_mfma_f32_16x16x32_bf16 v[4:7], v[84:87], v[176:179], v[4:7]
	ds_read_b128 v[224:227], v247 offset:32768
	global_load_lds_dwordx4 v240, s[76:77]
	s_waitcnt lgkmcnt(6)
	v_mfma_f32_16x16x32_bf16 v[8:11], v[88:91], v[176:179], v[8:11]
	ds_read_b128 v[228:231], v247 offset:34816
	s_add_i32 m0, s81, 4096
	s_waitcnt lgkmcnt(6)
	v_mfma_f32_16x16x32_bf16 v[12:15], v[92:95], v[176:179], v[12:15]
	ds_read_b128 v[232:235], v247 offset:36864
	global_load_lds_dwordx4 v241, s[76:77]
	s_waitcnt lgkmcnt(6)
	v_mfma_f32_16x16x32_bf16 v[16:19], v[80:83], v[180:183], v[16:19]
	ds_read_b128 v[236:239], v247 offset:38912
	s_add_i32 m0, s81, 8192
	v_mfma_f32_16x16x32_bf16 v[20:23], v[84:87], v[180:183], v[20:23]
	ds_read_b128 v[212:215], v245 offset:34816
	global_load_lds_dwordx4 v242, s[76:77]
	v_mfma_f32_16x16x32_bf16 v[24:27], v[88:91], v[180:183], v[24:27]
	ds_read_b128 v[216:219], v245 offset:36864
	s_add_i32 m0, s81, 12288
	v_mfma_f32_16x16x32_bf16 v[28:31], v[92:95], v[180:183], v[28:31]
	ds_read_b128 v[220:223], v245 offset:38912
	global_load_lds_dwordx4 v243, s[76:77]
	s_waitcnt lgkmcnt(9)
	v_mfma_f32_16x16x32_bf16 v[32:35], v[80:83], v[184:187], v[32:35]
	s_add_i32 m0, s81, 16384
	v_mfma_f32_16x16x32_bf16 v[36:39], v[84:87], v[184:187], v[36:39]
	global_load_lds_dwordx4 v240, s[78:79]
	v_mfma_f32_16x16x32_bf16 v[40:43], v[88:91], v[184:187], v[40:43]
	s_add_i32 m0, s81, 20480
	v_mfma_f32_16x16x32_bf16 v[44:47], v[92:95], v[184:187], v[44:47]
	global_load_lds_dwordx4 v241, s[78:79]
	s_waitcnt lgkmcnt(8)
	v_mfma_f32_16x16x32_bf16 v[48:51], v[80:83], v[188:191], v[48:51]
	s_add_i32 m0, s81, 24576
	v_mfma_f32_16x16x32_bf16 v[52:55], v[84:87], v[188:191], v[52:55]
	global_load_lds_dwordx4 v242, s[78:79]
	v_mfma_f32_16x16x32_bf16 v[56:59], v[88:91], v[188:191], v[56:59]
	s_add_i32 m0, s81, 28672
	v_mfma_f32_16x16x32_bf16 v[60:63], v[92:95], v[188:191], v[60:63]
	global_load_lds_dwordx4 v243, s[78:79]
	s_waitcnt lgkmcnt(6)
	v_mfma_f32_16x16x32_bf16 v[0:3], v[224:227], v[208:211], v[0:3]
	s_add_u32 s76, s76, 0x80
	s_addc_u32 s77, s77, 0
	s_waitcnt lgkmcnt(5)
	v_mfma_f32_16x16x32_bf16 v[4:7], v[228:231], v[208:211], v[4:7]
	s_waitcnt lgkmcnt(4)
	v_mfma_f32_16x16x32_bf16 v[8:11], v[232:235], v[208:211], v[8:11]
	s_add_u32 s78, s78, 0x80
	s_addc_u32 s79, s79, 0
	s_waitcnt lgkmcnt(3)
	v_mfma_f32_16x16x32_bf16 v[12:15], v[236:239], v[208:211], v[12:15]
	s_waitcnt lgkmcnt(2)
	v_mfma_f32_16x16x32_bf16 v[16:19], v[224:227], v[212:215], v[16:19]
	v_add_u32_e32 v96, 0x10000, v102
	v_mfma_f32_16x16x32_bf16 v[20:23], v[228:231], v[212:215], v[20:23]
	global_load_dwordx4 v[74:77], v96, s[86:87] nt
	v_mfma_f32_16x16x32_bf16 v[24:27], v[232:235], v[212:215], v[24:27]
	v_mfma_f32_16x16x32_bf16 v[28:31], v[236:239], v[212:215], v[28:31]
	s_waitcnt lgkmcnt(1)
	v_mfma_f32_16x16x32_bf16 v[32:35], v[224:227], v[216:219], v[32:35]
	v_mfma_f32_16x16x32_bf16 v[36:39], v[228:231], v[216:219], v[36:39]
	v_mfma_f32_16x16x32_bf16 v[40:43], v[232:235], v[216:219], v[40:43]
	v_mfma_f32_16x16x32_bf16 v[44:47], v[236:239], v[216:219], v[44:47]
	s_waitcnt lgkmcnt(0)
	v_mfma_f32_16x16x32_bf16 v[48:51], v[224:227], v[220:223], v[48:51]
	v_mfma_f32_16x16x32_bf16 v[52:55], v[228:231], v[220:223], v[52:55]
	v_mfma_f32_16x16x32_bf16 v[56:59], v[232:235], v[220:223], v[56:59]
	v_mfma_f32_16x16x32_bf16 v[60:63], v[236:239], v[220:223], v[60:63]
	s_waitcnt vmcnt(1)
	s_barrier
	ds_read_b128 v[176:179], v244 offset:0
	ds_read_b128 v[80:83], v246 offset:0
	ds_read_b128 v[84:87], v246 offset:2048
	ds_read_b128 v[88:91], v246 offset:4096
	ds_read_b128 v[92:95], v246 offset:6144
	ds_read_b128 v[180:183], v244 offset:2048
	ds_read_b128 v[184:187], v244 offset:4096
	ds_read_b128 v[188:191], v244 offset:6144
	s_waitcnt lgkmcnt(6)
	v_mfma_f32_16x16x32_bf16 v[0:3], v[80:83], v[176:179], v[0:3]
	ds_read_b128 v[208:211], v245 offset:0
	s_add_i32 m0, s81, 32768
	s_waitcnt lgkmcnt(6)
	v_mfma_f32_16x16x32_bf16 v[4:7], v[84:87], v[176:179], v[4:7]
	ds_read_b128 v[224:227], v247 offset:0
	global_load_lds_dwordx4 v240, s[76:77]
	s_waitcnt lgkmcnt(6)
	v_mfma_f32_16x16x32_bf16 v[8:11], v[88:91], v[176:179], v[8:11]
	ds_read_b128 v[228:231], v247 offset:2048
	s_add_i32 m0, s81, 36864
	s_waitcnt lgkmcnt(6)
	v_mfma_f32_16x16x32_bf16 v[12:15], v[92:95], v[176:179], v[12:15]
	ds_read_b128 v[232:235], v247 offset:4096
	global_load_lds_dwordx4 v241, s[76:77]
	s_waitcnt lgkmcnt(6)
	v_mfma_f32_16x16x32_bf16 v[16:19], v[80:83], v[180:183], v[16:19]
	ds_read_b128 v[236:239], v247 offset:6144
	s_add_i32 m0, s81, 40960
	v_mfma_f32_16x16x32_bf16 v[20:23], v[84:87], v[180:183], v[20:23]
	ds_read_b128 v[212:215], v245 offset:2048
	global_load_lds_dwordx4 v242, s[76:77]
	v_mfma_f32_16x16x32_bf16 v[24:27], v[88:91], v[180:183], v[24:27]
	ds_read_b128 v[216:219], v245 offset:4096
	s_add_i32 m0, s81, 45056
	v_mfma_f32_16x16x32_bf16 v[28:31], v[92:95], v[180:183], v[28:31]
	ds_read_b128 v[220:223], v245 offset:6144
	global_load_lds_dwordx4 v243, s[76:77]
	s_waitcnt lgkmcnt(9)
	v_mfma_f32_16x16x32_bf16 v[32:35], v[80:83], v[184:187], v[32:35]
	s_add_i32 m0, s81, 49152
	v_mfma_f32_16x16x32_bf16 v[36:39], v[84:87], v[184:187], v[36:39]
	global_load_lds_dwordx4 v240, s[78:79]
	v_mfma_f32_16x16x32_bf16 v[40:43], v[88:91], v[184:187], v[40:43]
	s_add_i32 m0, s81, 53248
	v_mfma_f32_16x16x32_bf16 v[44:47], v[92:95], v[184:187], v[44:47]
	global_load_lds_dwordx4 v241, s[78:79]
	s_waitcnt lgkmcnt(8)
	v_mfma_f32_16x16x32_bf16 v[48:51], v[80:83], v[188:191], v[48:51]
	s_add_i32 m0, s81, 57344
	v_mfma_f32_16x16x32_bf16 v[52:55], v[84:87], v[188:191], v[52:55]
	global_load_lds_dwordx4 v242, s[78:79]
	v_mfma_f32_16x16x32_bf16 v[56:59], v[88:91], v[188:191], v[56:59]
	s_add_i32 m0, s81, 61440
	v_mfma_f32_16x16x32_bf16 v[60:63], v[92:95], v[188:191], v[60:63]
	global_load_lds_dwordx4 v243, s[78:79]
	s_waitcnt lgkmcnt(6)
	v_mfma_f32_16x16x32_bf16 v[0:3], v[224:227], v[208:211], v[0:3]
	s_add_u32 s76, s76, 0x80
	s_addc_u32 s77, s77, 0
	s_waitcnt lgkmcnt(5)
	v_mfma_f32_16x16x32_bf16 v[4:7], v[228:231], v[208:211], v[4:7]
	s_waitcnt lgkmcnt(4)
	v_mfma_f32_16x16x32_bf16 v[8:11], v[232:235], v[208:211], v[8:11]
	s_add_u32 s78, s78, 0x80
	s_addc_u32 s79, s79, 0
	s_waitcnt lgkmcnt(3)
	v_mfma_f32_16x16x32_bf16 v[12:15], v[236:239], v[208:211], v[12:15]
	s_waitcnt lgkmcnt(2)
	v_mfma_f32_16x16x32_bf16 v[16:19], v[224:227], v[212:215], v[16:19]
	v_add_u32_e32 v96, 0x10000, v102
	v_mfma_f32_16x16x32_bf16 v[20:23], v[228:231], v[212:215], v[20:23]
	global_load_dwordx4 v[98:101], v96, s[86:87] offset:16 nt
	v_mfma_f32_16x16x32_bf16 v[24:27], v[232:235], v[212:215], v[24:27]
	v_mfma_f32_16x16x32_bf16 v[28:31], v[236:239], v[212:215], v[28:31]
	s_waitcnt lgkmcnt(1)
	v_mfma_f32_16x16x32_bf16 v[32:35], v[224:227], v[216:219], v[32:35]
	v_mfma_f32_16x16x32_bf16 v[36:39], v[228:231], v[216:219], v[36:39]
	v_mfma_f32_16x16x32_bf16 v[40:43], v[232:235], v[216:219], v[40:43]
	v_mfma_f32_16x16x32_bf16 v[44:47], v[236:239], v[216:219], v[44:47]
	s_waitcnt lgkmcnt(0)
	v_mfma_f32_16x16x32_bf16 v[48:51], v[224:227], v[220:223], v[48:51]
	v_mfma_f32_16x16x32_bf16 v[52:55], v[228:231], v[220:223], v[52:55]
	v_mfma_f32_16x16x32_bf16 v[56:59], v[232:235], v[220:223], v[56:59]
	v_mfma_f32_16x16x32_bf16 v[60:63], v[236:239], v[220:223], v[60:63]
	s_waitcnt vmcnt(1)
	s_barrier
	ds_read_b128 v[176:179], v244 offset:32768
	ds_read_b128 v[80:83], v246 offset:32768
	ds_read_b128 v[84:87], v246 offset:34816
	ds_read_b128 v[88:91], v246 offset:36864
	ds_read_b128 v[92:95], v246 offset:38912
	ds_read_b128 v[180:183], v244 offset:34816
	ds_read_b128 v[184:187], v244 offset:36864
	ds_read_b128 v[188:191], v244 offset:38912
	s_waitcnt lgkmcnt(6)
	v_mfma_f32_16x16x32_bf16 v[0:3], v[80:83], v[176:179], v[0:3]
	ds_read_b128 v[208:211], v245 offset:32768
	s_add_i32 m0, s81, 0
	s_waitcnt lgkmcnt(6)
	v_mfma_f32_16x16x32_bf16 v[4:7], v[84:87], v[176:179], v[4:7]
	ds_read_b128 v[224:227], v247 offset:32768
	global_load_lds_dwordx4 v240, s[76:77]
	s_waitcnt lgkmcnt(6)
	v_mfma_f32_16x16x32_bf16 v[8:11], v[88:91], v[176:179], v[8:11]
	ds_read_b128 v[228:231], v247 offset:34816
	s_add_i32 m0, s81, 4096
	s_waitcnt lgkmcnt(6)
	v_mfma_f32_16x16x32_bf16 v[12:15], v[92:95], v[176:179], v[12:15]
	ds_read_b128 v[232:235], v247 offset:36864
	global_load_lds_dwordx4 v241, s[76:77]
	s_waitcnt lgkmcnt(6)
	v_mfma_f32_16x16x32_bf16 v[16:19], v[80:83], v[180:183], v[16:19]
	ds_read_b128 v[236:239], v247 offset:38912
	s_add_i32 m0, s81, 8192
	v_mfma_f32_16x16x32_bf16 v[20:23], v[84:87], v[180:183], v[20:23]
	ds_read_b128 v[212:215], v245 offset:34816
	global_load_lds_dwordx4 v242, s[76:77]
	v_mfma_f32_16x16x32_bf16 v[24:27], v[88:91], v[180:183], v[24:27]
	ds_read_b128 v[216:219], v245 offset:36864
	s_add_i32 m0, s81, 12288
	v_mfma_f32_16x16x32_bf16 v[28:31], v[92:95], v[180:183], v[28:31]
	ds_read_b128 v[220:223], v245 offset:38912
	global_load_lds_dwordx4 v243, s[76:77]
	s_waitcnt lgkmcnt(9)
	v_mfma_f32_16x16x32_bf16 v[32:35], v[80:83], v[184:187], v[32:35]
	s_add_i32 m0, s81, 16384
	v_mfma_f32_16x16x32_bf16 v[36:39], v[84:87], v[184:187], v[36:39]
	global_load_lds_dwordx4 v240, s[78:79]
	v_mfma_f32_16x16x32_bf16 v[40:43], v[88:91], v[184:187], v[40:43]
	s_add_i32 m0, s81, 20480
	v_mfma_f32_16x16x32_bf16 v[44:47], v[92:95], v[184:187], v[44:47]
	global_load_lds_dwordx4 v241, s[78:79]
	s_waitcnt lgkmcnt(8)
	v_mfma_f32_16x16x32_bf16 v[48:51], v[80:83], v[188:191], v[48:51]
	s_add_i32 m0, s81, 24576
	v_mfma_f32_16x16x32_bf16 v[52:55], v[84:87], v[188:191], v[52:55]
	global_load_lds_dwordx4 v242, s[78:79]
	v_mfma_f32_16x16x32_bf16 v[56:59], v[88:91], v[188:191], v[56:59]
	s_add_i32 m0, s81, 28672
	v_mfma_f32_16x16x32_bf16 v[60:63], v[92:95], v[188:191], v[60:63]
	global_load_lds_dwordx4 v243, s[78:79]
	s_waitcnt lgkmcnt(6)
	v_mfma_f32_16x16x32_bf16 v[0:3], v[224:227], v[208:211], v[0:3]
	s_add_u32 s76, s76, 0x80
	s_addc_u32 s77, s77, 0
	s_waitcnt lgkmcnt(5)
	v_mfma_f32_16x16x32_bf16 v[4:7], v[228:231], v[208:211], v[4:7]
	s_waitcnt lgkmcnt(4)
	v_mfma_f32_16x16x32_bf16 v[8:11], v[232:235], v[208:211], v[8:11]
	s_add_u32 s78, s78, 0x80
	s_addc_u32 s79, s79, 0
	s_waitcnt lgkmcnt(3)
	v_mfma_f32_16x16x32_bf16 v[12:15], v[236:239], v[208:211], v[12:15]
	s_waitcnt lgkmcnt(2)
	v_mfma_f32_16x16x32_bf16 v[16:19], v[224:227], v[212:215], v[16:19]
	v_add_u32_e32 v96, 0x20000, v102
	v_mfma_f32_16x16x32_bf16 v[20:23], v[228:231], v[212:215], v[20:23]
	global_load_dwordx4 v[104:107], v96, s[86:87] nt
	v_mfma_f32_16x16x32_bf16 v[24:27], v[232:235], v[212:215], v[24:27]
	v_mfma_f32_16x16x32_bf16 v[28:31], v[236:239], v[212:215], v[28:31]
	s_waitcnt lgkmcnt(1)
	v_mfma_f32_16x16x32_bf16 v[32:35], v[224:227], v[216:219], v[32:35]
	v_mfma_f32_16x16x32_bf16 v[36:39], v[228:231], v[216:219], v[36:39]
	v_mfma_f32_16x16x32_bf16 v[40:43], v[232:235], v[216:219], v[40:43]
	v_mfma_f32_16x16x32_bf16 v[44:47], v[236:239], v[216:219], v[44:47]
	s_waitcnt lgkmcnt(0)
	v_mfma_f32_16x16x32_bf16 v[48:51], v[224:227], v[220:223], v[48:51]
	v_mfma_f32_16x16x32_bf16 v[52:55], v[228:231], v[220:223], v[52:55]
	v_mfma_f32_16x16x32_bf16 v[56:59], v[232:235], v[220:223], v[56:59]
	v_mfma_f32_16x16x32_bf16 v[60:63], v[236:239], v[220:223], v[60:63]
	s_waitcnt vmcnt(1)
	s_barrier
	ds_read_b128 v[176:179], v244 offset:0
	ds_read_b128 v[80:83], v246 offset:0
	ds_read_b128 v[84:87], v246 offset:2048
	ds_read_b128 v[88:91], v246 offset:4096
	ds_read_b128 v[92:95], v246 offset:6144
	ds_read_b128 v[180:183], v244 offset:2048
	ds_read_b128 v[184:187], v244 offset:4096
	ds_read_b128 v[188:191], v244 offset:6144
	s_waitcnt lgkmcnt(6)
	v_mfma_f32_16x16x32_bf16 v[0:3], v[80:83], v[176:179], v[0:3]
	ds_read_b128 v[208:211], v245 offset:0
	s_add_i32 m0, s81, 32768
	s_waitcnt lgkmcnt(6)
	v_mfma_f32_16x16x32_bf16 v[4:7], v[84:87], v[176:179], v[4:7]
	ds_read_b128 v[224:227], v247 offset:0
	global_load_lds_dwordx4 v240, s[76:77]
	s_waitcnt lgkmcnt(6)
	v_mfma_f32_16x16x32_bf16 v[8:11], v[88:91], v[176:179], v[8:11]
	ds_read_b128 v[228:231], v247 offset:2048
	s_add_i32 m0, s81, 36864
	s_waitcnt lgkmcnt(6)
	v_mfma_f32_16x16x32_bf16 v[12:15], v[92:95], v[176:179], v[12:15]
	ds_read_b128 v[232:235], v247 offset:4096
	global_load_lds_dwordx4 v241, s[76:77]
	s_waitcnt lgkmcnt(6)
	v_mfma_f32_16x16x32_bf16 v[16:19], v[80:83], v[180:183], v[16:19]
	ds_read_b128 v[236:239], v247 offset:6144
	s_add_i32 m0, s81, 40960
	v_mfma_f32_16x16x32_bf16 v[20:23], v[84:87], v[180:183], v[20:23]
	ds_read_b128 v[212:215], v245 offset:2048
	global_load_lds_dwordx4 v242, s[76:77]
	v_mfma_f32_16x16x32_bf16 v[24:27], v[88:91], v[180:183], v[24:27]
	ds_read_b128 v[216:219], v245 offset:4096
	s_add_i32 m0, s81, 45056
	v_mfma_f32_16x16x32_bf16 v[28:31], v[92:95], v[180:183], v[28:31]
	ds_read_b128 v[220:223], v245 offset:6144
	global_load_lds_dwordx4 v243, s[76:77]
	s_waitcnt lgkmcnt(9)
	v_mfma_f32_16x16x32_bf16 v[32:35], v[80:83], v[184:187], v[32:35]
	s_add_i32 m0, s81, 49152
	v_mfma_f32_16x16x32_bf16 v[36:39], v[84:87], v[184:187], v[36:39]
	global_load_lds_dwordx4 v240, s[78:79]
	v_mfma_f32_16x16x32_bf16 v[40:43], v[88:91], v[184:187], v[40:43]
	s_add_i32 m0, s81, 53248
	v_mfma_f32_16x16x32_bf16 v[44:47], v[92:95], v[184:187], v[44:47]
	global_load_lds_dwordx4 v241, s[78:79]
	s_waitcnt lgkmcnt(8)
	v_mfma_f32_16x16x32_bf16 v[48:51], v[80:83], v[188:191], v[48:51]
	s_add_i32 m0, s81, 57344
	v_mfma_f32_16x16x32_bf16 v[52:55], v[84:87], v[188:191], v[52:55]
	global_load_lds_dwordx4 v242, s[78:79]
	v_mfma_f32_16x16x32_bf16 v[56:59], v[88:91], v[188:191], v[56:59]
	s_add_i32 m0, s81, 61440
	v_mfma_f32_16x16x32_bf16 v[60:63], v[92:95], v[188:191], v[60:63]
	global_load_lds_dwordx4 v243, s[78:79]
	s_waitcnt lgkmcnt(6)
	v_mfma_f32_16x16x32_bf16 v[0:3], v[224:227], v[208:211], v[0:3]
	s_add_u32 s76, s76, 0x80
	s_addc_u32 s77, s77, 0
	s_waitcnt lgkmcnt(5)
	v_mfma_f32_16x16x32_bf16 v[4:7], v[228:231], v[208:211], v[4:7]
	s_waitcnt lgkmcnt(4)
	v_mfma_f32_16x16x32_bf16 v[8:11], v[232:235], v[208:211], v[8:11]
	s_add_u32 s78, s78, 0x80
	s_addc_u32 s79, s79, 0
	s_waitcnt lgkmcnt(3)
	v_mfma_f32_16x16x32_bf16 v[12:15], v[236:239], v[208:211], v[12:15]
	s_waitcnt lgkmcnt(2)
	v_mfma_f32_16x16x32_bf16 v[16:19], v[224:227], v[212:215], v[16:19]
	v_add_u32_e32 v96, 0x20000, v102
	v_mfma_f32_16x16x32_bf16 v[20:23], v[228:231], v[212:215], v[20:23]
	global_load_dwordx4 v[110:113], v96, s[86:87] offset:16 nt
	v_mfma_f32_16x16x32_bf16 v[24:27], v[232:235], v[212:215], v[24:27]
	v_mfma_f32_16x16x32_bf16 v[28:31], v[236:239], v[212:215], v[28:31]
	s_waitcnt lgkmcnt(1)
	v_mfma_f32_16x16x32_bf16 v[32:35], v[224:227], v[216:219], v[32:35]
	v_mfma_f32_16x16x32_bf16 v[36:39], v[228:231], v[216:219], v[36:39]
	v_mfma_f32_16x16x32_bf16 v[40:43], v[232:235], v[216:219], v[40:43]
	v_mfma_f32_16x16x32_bf16 v[44:47], v[236:239], v[216:219], v[44:47]
	s_waitcnt lgkmcnt(0)
	v_mfma_f32_16x16x32_bf16 v[48:51], v[224:227], v[220:223], v[48:51]
	v_mfma_f32_16x16x32_bf16 v[52:55], v[228:231], v[220:223], v[52:55]
	v_mfma_f32_16x16x32_bf16 v[56:59], v[232:235], v[220:223], v[56:59]
	v_mfma_f32_16x16x32_bf16 v[60:63], v[236:239], v[220:223], v[60:63]
	s_waitcnt vmcnt(1)
	s_barrier
	ds_read_b128 v[176:179], v244 offset:32768
	ds_read_b128 v[80:83], v246 offset:32768
	ds_read_b128 v[84:87], v246 offset:34816
	ds_read_b128 v[88:91], v246 offset:36864
	ds_read_b128 v[92:95], v246 offset:38912
	ds_read_b128 v[180:183], v244 offset:34816
	ds_read_b128 v[184:187], v244 offset:36864
	ds_read_b128 v[188:191], v244 offset:38912
	s_waitcnt lgkmcnt(6)
	v_mfma_f32_16x16x32_bf16 v[0:3], v[80:83], v[176:179], v[0:3]
	ds_read_b128 v[208:211], v245 offset:32768
	s_add_i32 m0, s81, 0
	s_waitcnt lgkmcnt(6)
	v_mfma_f32_16x16x32_bf16 v[4:7], v[84:87], v[176:179], v[4:7]
	ds_read_b128 v[224:227], v247 offset:32768
	global_load_lds_dwordx4 v240, s[76:77]
	s_waitcnt lgkmcnt(6)
	v_mfma_f32_16x16x32_bf16 v[8:11], v[88:91], v[176:179], v[8:11]
	ds_read_b128 v[228:231], v247 offset:34816
	s_add_i32 m0, s81, 4096
	s_waitcnt lgkmcnt(6)
	v_mfma_f32_16x16x32_bf16 v[12:15], v[92:95], v[176:179], v[12:15]
	ds_read_b128 v[232:235], v247 offset:36864
	global_load_lds_dwordx4 v241, s[76:77]
	s_waitcnt lgkmcnt(6)
	v_mfma_f32_16x16x32_bf16 v[16:19], v[80:83], v[180:183], v[16:19]
	ds_read_b128 v[236:239], v247 offset:38912
	s_add_i32 m0, s81, 8192
	v_mfma_f32_16x16x32_bf16 v[20:23], v[84:87], v[180:183], v[20:23]
	ds_read_b128 v[212:215], v245 offset:34816
	global_load_lds_dwordx4 v242, s[76:77]
	v_mfma_f32_16x16x32_bf16 v[24:27], v[88:91], v[180:183], v[24:27]
	ds_read_b128 v[216:219], v245 offset:36864
	s_add_i32 m0, s81, 12288
	v_mfma_f32_16x16x32_bf16 v[28:31], v[92:95], v[180:183], v[28:31]
	ds_read_b128 v[220:223], v245 offset:38912
	global_load_lds_dwordx4 v243, s[76:77]
	s_waitcnt lgkmcnt(9)
	v_mfma_f32_16x16x32_bf16 v[32:35], v[80:83], v[184:187], v[32:35]
	s_add_i32 m0, s81, 16384
	v_mfma_f32_16x16x32_bf16 v[36:39], v[84:87], v[184:187], v[36:39]
	global_load_lds_dwordx4 v240, s[78:79]
	v_mfma_f32_16x16x32_bf16 v[40:43], v[88:91], v[184:187], v[40:43]
	s_add_i32 m0, s81, 20480
	v_mfma_f32_16x16x32_bf16 v[44:47], v[92:95], v[184:187], v[44:47]
	global_load_lds_dwordx4 v241, s[78:79]
	s_waitcnt lgkmcnt(8)
	v_mfma_f32_16x16x32_bf16 v[48:51], v[80:83], v[188:191], v[48:51]
	s_add_i32 m0, s81, 24576
	v_mfma_f32_16x16x32_bf16 v[52:55], v[84:87], v[188:191], v[52:55]
	global_load_lds_dwordx4 v242, s[78:79]
	v_mfma_f32_16x16x32_bf16 v[56:59], v[88:91], v[188:191], v[56:59]
	s_add_i32 m0, s81, 28672
	v_mfma_f32_16x16x32_bf16 v[60:63], v[92:95], v[188:191], v[60:63]
	global_load_lds_dwordx4 v243, s[78:79]
	s_waitcnt lgkmcnt(6)
	v_mfma_f32_16x16x32_bf16 v[0:3], v[224:227], v[208:211], v[0:3]
	s_add_u32 s76, s76, 0x80
	s_addc_u32 s77, s77, 0
	s_waitcnt lgkmcnt(5)
	v_mfma_f32_16x16x32_bf16 v[4:7], v[228:231], v[208:211], v[4:7]
	s_waitcnt lgkmcnt(4)
	v_mfma_f32_16x16x32_bf16 v[8:11], v[232:235], v[208:211], v[8:11]
	s_add_u32 s78, s78, 0x80
	s_addc_u32 s79, s79, 0
	s_waitcnt lgkmcnt(3)
	v_mfma_f32_16x16x32_bf16 v[12:15], v[236:239], v[208:211], v[12:15]
	s_waitcnt lgkmcnt(2)
	v_mfma_f32_16x16x32_bf16 v[16:19], v[224:227], v[212:215], v[16:19]
	v_add_u32_e32 v96, 0x30000, v102
	v_mfma_f32_16x16x32_bf16 v[20:23], v[228:231], v[212:215], v[20:23]
	global_load_dwordx4 v[116:119], v96, s[86:87] nt
	v_mfma_f32_16x16x32_bf16 v[24:27], v[232:235], v[212:215], v[24:27]
	v_mfma_f32_16x16x32_bf16 v[28:31], v[236:239], v[212:215], v[28:31]
	s_waitcnt lgkmcnt(1)
	v_mfma_f32_16x16x32_bf16 v[32:35], v[224:227], v[216:219], v[32:35]
	v_mfma_f32_16x16x32_bf16 v[36:39], v[228:231], v[216:219], v[36:39]
	v_mfma_f32_16x16x32_bf16 v[40:43], v[232:235], v[216:219], v[40:43]
	v_mfma_f32_16x16x32_bf16 v[44:47], v[236:239], v[216:219], v[44:47]
	s_waitcnt lgkmcnt(0)
	v_mfma_f32_16x16x32_bf16 v[48:51], v[224:227], v[220:223], v[48:51]
	v_mfma_f32_16x16x32_bf16 v[52:55], v[228:231], v[220:223], v[52:55]
	v_mfma_f32_16x16x32_bf16 v[56:59], v[232:235], v[220:223], v[56:59]
	v_mfma_f32_16x16x32_bf16 v[60:63], v[236:239], v[220:223], v[60:63]
	s_waitcnt vmcnt(1)
	s_barrier
	ds_read_b128 v[176:179], v244 offset:0
	ds_read_b128 v[80:83], v246 offset:0
	ds_read_b128 v[84:87], v246 offset:2048
	ds_read_b128 v[88:91], v246 offset:4096
	ds_read_b128 v[92:95], v246 offset:6144
	ds_read_b128 v[180:183], v244 offset:2048
	ds_read_b128 v[184:187], v244 offset:4096
	ds_read_b128 v[188:191], v244 offset:6144
	s_waitcnt lgkmcnt(6)
	v_mfma_f32_16x16x32_bf16 v[0:3], v[80:83], v[176:179], v[0:3]
	ds_read_b128 v[208:211], v245 offset:0
	s_add_i32 m0, s81, 32768
	s_waitcnt lgkmcnt(6)
	v_mfma_f32_16x16x32_bf16 v[4:7], v[84:87], v[176:179], v[4:7]
	ds_read_b128 v[224:227], v247 offset:0
	global_load_lds_dwordx4 v240, s[76:77]
	s_waitcnt lgkmcnt(6)
	v_mfma_f32_16x16x32_bf16 v[8:11], v[88:91], v[176:179], v[8:11]
	ds_read_b128 v[228:231], v247 offset:2048
	s_add_i32 m0, s81, 36864
	s_waitcnt lgkmcnt(6)
	v_mfma_f32_16x16x32_bf16 v[12:15], v[92:95], v[176:179], v[12:15]
	ds_read_b128 v[232:235], v247 offset:4096
	global_load_lds_dwordx4 v241, s[76:77]
	s_waitcnt lgkmcnt(6)
	v_mfma_f32_16x16x32_bf16 v[16:19], v[80:83], v[180:183], v[16:19]
	ds_read_b128 v[236:239], v247 offset:6144
	s_add_i32 m0, s81, 40960
	v_mfma_f32_16x16x32_bf16 v[20:23], v[84:87], v[180:183], v[20:23]
	ds_read_b128 v[212:215], v245 offset:2048
	global_load_lds_dwordx4 v242, s[76:77]
	v_mfma_f32_16x16x32_bf16 v[24:27], v[88:91], v[180:183], v[24:27]
	ds_read_b128 v[216:219], v245 offset:4096
	s_add_i32 m0, s81, 45056
	v_mfma_f32_16x16x32_bf16 v[28:31], v[92:95], v[180:183], v[28:31]
	ds_read_b128 v[220:223], v245 offset:6144
	global_load_lds_dwordx4 v243, s[76:77]
	s_waitcnt lgkmcnt(9)
	v_mfma_f32_16x16x32_bf16 v[32:35], v[80:83], v[184:187], v[32:35]
	s_add_i32 m0, s81, 49152
	v_mfma_f32_16x16x32_bf16 v[36:39], v[84:87], v[184:187], v[36:39]
	global_load_lds_dwordx4 v240, s[78:79]
	v_mfma_f32_16x16x32_bf16 v[40:43], v[88:91], v[184:187], v[40:43]
	s_add_i32 m0, s81, 53248
	v_mfma_f32_16x16x32_bf16 v[44:47], v[92:95], v[184:187], v[44:47]
	global_load_lds_dwordx4 v241, s[78:79]
	s_waitcnt lgkmcnt(8)
	v_mfma_f32_16x16x32_bf16 v[48:51], v[80:83], v[188:191], v[48:51]
	s_add_i32 m0, s81, 57344
	v_mfma_f32_16x16x32_bf16 v[52:55], v[84:87], v[188:191], v[52:55]
	global_load_lds_dwordx4 v242, s[78:79]
	v_mfma_f32_16x16x32_bf16 v[56:59], v[88:91], v[188:191], v[56:59]
	s_add_i32 m0, s81, 61440
	v_mfma_f32_16x16x32_bf16 v[60:63], v[92:95], v[188:191], v[60:63]
	global_load_lds_dwordx4 v243, s[78:79]
	s_waitcnt lgkmcnt(6)
	v_mfma_f32_16x16x32_bf16 v[0:3], v[224:227], v[208:211], v[0:3]
	s_add_u32 s76, s76, 0x80
	s_addc_u32 s77, s77, 0
	s_waitcnt lgkmcnt(5)
	v_mfma_f32_16x16x32_bf16 v[4:7], v[228:231], v[208:211], v[4:7]
	s_waitcnt lgkmcnt(4)
	v_mfma_f32_16x16x32_bf16 v[8:11], v[232:235], v[208:211], v[8:11]
	s_add_u32 s78, s78, 0x80
	s_addc_u32 s79, s79, 0
	s_waitcnt lgkmcnt(3)
	v_mfma_f32_16x16x32_bf16 v[12:15], v[236:239], v[208:211], v[12:15]
	s_waitcnt lgkmcnt(2)
	v_mfma_f32_16x16x32_bf16 v[16:19], v[224:227], v[212:215], v[16:19]
	v_add_u32_e32 v96, 0x30000, v102
	v_mfma_f32_16x16x32_bf16 v[20:23], v[228:231], v[212:215], v[20:23]
	global_load_dwordx4 v[120:123], v96, s[86:87] offset:16 nt
	v_mfma_f32_16x16x32_bf16 v[24:27], v[232:235], v[212:215], v[24:27]
	v_mfma_f32_16x16x32_bf16 v[28:31], v[236:239], v[212:215], v[28:31]
	s_waitcnt lgkmcnt(1)
	v_mfma_f32_16x16x32_bf16 v[32:35], v[224:227], v[216:219], v[32:35]
	v_mfma_f32_16x16x32_bf16 v[36:39], v[228:231], v[216:219], v[36:39]
	v_mfma_f32_16x16x32_bf16 v[40:43], v[232:235], v[216:219], v[40:43]
	v_mfma_f32_16x16x32_bf16 v[44:47], v[236:239], v[216:219], v[44:47]
	s_waitcnt lgkmcnt(0)
	v_mfma_f32_16x16x32_bf16 v[48:51], v[224:227], v[220:223], v[48:51]
	v_mfma_f32_16x16x32_bf16 v[52:55], v[228:231], v[220:223], v[52:55]
	v_mfma_f32_16x16x32_bf16 v[56:59], v[232:235], v[220:223], v[56:59]
	v_mfma_f32_16x16x32_bf16 v[60:63], v[236:239], v[220:223], v[60:63]
	s_waitcnt vmcnt(1)
	s_barrier
	ds_read_b128 v[176:179], v244 offset:32768
	ds_read_b128 v[80:83], v246 offset:32768
	ds_read_b128 v[84:87], v246 offset:34816
	ds_read_b128 v[88:91], v246 offset:36864
	ds_read_b128 v[92:95], v246 offset:38912
	ds_read_b128 v[180:183], v244 offset:34816
	ds_read_b128 v[184:187], v244 offset:36864
	ds_read_b128 v[188:191], v244 offset:38912
	s_waitcnt lgkmcnt(6)
	v_mfma_f32_16x16x32_bf16 v[0:3], v[80:83], v[176:179], v[0:3]
	ds_read_b128 v[208:211], v245 offset:32768
	s_add_i32 m0, s81, 0
	s_waitcnt lgkmcnt(6)
	v_mfma_f32_16x16x32_bf16 v[4:7], v[84:87], v[176:179], v[4:7]
	ds_read_b128 v[224:227], v247 offset:32768
	global_load_lds_dwordx4 v240, s[76:77]
	s_waitcnt lgkmcnt(6)
	v_mfma_f32_16x16x32_bf16 v[8:11], v[88:91], v[176:179], v[8:11]
	ds_read_b128 v[228:231], v247 offset:34816
	s_add_i32 m0, s81, 4096
	s_waitcnt lgkmcnt(6)
	v_mfma_f32_16x16x32_bf16 v[12:15], v[92:95], v[176:179], v[12:15]
	ds_read_b128 v[232:235], v247 offset:36864
	global_load_lds_dwordx4 v241, s[76:77]
	s_waitcnt lgkmcnt(6)
	v_mfma_f32_16x16x32_bf16 v[16:19], v[80:83], v[180:183], v[16:19]
	ds_read_b128 v[236:239], v247 offset:38912
	s_add_i32 m0, s81, 8192
	v_mfma_f32_16x16x32_bf16 v[20:23], v[84:87], v[180:183], v[20:23]
	ds_read_b128 v[212:215], v245 offset:34816
	global_load_lds_dwordx4 v242, s[76:77]
	v_mfma_f32_16x16x32_bf16 v[24:27], v[88:91], v[180:183], v[24:27]
	ds_read_b128 v[216:219], v245 offset:36864
	s_add_i32 m0, s81, 12288
	v_mfma_f32_16x16x32_bf16 v[28:31], v[92:95], v[180:183], v[28:31]
	ds_read_b128 v[220:223], v245 offset:38912
	global_load_lds_dwordx4 v243, s[76:77]
	s_waitcnt lgkmcnt(9)
	v_mfma_f32_16x16x32_bf16 v[32:35], v[80:83], v[184:187], v[32:35]
	s_add_i32 m0, s81, 16384
	v_mfma_f32_16x16x32_bf16 v[36:39], v[84:87], v[184:187], v[36:39]
	global_load_lds_dwordx4 v240, s[78:79]
	v_mfma_f32_16x16x32_bf16 v[40:43], v[88:91], v[184:187], v[40:43]
	s_add_i32 m0, s81, 20480
	v_mfma_f32_16x16x32_bf16 v[44:47], v[92:95], v[184:187], v[44:47]
	global_load_lds_dwordx4 v241, s[78:79]
	s_waitcnt lgkmcnt(8)
	v_mfma_f32_16x16x32_bf16 v[48:51], v[80:83], v[188:191], v[48:51]
	s_add_i32 m0, s81, 24576
	v_mfma_f32_16x16x32_bf16 v[52:55], v[84:87], v[188:191], v[52:55]
	global_load_lds_dwordx4 v242, s[78:79]
	v_mfma_f32_16x16x32_bf16 v[56:59], v[88:91], v[188:191], v[56:59]
	s_add_i32 m0, s81, 28672
	v_mfma_f32_16x16x32_bf16 v[60:63], v[92:95], v[188:191], v[60:63]
	global_load_lds_dwordx4 v243, s[78:79]
	s_waitcnt lgkmcnt(6)
	v_mfma_f32_16x16x32_bf16 v[0:3], v[224:227], v[208:211], v[0:3]
	s_add_u32 s76, s76, 0x80
	s_addc_u32 s77, s77, 0
	s_waitcnt lgkmcnt(5)
	v_mfma_f32_16x16x32_bf16 v[4:7], v[228:231], v[208:211], v[4:7]
	s_waitcnt lgkmcnt(4)
	v_mfma_f32_16x16x32_bf16 v[8:11], v[232:235], v[208:211], v[8:11]
	s_add_u32 s78, s78, 0x80
	s_addc_u32 s79, s79, 0
	s_waitcnt lgkmcnt(3)
	v_mfma_f32_16x16x32_bf16 v[12:15], v[236:239], v[208:211], v[12:15]
	s_waitcnt lgkmcnt(2)
	v_mfma_f32_16x16x32_bf16 v[16:19], v[224:227], v[212:215], v[16:19]
	v_add_u32_e32 v96, 0x40000, v102
	v_mfma_f32_16x16x32_bf16 v[20:23], v[228:231], v[212:215], v[20:23]
	global_load_dwordx4 v[126:129], v96, s[86:87] nt
	v_mfma_f32_16x16x32_bf16 v[24:27], v[232:235], v[212:215], v[24:27]
	v_mfma_f32_16x16x32_bf16 v[28:31], v[236:239], v[212:215], v[28:31]
	s_waitcnt lgkmcnt(1)
	v_mfma_f32_16x16x32_bf16 v[32:35], v[224:227], v[216:219], v[32:35]
	v_mfma_f32_16x16x32_bf16 v[36:39], v[228:231], v[216:219], v[36:39]
	v_mfma_f32_16x16x32_bf16 v[40:43], v[232:235], v[216:219], v[40:43]
	v_mfma_f32_16x16x32_bf16 v[44:47], v[236:239], v[216:219], v[44:47]
	s_waitcnt lgkmcnt(0)
	v_mfma_f32_16x16x32_bf16 v[48:51], v[224:227], v[220:223], v[48:51]
	v_mfma_f32_16x16x32_bf16 v[52:55], v[228:231], v[220:223], v[52:55]
	v_mfma_f32_16x16x32_bf16 v[56:59], v[232:235], v[220:223], v[56:59]
	v_mfma_f32_16x16x32_bf16 v[60:63], v[236:239], v[220:223], v[60:63]
	s_waitcnt vmcnt(1)
	s_barrier
	ds_read_b128 v[176:179], v244 offset:0
	ds_read_b128 v[80:83], v246 offset:0
	ds_read_b128 v[84:87], v246 offset:2048
	ds_read_b128 v[88:91], v246 offset:4096
	ds_read_b128 v[92:95], v246 offset:6144
	ds_read_b128 v[180:183], v244 offset:2048
	ds_read_b128 v[184:187], v244 offset:4096
	ds_read_b128 v[188:191], v244 offset:6144
	s_waitcnt lgkmcnt(6)
	v_mfma_f32_16x16x32_bf16 v[0:3], v[80:83], v[176:179], v[0:3]
	ds_read_b128 v[208:211], v245 offset:0
	s_add_i32 m0, s81, 32768
	s_waitcnt lgkmcnt(6)
	v_mfma_f32_16x16x32_bf16 v[4:7], v[84:87], v[176:179], v[4:7]
	ds_read_b128 v[224:227], v247 offset:0
	global_load_lds_dwordx4 v240, s[76:77]
	s_waitcnt lgkmcnt(6)
	v_mfma_f32_16x16x32_bf16 v[8:11], v[88:91], v[176:179], v[8:11]
	ds_read_b128 v[228:231], v247 offset:2048
	s_add_i32 m0, s81, 36864
	s_waitcnt lgkmcnt(6)
	v_mfma_f32_16x16x32_bf16 v[12:15], v[92:95], v[176:179], v[12:15]
	ds_read_b128 v[232:235], v247 offset:4096
	global_load_lds_dwordx4 v241, s[76:77]
	s_waitcnt lgkmcnt(6)
	v_mfma_f32_16x16x32_bf16 v[16:19], v[80:83], v[180:183], v[16:19]
	ds_read_b128 v[236:239], v247 offset:6144
	s_add_i32 m0, s81, 40960
	v_mfma_f32_16x16x32_bf16 v[20:23], v[84:87], v[180:183], v[20:23]
	ds_read_b128 v[212:215], v245 offset:2048
	global_load_lds_dwordx4 v242, s[76:77]
	v_mfma_f32_16x16x32_bf16 v[24:27], v[88:91], v[180:183], v[24:27]
	ds_read_b128 v[216:219], v245 offset:4096
	s_add_i32 m0, s81, 45056
	v_mfma_f32_16x16x32_bf16 v[28:31], v[92:95], v[180:183], v[28:31]
	ds_read_b128 v[220:223], v245 offset:6144
	global_load_lds_dwordx4 v243, s[76:77]
	s_waitcnt lgkmcnt(9)
	v_mfma_f32_16x16x32_bf16 v[32:35], v[80:83], v[184:187], v[32:35]
	s_add_i32 m0, s81, 49152
	v_mfma_f32_16x16x32_bf16 v[36:39], v[84:87], v[184:187], v[36:39]
	global_load_lds_dwordx4 v240, s[78:79]
	v_mfma_f32_16x16x32_bf16 v[40:43], v[88:91], v[184:187], v[40:43]
	s_add_i32 m0, s81, 53248
	v_mfma_f32_16x16x32_bf16 v[44:47], v[92:95], v[184:187], v[44:47]
	global_load_lds_dwordx4 v241, s[78:79]
	s_waitcnt lgkmcnt(8)
	v_mfma_f32_16x16x32_bf16 v[48:51], v[80:83], v[188:191], v[48:51]
	s_add_i32 m0, s81, 57344
	v_mfma_f32_16x16x32_bf16 v[52:55], v[84:87], v[188:191], v[52:55]
	global_load_lds_dwordx4 v242, s[78:79]
	v_mfma_f32_16x16x32_bf16 v[56:59], v[88:91], v[188:191], v[56:59]
	s_add_i32 m0, s81, 61440
	v_mfma_f32_16x16x32_bf16 v[60:63], v[92:95], v[188:191], v[60:63]
	global_load_lds_dwordx4 v243, s[78:79]
	s_waitcnt lgkmcnt(6)
	v_mfma_f32_16x16x32_bf16 v[0:3], v[224:227], v[208:211], v[0:3]
	s_add_u32 s76, s76, 0x80
	s_addc_u32 s77, s77, 0
	s_waitcnt lgkmcnt(5)
	v_mfma_f32_16x16x32_bf16 v[4:7], v[228:231], v[208:211], v[4:7]
	s_waitcnt lgkmcnt(4)
	v_mfma_f32_16x16x32_bf16 v[8:11], v[232:235], v[208:211], v[8:11]
	s_add_u32 s78, s78, 0x80
	s_addc_u32 s79, s79, 0
	s_waitcnt lgkmcnt(3)
	v_mfma_f32_16x16x32_bf16 v[12:15], v[236:239], v[208:211], v[12:15]
	s_waitcnt lgkmcnt(2)
	v_mfma_f32_16x16x32_bf16 v[16:19], v[224:227], v[212:215], v[16:19]
	v_add_u32_e32 v96, 0x40000, v102
	v_mfma_f32_16x16x32_bf16 v[20:23], v[228:231], v[212:215], v[20:23]
	global_load_dwordx4 v[168:171], v96, s[86:87] offset:16 nt
	v_mfma_f32_16x16x32_bf16 v[24:27], v[232:235], v[212:215], v[24:27]
	v_mfma_f32_16x16x32_bf16 v[28:31], v[236:239], v[212:215], v[28:31]
	s_waitcnt lgkmcnt(1)
	v_mfma_f32_16x16x32_bf16 v[32:35], v[224:227], v[216:219], v[32:35]
	v_mfma_f32_16x16x32_bf16 v[36:39], v[228:231], v[216:219], v[36:39]
	v_mfma_f32_16x16x32_bf16 v[40:43], v[232:235], v[216:219], v[40:43]
	v_mfma_f32_16x16x32_bf16 v[44:47], v[236:239], v[216:219], v[44:47]
	s_waitcnt lgkmcnt(0)
	v_mfma_f32_16x16x32_bf16 v[48:51], v[224:227], v[220:223], v[48:51]
	v_mfma_f32_16x16x32_bf16 v[52:55], v[228:231], v[220:223], v[52:55]
	v_mfma_f32_16x16x32_bf16 v[56:59], v[232:235], v[220:223], v[56:59]
	v_mfma_f32_16x16x32_bf16 v[60:63], v[236:239], v[220:223], v[60:63]
	s_waitcnt vmcnt(1)
	s_barrier
	ds_read_b128 v[176:179], v244 offset:32768
	ds_read_b128 v[80:83], v246 offset:32768
	ds_read_b128 v[84:87], v246 offset:34816
	ds_read_b128 v[88:91], v246 offset:36864
	ds_read_b128 v[92:95], v246 offset:38912
	ds_read_b128 v[180:183], v244 offset:34816
	ds_read_b128 v[184:187], v244 offset:36864
	ds_read_b128 v[188:191], v244 offset:38912
	s_waitcnt lgkmcnt(6)
	v_mfma_f32_16x16x32_bf16 v[0:3], v[80:83], v[176:179], v[0:3]
	ds_read_b128 v[208:211], v245 offset:32768
	s_add_i32 m0, s81, 0
	s_waitcnt lgkmcnt(6)
	v_mfma_f32_16x16x32_bf16 v[4:7], v[84:87], v[176:179], v[4:7]
	ds_read_b128 v[224:227], v247 offset:32768
	global_load_lds_dwordx4 v240, s[76:77]
	s_waitcnt lgkmcnt(6)
	v_mfma_f32_16x16x32_bf16 v[8:11], v[88:91], v[176:179], v[8:11]
	ds_read_b128 v[228:231], v247 offset:34816
	s_add_i32 m0, s81, 4096
	s_waitcnt lgkmcnt(6)
	v_mfma_f32_16x16x32_bf16 v[12:15], v[92:95], v[176:179], v[12:15]
	ds_read_b128 v[232:235], v247 offset:36864
	global_load_lds_dwordx4 v241, s[76:77]
	s_waitcnt lgkmcnt(6)
	v_mfma_f32_16x16x32_bf16 v[16:19], v[80:83], v[180:183], v[16:19]
	ds_read_b128 v[236:239], v247 offset:38912
	s_add_i32 m0, s81, 8192
	v_mfma_f32_16x16x32_bf16 v[20:23], v[84:87], v[180:183], v[20:23]
	ds_read_b128 v[212:215], v245 offset:34816
	global_load_lds_dwordx4 v242, s[76:77]
	v_mfma_f32_16x16x32_bf16 v[24:27], v[88:91], v[180:183], v[24:27]
	ds_read_b128 v[216:219], v245 offset:36864
	s_add_i32 m0, s81, 12288
	v_mfma_f32_16x16x32_bf16 v[28:31], v[92:95], v[180:183], v[28:31]
	ds_read_b128 v[220:223], v245 offset:38912
	global_load_lds_dwordx4 v243, s[76:77]
	s_waitcnt lgkmcnt(9)
	v_mfma_f32_16x16x32_bf16 v[32:35], v[80:83], v[184:187], v[32:35]
	s_add_i32 m0, s81, 16384
	v_mfma_f32_16x16x32_bf16 v[36:39], v[84:87], v[184:187], v[36:39]
	global_load_lds_dwordx4 v240, s[78:79]
	v_mfma_f32_16x16x32_bf16 v[40:43], v[88:91], v[184:187], v[40:43]
	s_add_i32 m0, s81, 20480
	v_mfma_f32_16x16x32_bf16 v[44:47], v[92:95], v[184:187], v[44:47]
	global_load_lds_dwordx4 v241, s[78:79]
	s_waitcnt lgkmcnt(8)
	v_mfma_f32_16x16x32_bf16 v[48:51], v[80:83], v[188:191], v[48:51]
	s_add_i32 m0, s81, 24576
	v_mfma_f32_16x16x32_bf16 v[52:55], v[84:87], v[188:191], v[52:55]
	global_load_lds_dwordx4 v242, s[78:79]
	v_mfma_f32_16x16x32_bf16 v[56:59], v[88:91], v[188:191], v[56:59]
	s_add_i32 m0, s81, 28672
	v_mfma_f32_16x16x32_bf16 v[60:63], v[92:95], v[188:191], v[60:63]
	global_load_lds_dwordx4 v243, s[78:79]
	s_waitcnt lgkmcnt(6)
	v_mfma_f32_16x16x32_bf16 v[0:3], v[224:227], v[208:211], v[0:3]
	s_add_u32 s76, s76, 0x80
	s_addc_u32 s77, s77, 0
	s_waitcnt lgkmcnt(5)
	v_mfma_f32_16x16x32_bf16 v[4:7], v[228:231], v[208:211], v[4:7]
	s_waitcnt lgkmcnt(4)
	v_mfma_f32_16x16x32_bf16 v[8:11], v[232:235], v[208:211], v[8:11]
	s_add_u32 s78, s78, 0x80
	s_addc_u32 s79, s79, 0
	s_waitcnt lgkmcnt(3)
	v_mfma_f32_16x16x32_bf16 v[12:15], v[236:239], v[208:211], v[12:15]
	s_waitcnt lgkmcnt(2)
	v_mfma_f32_16x16x32_bf16 v[16:19], v[224:227], v[212:215], v[16:19]
	v_add_u32_e32 v96, 0x50000, v102
	v_mfma_f32_16x16x32_bf16 v[20:23], v[228:231], v[212:215], v[20:23]
	global_load_dwordx4 v[192:195], v96, s[86:87] nt
	v_mfma_f32_16x16x32_bf16 v[24:27], v[232:235], v[212:215], v[24:27]
	v_mfma_f32_16x16x32_bf16 v[28:31], v[236:239], v[212:215], v[28:31]
	s_waitcnt lgkmcnt(1)
	v_mfma_f32_16x16x32_bf16 v[32:35], v[224:227], v[216:219], v[32:35]
	v_mfma_f32_16x16x32_bf16 v[36:39], v[228:231], v[216:219], v[36:39]
	v_mfma_f32_16x16x32_bf16 v[40:43], v[232:235], v[216:219], v[40:43]
	v_mfma_f32_16x16x32_bf16 v[44:47], v[236:239], v[216:219], v[44:47]
	s_waitcnt lgkmcnt(0)
	v_mfma_f32_16x16x32_bf16 v[48:51], v[224:227], v[220:223], v[48:51]
	v_mfma_f32_16x16x32_bf16 v[52:55], v[228:231], v[220:223], v[52:55]
	v_mfma_f32_16x16x32_bf16 v[56:59], v[232:235], v[220:223], v[56:59]
	v_mfma_f32_16x16x32_bf16 v[60:63], v[236:239], v[220:223], v[60:63]
	s_waitcnt vmcnt(1)
	s_barrier
	ds_read_b128 v[176:179], v244 offset:0
	ds_read_b128 v[80:83], v246 offset:0
	ds_read_b128 v[84:87], v246 offset:2048
	ds_read_b128 v[88:91], v246 offset:4096
	ds_read_b128 v[92:95], v246 offset:6144
	ds_read_b128 v[180:183], v244 offset:2048
	ds_read_b128 v[184:187], v244 offset:4096
	ds_read_b128 v[188:191], v244 offset:6144
	s_waitcnt lgkmcnt(6)
	v_mfma_f32_16x16x32_bf16 v[0:3], v[80:83], v[176:179], v[0:3]
	ds_read_b128 v[208:211], v245 offset:0
	s_add_i32 m0, s81, 32768
	s_waitcnt lgkmcnt(6)
	v_mfma_f32_16x16x32_bf16 v[4:7], v[84:87], v[176:179], v[4:7]
	ds_read_b128 v[224:227], v247 offset:0
	global_load_lds_dwordx4 v240, s[76:77]
	s_waitcnt lgkmcnt(6)
	v_mfma_f32_16x16x32_bf16 v[8:11], v[88:91], v[176:179], v[8:11]
	ds_read_b128 v[228:231], v247 offset:2048
	s_add_i32 m0, s81, 36864
	s_waitcnt lgkmcnt(6)
	v_mfma_f32_16x16x32_bf16 v[12:15], v[92:95], v[176:179], v[12:15]
	ds_read_b128 v[232:235], v247 offset:4096
	global_load_lds_dwordx4 v241, s[76:77]
	s_waitcnt lgkmcnt(6)
	v_mfma_f32_16x16x32_bf16 v[16:19], v[80:83], v[180:183], v[16:19]
	ds_read_b128 v[236:239], v247 offset:6144
	s_add_i32 m0, s81, 40960
	v_mfma_f32_16x16x32_bf16 v[20:23], v[84:87], v[180:183], v[20:23]
	ds_read_b128 v[212:215], v245 offset:2048
	global_load_lds_dwordx4 v242, s[76:77]
	v_mfma_f32_16x16x32_bf16 v[24:27], v[88:91], v[180:183], v[24:27]
	ds_read_b128 v[216:219], v245 offset:4096
	s_add_i32 m0, s81, 45056
	v_mfma_f32_16x16x32_bf16 v[28:31], v[92:95], v[180:183], v[28:31]
	ds_read_b128 v[220:223], v245 offset:6144
	global_load_lds_dwordx4 v243, s[76:77]
	s_waitcnt lgkmcnt(9)
	v_mfma_f32_16x16x32_bf16 v[32:35], v[80:83], v[184:187], v[32:35]
	s_add_i32 m0, s81, 49152
	v_mfma_f32_16x16x32_bf16 v[36:39], v[84:87], v[184:187], v[36:39]
	global_load_lds_dwordx4 v240, s[78:79]
	v_mfma_f32_16x16x32_bf16 v[40:43], v[88:91], v[184:187], v[40:43]
	s_add_i32 m0, s81, 53248
	v_mfma_f32_16x16x32_bf16 v[44:47], v[92:95], v[184:187], v[44:47]
	global_load_lds_dwordx4 v241, s[78:79]
	s_waitcnt lgkmcnt(8)
	v_mfma_f32_16x16x32_bf16 v[48:51], v[80:83], v[188:191], v[48:51]
	s_add_i32 m0, s81, 57344
	v_mfma_f32_16x16x32_bf16 v[52:55], v[84:87], v[188:191], v[52:55]
	global_load_lds_dwordx4 v242, s[78:79]
	v_mfma_f32_16x16x32_bf16 v[56:59], v[88:91], v[188:191], v[56:59]
	s_add_i32 m0, s81, 61440
	v_mfma_f32_16x16x32_bf16 v[60:63], v[92:95], v[188:191], v[60:63]
	global_load_lds_dwordx4 v243, s[78:79]
	s_waitcnt lgkmcnt(6)
	v_mfma_f32_16x16x32_bf16 v[0:3], v[224:227], v[208:211], v[0:3]
	s_add_u32 s76, s76, 0x80
	s_addc_u32 s77, s77, 0
	s_waitcnt lgkmcnt(5)
	v_mfma_f32_16x16x32_bf16 v[4:7], v[228:231], v[208:211], v[4:7]
	s_waitcnt lgkmcnt(4)
	v_mfma_f32_16x16x32_bf16 v[8:11], v[232:235], v[208:211], v[8:11]
	s_add_u32 s78, s78, 0x80
	s_addc_u32 s79, s79, 0
	s_waitcnt lgkmcnt(3)
	v_mfma_f32_16x16x32_bf16 v[12:15], v[236:239], v[208:211], v[12:15]
	s_waitcnt lgkmcnt(2)
	v_mfma_f32_16x16x32_bf16 v[16:19], v[224:227], v[212:215], v[16:19]
	v_add_u32_e32 v96, 0x50000, v102
	v_mfma_f32_16x16x32_bf16 v[20:23], v[228:231], v[212:215], v[20:23]
	global_load_dwordx4 v[196:199], v96, s[86:87] offset:16 nt
	v_mfma_f32_16x16x32_bf16 v[24:27], v[232:235], v[212:215], v[24:27]
	v_mfma_f32_16x16x32_bf16 v[28:31], v[236:239], v[212:215], v[28:31]
	s_waitcnt lgkmcnt(1)
	v_mfma_f32_16x16x32_bf16 v[32:35], v[224:227], v[216:219], v[32:35]
	v_mfma_f32_16x16x32_bf16 v[36:39], v[228:231], v[216:219], v[36:39]
	v_mfma_f32_16x16x32_bf16 v[40:43], v[232:235], v[216:219], v[40:43]
	v_mfma_f32_16x16x32_bf16 v[44:47], v[236:239], v[216:219], v[44:47]
	s_waitcnt lgkmcnt(0)
	v_mfma_f32_16x16x32_bf16 v[48:51], v[224:227], v[220:223], v[48:51]
	v_mfma_f32_16x16x32_bf16 v[52:55], v[228:231], v[220:223], v[52:55]
	v_mfma_f32_16x16x32_bf16 v[56:59], v[232:235], v[220:223], v[56:59]
	v_mfma_f32_16x16x32_bf16 v[60:63], v[236:239], v[220:223], v[60:63]
	s_waitcnt vmcnt(1)
	s_barrier
	ds_read_b128 v[176:179], v244 offset:32768
	ds_read_b128 v[80:83], v246 offset:32768
	ds_read_b128 v[84:87], v246 offset:34816
	ds_read_b128 v[88:91], v246 offset:36864
	ds_read_b128 v[92:95], v246 offset:38912
	ds_read_b128 v[180:183], v244 offset:34816
	ds_read_b128 v[184:187], v244 offset:36864
	ds_read_b128 v[188:191], v244 offset:38912
	s_waitcnt lgkmcnt(6)
	v_mfma_f32_16x16x32_bf16 v[0:3], v[80:83], v[176:179], v[0:3]
	ds_read_b128 v[208:211], v245 offset:32768
	s_add_i32 m0, s81, 0
	s_waitcnt lgkmcnt(6)
	v_mfma_f32_16x16x32_bf16 v[4:7], v[84:87], v[176:179], v[4:7]
	ds_read_b128 v[224:227], v247 offset:32768
	global_load_lds_dwordx4 v240, s[76:77]
	s_waitcnt lgkmcnt(6)
	v_mfma_f32_16x16x32_bf16 v[8:11], v[88:91], v[176:179], v[8:11]
	ds_read_b128 v[228:231], v247 offset:34816
	s_add_i32 m0, s81, 4096
	s_waitcnt lgkmcnt(6)
	v_mfma_f32_16x16x32_bf16 v[12:15], v[92:95], v[176:179], v[12:15]
	ds_read_b128 v[232:235], v247 offset:36864
	global_load_lds_dwordx4 v241, s[76:77]
	s_waitcnt lgkmcnt(6)
	v_mfma_f32_16x16x32_bf16 v[16:19], v[80:83], v[180:183], v[16:19]
	ds_read_b128 v[236:239], v247 offset:38912
	s_add_i32 m0, s81, 8192
	v_mfma_f32_16x16x32_bf16 v[20:23], v[84:87], v[180:183], v[20:23]
	ds_read_b128 v[212:215], v245 offset:34816
	global_load_lds_dwordx4 v242, s[76:77]
	v_mfma_f32_16x16x32_bf16 v[24:27], v[88:91], v[180:183], v[24:27]
	ds_read_b128 v[216:219], v245 offset:36864
	s_add_i32 m0, s81, 12288
	v_mfma_f32_16x16x32_bf16 v[28:31], v[92:95], v[180:183], v[28:31]
	ds_read_b128 v[220:223], v245 offset:38912
	global_load_lds_dwordx4 v243, s[76:77]
	s_waitcnt lgkmcnt(9)
	v_mfma_f32_16x16x32_bf16 v[32:35], v[80:83], v[184:187], v[32:35]
	s_add_i32 m0, s81, 16384
	v_mfma_f32_16x16x32_bf16 v[36:39], v[84:87], v[184:187], v[36:39]
	global_load_lds_dwordx4 v240, s[78:79]
	v_mfma_f32_16x16x32_bf16 v[40:43], v[88:91], v[184:187], v[40:43]
	s_add_i32 m0, s81, 20480
	v_mfma_f32_16x16x32_bf16 v[44:47], v[92:95], v[184:187], v[44:47]
	global_load_lds_dwordx4 v241, s[78:79]
	s_waitcnt lgkmcnt(8)
	v_mfma_f32_16x16x32_bf16 v[48:51], v[80:83], v[188:191], v[48:51]
	s_add_i32 m0, s81, 24576
	v_mfma_f32_16x16x32_bf16 v[52:55], v[84:87], v[188:191], v[52:55]
	global_load_lds_dwordx4 v242, s[78:79]
	v_mfma_f32_16x16x32_bf16 v[56:59], v[88:91], v[188:191], v[56:59]
	s_add_i32 m0, s81, 28672
	v_mfma_f32_16x16x32_bf16 v[60:63], v[92:95], v[188:191], v[60:63]
	global_load_lds_dwordx4 v243, s[78:79]
	s_waitcnt lgkmcnt(6)
	v_mfma_f32_16x16x32_bf16 v[0:3], v[224:227], v[208:211], v[0:3]
	s_add_u32 s76, s76, 0x80
	s_addc_u32 s77, s77, 0
	s_waitcnt lgkmcnt(5)
	v_mfma_f32_16x16x32_bf16 v[4:7], v[228:231], v[208:211], v[4:7]
	s_waitcnt lgkmcnt(4)
	v_mfma_f32_16x16x32_bf16 v[8:11], v[232:235], v[208:211], v[8:11]
	s_add_u32 s78, s78, 0x80
	s_addc_u32 s79, s79, 0
	s_waitcnt lgkmcnt(3)
	v_mfma_f32_16x16x32_bf16 v[12:15], v[236:239], v[208:211], v[12:15]
	s_waitcnt lgkmcnt(2)
	v_mfma_f32_16x16x32_bf16 v[16:19], v[224:227], v[212:215], v[16:19]
	v_add_u32_e32 v96, 0x60000, v102
	v_mfma_f32_16x16x32_bf16 v[20:23], v[228:231], v[212:215], v[20:23]
	global_load_dwordx4 v[200:203], v96, s[86:87] nt
	v_mfma_f32_16x16x32_bf16 v[24:27], v[232:235], v[212:215], v[24:27]
	v_mfma_f32_16x16x32_bf16 v[28:31], v[236:239], v[212:215], v[28:31]
	s_waitcnt lgkmcnt(1)
	v_mfma_f32_16x16x32_bf16 v[32:35], v[224:227], v[216:219], v[32:35]
	v_mfma_f32_16x16x32_bf16 v[36:39], v[228:231], v[216:219], v[36:39]
	v_mfma_f32_16x16x32_bf16 v[40:43], v[232:235], v[216:219], v[40:43]
	v_mfma_f32_16x16x32_bf16 v[44:47], v[236:239], v[216:219], v[44:47]
	s_waitcnt lgkmcnt(0)
	v_mfma_f32_16x16x32_bf16 v[48:51], v[224:227], v[220:223], v[48:51]
	v_mfma_f32_16x16x32_bf16 v[52:55], v[228:231], v[220:223], v[52:55]
	v_mfma_f32_16x16x32_bf16 v[56:59], v[232:235], v[220:223], v[56:59]
	v_mfma_f32_16x16x32_bf16 v[60:63], v[236:239], v[220:223], v[60:63]
	s_waitcnt vmcnt(1)
	s_barrier
	ds_read_b128 v[176:179], v244 offset:0
	ds_read_b128 v[80:83], v246 offset:0
	ds_read_b128 v[84:87], v246 offset:2048
	ds_read_b128 v[88:91], v246 offset:4096
	ds_read_b128 v[92:95], v246 offset:6144
	ds_read_b128 v[180:183], v244 offset:2048
	ds_read_b128 v[184:187], v244 offset:4096
	ds_read_b128 v[188:191], v244 offset:6144
	s_waitcnt lgkmcnt(6)
	v_mfma_f32_16x16x32_bf16 v[0:3], v[80:83], v[176:179], v[0:3]
	ds_read_b128 v[208:211], v245 offset:0
	s_add_i32 m0, s81, 32768
	s_waitcnt lgkmcnt(6)
	v_mfma_f32_16x16x32_bf16 v[4:7], v[84:87], v[176:179], v[4:7]
	ds_read_b128 v[224:227], v247 offset:0
	global_load_lds_dwordx4 v240, s[76:77]
	s_waitcnt lgkmcnt(6)
	v_mfma_f32_16x16x32_bf16 v[8:11], v[88:91], v[176:179], v[8:11]
	ds_read_b128 v[228:231], v247 offset:2048
	s_add_i32 m0, s81, 36864
	s_waitcnt lgkmcnt(6)
	v_mfma_f32_16x16x32_bf16 v[12:15], v[92:95], v[176:179], v[12:15]
	ds_read_b128 v[232:235], v247 offset:4096
	global_load_lds_dwordx4 v241, s[76:77]
	s_waitcnt lgkmcnt(6)
	v_mfma_f32_16x16x32_bf16 v[16:19], v[80:83], v[180:183], v[16:19]
	ds_read_b128 v[236:239], v247 offset:6144
	s_add_i32 m0, s81, 40960
	v_mfma_f32_16x16x32_bf16 v[20:23], v[84:87], v[180:183], v[20:23]
	ds_read_b128 v[212:215], v245 offset:2048
	global_load_lds_dwordx4 v242, s[76:77]
	v_mfma_f32_16x16x32_bf16 v[24:27], v[88:91], v[180:183], v[24:27]
	ds_read_b128 v[216:219], v245 offset:4096
	s_add_i32 m0, s81, 45056
	v_mfma_f32_16x16x32_bf16 v[28:31], v[92:95], v[180:183], v[28:31]
	ds_read_b128 v[220:223], v245 offset:6144
	global_load_lds_dwordx4 v243, s[76:77]
	s_waitcnt lgkmcnt(9)
	v_mfma_f32_16x16x32_bf16 v[32:35], v[80:83], v[184:187], v[32:35]
	s_add_i32 m0, s81, 49152
	v_mfma_f32_16x16x32_bf16 v[36:39], v[84:87], v[184:187], v[36:39]
	global_load_lds_dwordx4 v240, s[78:79]
	v_mfma_f32_16x16x32_bf16 v[40:43], v[88:91], v[184:187], v[40:43]
	s_add_i32 m0, s81, 53248
	v_mfma_f32_16x16x32_bf16 v[44:47], v[92:95], v[184:187], v[44:47]
	global_load_lds_dwordx4 v241, s[78:79]
	s_waitcnt lgkmcnt(8)
	v_mfma_f32_16x16x32_bf16 v[48:51], v[80:83], v[188:191], v[48:51]
	s_add_i32 m0, s81, 57344
	v_mfma_f32_16x16x32_bf16 v[52:55], v[84:87], v[188:191], v[52:55]
	global_load_lds_dwordx4 v242, s[78:79]
	v_mfma_f32_16x16x32_bf16 v[56:59], v[88:91], v[188:191], v[56:59]
	s_add_i32 m0, s81, 61440
	v_mfma_f32_16x16x32_bf16 v[60:63], v[92:95], v[188:191], v[60:63]
	global_load_lds_dwordx4 v243, s[78:79]
	s_waitcnt lgkmcnt(6)
	v_mfma_f32_16x16x32_bf16 v[0:3], v[224:227], v[208:211], v[0:3]
	s_add_u32 s76, s76, 0x80
	s_addc_u32 s77, s77, 0
	s_waitcnt lgkmcnt(5)
	v_mfma_f32_16x16x32_bf16 v[4:7], v[228:231], v[208:211], v[4:7]
	s_waitcnt lgkmcnt(4)
	v_mfma_f32_16x16x32_bf16 v[8:11], v[232:235], v[208:211], v[8:11]
	s_add_u32 s78, s78, 0x80
	s_addc_u32 s79, s79, 0
	s_waitcnt lgkmcnt(3)
	v_mfma_f32_16x16x32_bf16 v[12:15], v[236:239], v[208:211], v[12:15]
	s_waitcnt lgkmcnt(2)
	v_mfma_f32_16x16x32_bf16 v[16:19], v[224:227], v[212:215], v[16:19]
	v_add_u32_e32 v96, 0x60000, v102
	v_mfma_f32_16x16x32_bf16 v[20:23], v[228:231], v[212:215], v[20:23]
	global_load_dwordx4 v[250:253], v96, s[86:87] offset:16 nt
	v_mfma_f32_16x16x32_bf16 v[24:27], v[232:235], v[212:215], v[24:27]
	v_mfma_f32_16x16x32_bf16 v[28:31], v[236:239], v[212:215], v[28:31]
	s_waitcnt lgkmcnt(1)
	v_mfma_f32_16x16x32_bf16 v[32:35], v[224:227], v[216:219], v[32:35]
	v_mfma_f32_16x16x32_bf16 v[36:39], v[228:231], v[216:219], v[36:39]
	v_mfma_f32_16x16x32_bf16 v[40:43], v[232:235], v[216:219], v[40:43]
	v_mfma_f32_16x16x32_bf16 v[44:47], v[236:239], v[216:219], v[44:47]
	s_waitcnt lgkmcnt(0)
	v_mfma_f32_16x16x32_bf16 v[48:51], v[224:227], v[220:223], v[48:51]
	v_mfma_f32_16x16x32_bf16 v[52:55], v[228:231], v[220:223], v[52:55]
	v_mfma_f32_16x16x32_bf16 v[56:59], v[232:235], v[220:223], v[56:59]
	v_mfma_f32_16x16x32_bf16 v[60:63], v[236:239], v[220:223], v[60:63]
	s_waitcnt vmcnt(1)
	s_barrier
	ds_read_b128 v[176:179], v244 offset:32768
	ds_read_b128 v[80:83], v246 offset:32768
	ds_read_b128 v[84:87], v246 offset:34816
	ds_read_b128 v[88:91], v246 offset:36864
	ds_read_b128 v[92:95], v246 offset:38912
	ds_read_b128 v[180:183], v244 offset:34816
	ds_read_b128 v[184:187], v244 offset:36864
	ds_read_b128 v[188:191], v244 offset:38912
	s_waitcnt lgkmcnt(6)
	v_mfma_f32_16x16x32_bf16 v[0:3], v[80:83], v[176:179], v[0:3]
	ds_read_b128 v[208:211], v245 offset:32768
	s_waitcnt lgkmcnt(6)
	v_mfma_f32_16x16x32_bf16 v[4:7], v[84:87], v[176:179], v[4:7]
	ds_read_b128 v[224:227], v247 offset:32768
	s_waitcnt lgkmcnt(6)
	v_mfma_f32_16x16x32_bf16 v[8:11], v[88:91], v[176:179], v[8:11]
	ds_read_b128 v[228:231], v247 offset:34816
	s_waitcnt lgkmcnt(6)
	v_mfma_f32_16x16x32_bf16 v[12:15], v[92:95], v[176:179], v[12:15]
	ds_read_b128 v[232:235], v247 offset:36864
	s_waitcnt lgkmcnt(6)
	v_mfma_f32_16x16x32_bf16 v[16:19], v[80:83], v[180:183], v[16:19]
	ds_read_b128 v[236:239], v247 offset:38912
	v_mfma_f32_16x16x32_bf16 v[20:23], v[84:87], v[180:183], v[20:23]
	ds_read_b128 v[212:215], v245 offset:34816
	v_mfma_f32_16x16x32_bf16 v[24:27], v[88:91], v[180:183], v[24:27]
	ds_read_b128 v[216:219], v245 offset:36864
	v_mfma_f32_16x16x32_bf16 v[28:31], v[92:95], v[180:183], v[28:31]
	ds_read_b128 v[220:223], v245 offset:38912
	s_waitcnt lgkmcnt(9)
	v_mfma_f32_16x16x32_bf16 v[32:35], v[80:83], v[184:187], v[32:35]
	v_mfma_f32_16x16x32_bf16 v[36:39], v[84:87], v[184:187], v[36:39]
	v_mfma_f32_16x16x32_bf16 v[40:43], v[88:91], v[184:187], v[40:43]
	v_mfma_f32_16x16x32_bf16 v[44:47], v[92:95], v[184:187], v[44:47]
	s_waitcnt lgkmcnt(8)
	v_mfma_f32_16x16x32_bf16 v[48:51], v[80:83], v[188:191], v[48:51]
	v_mfma_f32_16x16x32_bf16 v[52:55], v[84:87], v[188:191], v[52:55]
	v_mfma_f32_16x16x32_bf16 v[56:59], v[88:91], v[188:191], v[56:59]
	v_mfma_f32_16x16x32_bf16 v[60:63], v[92:95], v[188:191], v[60:63]
	s_waitcnt lgkmcnt(6)
	v_mfma_f32_16x16x32_bf16 v[0:3], v[224:227], v[208:211], v[0:3]
	s_waitcnt lgkmcnt(5)
	v_mfma_f32_16x16x32_bf16 v[4:7], v[228:231], v[208:211], v[4:7]
	s_waitcnt lgkmcnt(4)
	v_mfma_f32_16x16x32_bf16 v[8:11], v[232:235], v[208:211], v[8:11]
	s_waitcnt lgkmcnt(3)
	v_mfma_f32_16x16x32_bf16 v[12:15], v[236:239], v[208:211], v[12:15]
	s_waitcnt lgkmcnt(2)
	v_mfma_f32_16x16x32_bf16 v[16:19], v[224:227], v[212:215], v[16:19]
	v_mfma_f32_16x16x32_bf16 v[20:23], v[228:231], v[212:215], v[20:23]
	v_mfma_f32_16x16x32_bf16 v[24:27], v[232:235], v[212:215], v[24:27]
	v_mfma_f32_16x16x32_bf16 v[28:31], v[236:239], v[212:215], v[28:31]
	s_waitcnt lgkmcnt(1)
	v_mfma_f32_16x16x32_bf16 v[32:35], v[224:227], v[216:219], v[32:35]
	v_mfma_f32_16x16x32_bf16 v[36:39], v[228:231], v[216:219], v[36:39]
	v_mfma_f32_16x16x32_bf16 v[40:43], v[232:235], v[216:219], v[40:43]
	v_mfma_f32_16x16x32_bf16 v[44:47], v[236:239], v[216:219], v[44:47]
	s_waitcnt lgkmcnt(0)
	v_mfma_f32_16x16x32_bf16 v[48:51], v[224:227], v[220:223], v[48:51]
	v_mfma_f32_16x16x32_bf16 v[52:55], v[228:231], v[220:223], v[52:55]
	v_mfma_f32_16x16x32_bf16 v[56:59], v[232:235], v[220:223], v[56:59]
	v_mfma_f32_16x16x32_bf16 v[60:63], v[236:239], v[220:223], v[60:63]
	s_branch .Lot_stage
.Lot_main_l1:
	s_waitcnt vmcnt(0)
	s_barrier
	ds_read_b128 v[176:179], v244 offset:0
	ds_read_b128 v[80:83], v246 offset:0
	ds_read_b128 v[84:87], v246 offset:2048
	ds_read_b128 v[88:91], v246 offset:4096
	ds_read_b128 v[92:95], v246 offset:6144
	ds_read_b128 v[180:183], v244 offset:2048
	ds_read_b128 v[184:187], v244 offset:4096
	ds_read_b128 v[188:191], v244 offset:6144
	s_waitcnt lgkmcnt(6)
	v_mfma_f32_16x16x32_bf16 v[0:3], v[80:83], v[176:179], 0
	ds_read_b128 v[208:211], v245 offset:0
	s_add_i32 m0, s81, 32768
	s_waitcnt lgkmcnt(6)
	v_mfma_f32_16x16x32_bf16 v[4:7], v[84:87], v[176:179], 0
	ds_read_b128 v[224:227], v247 offset:0
	global_load_lds_dwordx4 v240, s[76:77]
	s_waitcnt lgkmcnt(6)
	v_mfma_f32_16x16x32_bf16 v[8:11], v[88:91], v[176:179], 0
	ds_read_b128 v[228:231], v247 offset:2048
	s_add_i32 m0, s81, 36864
	s_waitcnt lgkmcnt(6)
	v_mfma_f32_16x16x32_bf16 v[12:15], v[92:95], v[176:179], 0
	ds_read_b128 v[232:235], v247 offset:4096
	global_load_lds_dwordx4 v241, s[76:77]
	s_waitcnt lgkmcnt(6)
	v_mfma_f32_16x16x32_bf16 v[16:19], v[80:83], v[180:183], 0
	ds_read_b128 v[236:239], v247 offset:6144
	s_add_i32 m0, s81, 40960
	v_mfma_f32_16x16x32_bf16 v[20:23], v[84:87], v[180:183], 0
	ds_read_b128 v[212:215], v245 offset:2048
	global_load_lds_dwordx4 v242, s[76:77]
	v_mfma_f32_16x16x32_bf16 v[24:27], v[88:91], v[180:183], 0
	ds_read_b128 v[216:219], v245 offset:4096
	s_add_i32 m0, s81, 45056
	v_mfma_f32_16x16x32_bf16 v[28:31], v[92:95], v[180:183], 0
	ds_read_b128 v[220:223], v245 offset:6144
	global_load_lds_dwordx4 v243, s[76:77]
	s_waitcnt lgkmcnt(9)
	v_mfma_f32_16x16x32_bf16 v[32:35], v[80:83], v[184:187], 0
	s_add_i32 m0, s81, 49152
	v_mfma_f32_16x16x32_bf16 v[36:39], v[84:87], v[184:187], 0
	global_load_lds_dwordx4 v240, s[78:79]
	v_mfma_f32_16x16x32_bf16 v[40:43], v[88:91], v[184:187], 0
	s_add_i32 m0, s81, 53248
	v_mfma_f32_16x16x32_bf16 v[44:47], v[92:95], v[184:187], 0
	global_load_lds_dwordx4 v241, s[78:79]
	s_waitcnt lgkmcnt(8)
	v_mfma_f32_16x16x32_bf16 v[48:51], v[80:83], v[188:191], 0
	s_add_i32 m0, s81, 57344
	v_mfma_f32_16x16x32_bf16 v[52:55], v[84:87], v[188:191], 0
	global_load_lds_dwordx4 v242, s[78:79]
	v_mfma_f32_16x16x32_bf16 v[56:59], v[88:91], v[188:191], 0
	s_add_i32 m0, s81, 61440
	v_mfma_f32_16x16x32_bf16 v[60:63], v[92:95], v[188:191], 0
	global_load_lds_dwordx4 v243, s[78:79]
	s_waitcnt lgkmcnt(6)
	v_mfma_f32_16x16x32_bf16 v[0:3], v[224:227], v[208:211], v[0:3]
	s_add_u32 s76, s76, 0x80
	s_addc_u32 s77, s77, 0
	s_waitcnt lgkmcnt(5)
	v_mfma_f32_16x16x32_bf16 v[4:7], v[228:231], v[208:211], v[4:7]
	s_waitcnt lgkmcnt(4)
	v_mfma_f32_16x16x32_bf16 v[8:11], v[232:235], v[208:211], v[8:11]
	s_add_u32 s78, s78, 0x80
	s_addc_u32 s79, s79, 0
	s_waitcnt lgkmcnt(3)
	v_mfma_f32_16x16x32_bf16 v[12:15], v[236:239], v[208:211], v[12:15]
	s_waitcnt lgkmcnt(2)
	v_mfma_f32_16x16x32_bf16 v[16:19], v[224:227], v[212:215], v[16:19]
	v_mfma_f32_16x16x32_bf16 v[20:23], v[228:231], v[212:215], v[20:23]
	v_mfma_f32_16x16x32_bf16 v[24:27], v[232:235], v[212:215], v[24:27]
	v_mfma_f32_16x16x32_bf16 v[28:31], v[236:239], v[212:215], v[28:31]
	s_waitcnt lgkmcnt(1)
	v_mfma_f32_16x16x32_bf16 v[32:35], v[224:227], v[216:219], v[32:35]
	v_mfma_f32_16x16x32_bf16 v[36:39], v[228:231], v[216:219], v[36:39]
	v_mfma_f32_16x16x32_bf16 v[40:43], v[232:235], v[216:219], v[40:43]
	v_mfma_f32_16x16x32_bf16 v[44:47], v[236:239], v[216:219], v[44:47]
	s_waitcnt lgkmcnt(0)
	v_mfma_f32_16x16x32_bf16 v[48:51], v[224:227], v[220:223], v[48:51]
	v_mfma_f32_16x16x32_bf16 v[52:55], v[228:231], v[220:223], v[52:55]
	v_mfma_f32_16x16x32_bf16 v[56:59], v[232:235], v[220:223], v[56:59]
	v_mfma_f32_16x16x32_bf16 v[60:63], v[236:239], v[220:223], v[60:63]
	s_waitcnt vmcnt(0)
	s_barrier
	ds_read_b128 v[176:179], v244 offset:32768
	ds_read_b128 v[80:83], v246 offset:32768
	ds_read_b128 v[84:87], v246 offset:34816
	ds_read_b128 v[88:91], v246 offset:36864
	ds_read_b128 v[92:95], v246 offset:38912
	ds_read_b128 v[180:183], v244 offset:34816
	ds_read_b128 v[184:187], v244 offset:36864
	ds_read_b128 v[188:191], v244 offset:38912
	s_waitcnt lgkmcnt(6)
	v_mfma_f32_16x16x32_bf16 v[0:3], v[80:83], v[176:179], v[0:3]
	ds_read_b128 v[208:211], v245 offset:32768
	s_add_i32 m0, s81, 0
	s_waitcnt lgkmcnt(6)
	v_mfma_f32_16x16x32_bf16 v[4:7], v[84:87], v[176:179], v[4:7]
	ds_read_b128 v[224:227], v247 offset:32768
	global_load_lds_dwordx4 v240, s[76:77]
	s_waitcnt lgkmcnt(6)
	v_mfma_f32_16x16x32_bf16 v[8:11], v[88:91], v[176:179], v[8:11]
	ds_read_b128 v[228:231], v247 offset:34816
	s_add_i32 m0, s81, 4096
	s_waitcnt lgkmcnt(6)
	v_mfma_f32_16x16x32_bf16 v[12:15], v[92:95], v[176:179], v[12:15]
	ds_read_b128 v[232:235], v247 offset:36864
	global_load_lds_dwordx4 v241, s[76:77]
	s_waitcnt lgkmcnt(6)
	v_mfma_f32_16x16x32_bf16 v[16:19], v[80:83], v[180:183], v[16:19]
	ds_read_b128 v[236:239], v247 offset:38912
	s_add_i32 m0, s81, 8192
	v_mfma_f32_16x16x32_bf16 v[20:23], v[84:87], v[180:183], v[20:23]
	ds_read_b128 v[212:215], v245 offset:34816
	global_load_lds_dwordx4 v242, s[76:77]
	v_mfma_f32_16x16x32_bf16 v[24:27], v[88:91], v[180:183], v[24:27]
	ds_read_b128 v[216:219], v245 offset:36864
	s_add_i32 m0, s81, 12288
	v_mfma_f32_16x16x32_bf16 v[28:31], v[92:95], v[180:183], v[28:31]
	ds_read_b128 v[220:223], v245 offset:38912
	global_load_lds_dwordx4 v243, s[76:77]
	s_waitcnt lgkmcnt(9)
	v_mfma_f32_16x16x32_bf16 v[32:35], v[80:83], v[184:187], v[32:35]
	s_add_i32 m0, s81, 16384
	v_mfma_f32_16x16x32_bf16 v[36:39], v[84:87], v[184:187], v[36:39]
	global_load_lds_dwordx4 v240, s[78:79]
	v_mfma_f32_16x16x32_bf16 v[40:43], v[88:91], v[184:187], v[40:43]
	s_add_i32 m0, s81, 20480
	v_mfma_f32_16x16x32_bf16 v[44:47], v[92:95], v[184:187], v[44:47]
	global_load_lds_dwordx4 v241, s[78:79]
	s_waitcnt lgkmcnt(8)
	v_mfma_f32_16x16x32_bf16 v[48:51], v[80:83], v[188:191], v[48:51]
	s_add_i32 m0, s81, 24576
	v_mfma_f32_16x16x32_bf16 v[52:55], v[84:87], v[188:191], v[52:55]
	global_load_lds_dwordx4 v242, s[78:79]
	v_mfma_f32_16x16x32_bf16 v[56:59], v[88:91], v[188:191], v[56:59]
	s_add_i32 m0, s81, 28672
	v_mfma_f32_16x16x32_bf16 v[60:63], v[92:95], v[188:191], v[60:63]
	global_load_lds_dwordx4 v243, s[78:79]
	s_waitcnt lgkmcnt(6)
	v_mfma_f32_16x16x32_bf16 v[0:3], v[224:227], v[208:211], v[0:3]
	s_add_u32 s76, s76, 0x80
	s_addc_u32 s77, s77, 0
	s_waitcnt lgkmcnt(5)
	v_mfma_f32_16x16x32_bf16 v[4:7], v[228:231], v[208:211], v[4:7]
	s_waitcnt lgkmcnt(4)
	v_mfma_f32_16x16x32_bf16 v[8:11], v[232:235], v[208:211], v[8:11]
	s_add_u32 s78, s78, 0x80
	s_addc_u32 s79, s79, 0
	s_waitcnt lgkmcnt(3)
	v_mfma_f32_16x16x32_bf16 v[12:15], v[236:239], v[208:211], v[12:15]
	s_waitcnt lgkmcnt(2)
	v_mfma_f32_16x16x32_bf16 v[16:19], v[224:227], v[212:215], v[16:19]
	v_mfma_f32_16x16x32_bf16 v[20:23], v[228:231], v[212:215], v[20:23]
	v_mfma_f32_16x16x32_bf16 v[24:27], v[232:235], v[212:215], v[24:27]
	v_mfma_f32_16x16x32_bf16 v[28:31], v[236:239], v[212:215], v[28:31]
	s_waitcnt lgkmcnt(1)
	v_mfma_f32_16x16x32_bf16 v[32:35], v[224:227], v[216:219], v[32:35]
	v_mfma_f32_16x16x32_bf16 v[36:39], v[228:231], v[216:219], v[36:39]
	v_mfma_f32_16x16x32_bf16 v[40:43], v[232:235], v[216:219], v[40:43]
	v_mfma_f32_16x16x32_bf16 v[44:47], v[236:239], v[216:219], v[44:47]
	s_waitcnt lgkmcnt(0)
	v_mfma_f32_16x16x32_bf16 v[48:51], v[224:227], v[220:223], v[48:51]
	v_mfma_f32_16x16x32_bf16 v[52:55], v[228:231], v[220:223], v[52:55]
	v_mfma_f32_16x16x32_bf16 v[56:59], v[232:235], v[220:223], v[56:59]
	v_mfma_f32_16x16x32_bf16 v[60:63], v[236:239], v[220:223], v[60:63]
	s_waitcnt vmcnt(0)
	s_barrier
	ds_read_b128 v[176:179], v244 offset:0
	ds_read_b128 v[80:83], v246 offset:0
	ds_read_b128 v[84:87], v246 offset:2048
	ds_read_b128 v[88:91], v246 offset:4096
	ds_read_b128 v[92:95], v246 offset:6144
	ds_read_b128 v[180:183], v244 offset:2048
	ds_read_b128 v[184:187], v244 offset:4096
	ds_read_b128 v[188:191], v244 offset:6144
	s_waitcnt lgkmcnt(6)
	v_mfma_f32_16x16x32_bf16 v[0:3], v[80:83], v[176:179], v[0:3]
	ds_read_b128 v[208:211], v245 offset:0
	s_add_i32 m0, s81, 32768
	s_waitcnt lgkmcnt(6)
	v_mfma_f32_16x16x32_bf16 v[4:7], v[84:87], v[176:179], v[4:7]
	ds_read_b128 v[224:227], v247 offset:0
	global_load_lds_dwordx4 v240, s[76:77]
	s_waitcnt lgkmcnt(6)
	v_mfma_f32_16x16x32_bf16 v[8:11], v[88:91], v[176:179], v[8:11]
	ds_read_b128 v[228:231], v247 offset:2048
	s_add_i32 m0, s81, 36864
	s_waitcnt lgkmcnt(6)
	v_mfma_f32_16x16x32_bf16 v[12:15], v[92:95], v[176:179], v[12:15]
	ds_read_b128 v[232:235], v247 offset:4096
	global_load_lds_dwordx4 v241, s[76:77]
	s_waitcnt lgkmcnt(6)
	v_mfma_f32_16x16x32_bf16 v[16:19], v[80:83], v[180:183], v[16:19]
	ds_read_b128 v[236:239], v247 offset:6144
	s_add_i32 m0, s81, 40960
	v_mfma_f32_16x16x32_bf16 v[20:23], v[84:87], v[180:183], v[20:23]
	ds_read_b128 v[212:215], v245 offset:2048
	global_load_lds_dwordx4 v242, s[76:77]
	v_mfma_f32_16x16x32_bf16 v[24:27], v[88:91], v[180:183], v[24:27]
	ds_read_b128 v[216:219], v245 offset:4096
	s_add_i32 m0, s81, 45056
	v_mfma_f32_16x16x32_bf16 v[28:31], v[92:95], v[180:183], v[28:31]
	ds_read_b128 v[220:223], v245 offset:6144
	global_load_lds_dwordx4 v243, s[76:77]
	s_waitcnt lgkmcnt(9)
	v_mfma_f32_16x16x32_bf16 v[32:35], v[80:83], v[184:187], v[32:35]
	s_add_i32 m0, s81, 49152
	v_mfma_f32_16x16x32_bf16 v[36:39], v[84:87], v[184:187], v[36:39]
	global_load_lds_dwordx4 v240, s[78:79]
	v_mfma_f32_16x16x32_bf16 v[40:43], v[88:91], v[184:187], v[40:43]
	s_add_i32 m0, s81, 53248
	v_mfma_f32_16x16x32_bf16 v[44:47], v[92:95], v[184:187], v[44:47]
	global_load_lds_dwordx4 v241, s[78:79]
	s_waitcnt lgkmcnt(8)
	v_mfma_f32_16x16x32_bf16 v[48:51], v[80:83], v[188:191], v[48:51]
	s_add_i32 m0, s81, 57344
	v_mfma_f32_16x16x32_bf16 v[52:55], v[84:87], v[188:191], v[52:55]
	global_load_lds_dwordx4 v242, s[78:79]
	v_mfma_f32_16x16x32_bf16 v[56:59], v[88:91], v[188:191], v[56:59]
	s_add_i32 m0, s81, 61440
	v_mfma_f32_16x16x32_bf16 v[60:63], v[92:95], v[188:191], v[60:63]
	global_load_lds_dwordx4 v243, s[78:79]
	s_waitcnt lgkmcnt(6)
	v_mfma_f32_16x16x32_bf16 v[0:3], v[224:227], v[208:211], v[0:3]
	s_add_u32 s76, s76, 0x80
	s_addc_u32 s77, s77, 0
	s_waitcnt lgkmcnt(5)
	v_mfma_f32_16x16x32_bf16 v[4:7], v[228:231], v[208:211], v[4:7]
	s_waitcnt lgkmcnt(4)
	v_mfma_f32_16x16x32_bf16 v[8:11], v[232:235], v[208:211], v[8:11]
	s_add_u32 s78, s78, 0x80
	s_addc_u32 s79, s79, 0
	s_waitcnt lgkmcnt(3)
	v_mfma_f32_16x16x32_bf16 v[12:15], v[236:239], v[208:211], v[12:15]
	s_waitcnt lgkmcnt(2)
	v_mfma_f32_16x16x32_bf16 v[16:19], v[224:227], v[212:215], v[16:19]
	v_mfma_f32_16x16x32_bf16 v[20:23], v[228:231], v[212:215], v[20:23]
	v_mfma_f32_16x16x32_bf16 v[24:27], v[232:235], v[212:215], v[24:27]
	v_mfma_f32_16x16x32_bf16 v[28:31], v[236:239], v[212:215], v[28:31]
	s_waitcnt lgkmcnt(1)
	v_mfma_f32_16x16x32_bf16 v[32:35], v[224:227], v[216:219], v[32:35]
	v_mfma_f32_16x16x32_bf16 v[36:39], v[228:231], v[216:219], v[36:39]
	v_mfma_f32_16x16x32_bf16 v[40:43], v[232:235], v[216:219], v[40:43]
	v_mfma_f32_16x16x32_bf16 v[44:47], v[236:239], v[216:219], v[44:47]
	s_waitcnt lgkmcnt(0)
	v_mfma_f32_16x16x32_bf16 v[48:51], v[224:227], v[220:223], v[48:51]
	v_mfma_f32_16x16x32_bf16 v[52:55], v[228:231], v[220:223], v[52:55]
	v_mfma_f32_16x16x32_bf16 v[56:59], v[232:235], v[220:223], v[56:59]
	v_mfma_f32_16x16x32_bf16 v[60:63], v[236:239], v[220:223], v[60:63]
	s_waitcnt vmcnt(0)
	s_barrier
	ds_read_b128 v[176:179], v244 offset:32768
	ds_read_b128 v[80:83], v246 offset:32768
	ds_read_b128 v[84:87], v246 offset:34816
	ds_read_b128 v[88:91], v246 offset:36864
	ds_read_b128 v[92:95], v246 offset:38912
	ds_read_b128 v[180:183], v244 offset:34816
	ds_read_b128 v[184:187], v244 offset:36864
	ds_read_b128 v[188:191], v244 offset:38912
	s_waitcnt lgkmcnt(6)
	v_mfma_f32_16x16x32_bf16 v[0:3], v[80:83], v[176:179], v[0:3]
	ds_read_b128 v[208:211], v245 offset:32768
	s_add_i32 m0, s81, 0
	s_waitcnt lgkmcnt(6)
	v_mfma_f32_16x16x32_bf16 v[4:7], v[84:87], v[176:179], v[4:7]
	ds_read_b128 v[224:227], v247 offset:32768
	global_load_lds_dwordx4 v240, s[76:77]
	s_waitcnt lgkmcnt(6)
	v_mfma_f32_16x16x32_bf16 v[8:11], v[88:91], v[176:179], v[8:11]
	ds_read_b128 v[228:231], v247 offset:34816
	s_add_i32 m0, s81, 4096
	s_waitcnt lgkmcnt(6)
	v_mfma_f32_16x16x32_bf16 v[12:15], v[92:95], v[176:179], v[12:15]
	ds_read_b128 v[232:235], v247 offset:36864
	global_load_lds_dwordx4 v241, s[76:77]
	s_waitcnt lgkmcnt(6)
	v_mfma_f32_16x16x32_bf16 v[16:19], v[80:83], v[180:183], v[16:19]
	ds_read_b128 v[236:239], v247 offset:38912
	s_add_i32 m0, s81, 8192
	v_mfma_f32_16x16x32_bf16 v[20:23], v[84:87], v[180:183], v[20:23]
	ds_read_b128 v[212:215], v245 offset:34816
	global_load_lds_dwordx4 v242, s[76:77]
	v_mfma_f32_16x16x32_bf16 v[24:27], v[88:91], v[180:183], v[24:27]
	ds_read_b128 v[216:219], v245 offset:36864
	s_add_i32 m0, s81, 12288
	v_mfma_f32_16x16x32_bf16 v[28:31], v[92:95], v[180:183], v[28:31]
	ds_read_b128 v[220:223], v245 offset:38912
	global_load_lds_dwordx4 v243, s[76:77]
	s_waitcnt lgkmcnt(9)
	v_mfma_f32_16x16x32_bf16 v[32:35], v[80:83], v[184:187], v[32:35]
	s_add_i32 m0, s81, 16384
	v_mfma_f32_16x16x32_bf16 v[36:39], v[84:87], v[184:187], v[36:39]
	global_load_lds_dwordx4 v240, s[78:79]
	v_mfma_f32_16x16x32_bf16 v[40:43], v[88:91], v[184:187], v[40:43]
	s_add_i32 m0, s81, 20480
	v_mfma_f32_16x16x32_bf16 v[44:47], v[92:95], v[184:187], v[44:47]
	global_load_lds_dwordx4 v241, s[78:79]
	s_waitcnt lgkmcnt(8)
	v_mfma_f32_16x16x32_bf16 v[48:51], v[80:83], v[188:191], v[48:51]
	s_add_i32 m0, s81, 24576
	v_mfma_f32_16x16x32_bf16 v[52:55], v[84:87], v[188:191], v[52:55]
	global_load_lds_dwordx4 v242, s[78:79]
	v_mfma_f32_16x16x32_bf16 v[56:59], v[88:91], v[188:191], v[56:59]
	s_add_i32 m0, s81, 28672
	v_mfma_f32_16x16x32_bf16 v[60:63], v[92:95], v[188:191], v[60:63]
	global_load_lds_dwordx4 v243, s[78:79]
	s_waitcnt lgkmcnt(6)
	v_mfma_f32_16x16x32_bf16 v[0:3], v[224:227], v[208:211], v[0:3]
	s_add_u32 s76, s76, 0x80
	s_addc_u32 s77, s77, 0
	s_waitcnt lgkmcnt(5)
	v_mfma_f32_16x16x32_bf16 v[4:7], v[228:231], v[208:211], v[4:7]
	s_waitcnt lgkmcnt(4)
	v_mfma_f32_16x16x32_bf16 v[8:11], v[232:235], v[208:211], v[8:11]
	s_add_u32 s78, s78, 0x80
	s_addc_u32 s79, s79, 0
	s_waitcnt lgkmcnt(3)
	v_mfma_f32_16x16x32_bf16 v[12:15], v[236:239], v[208:211], v[12:15]
	s_waitcnt lgkmcnt(2)
	v_mfma_f32_16x16x32_bf16 v[16:19], v[224:227], v[212:215], v[16:19]
	v_mfma_f32_16x16x32_bf16 v[20:23], v[228:231], v[212:215], v[20:23]
	v_mfma_f32_16x16x32_bf16 v[24:27], v[232:235], v[212:215], v[24:27]
	v_mfma_f32_16x16x32_bf16 v[28:31], v[236:239], v[212:215], v[28:31]
	s_waitcnt lgkmcnt(1)
	v_mfma_f32_16x16x32_bf16 v[32:35], v[224:227], v[216:219], v[32:35]
	v_mfma_f32_16x16x32_bf16 v[36:39], v[228:231], v[216:219], v[36:39]
	v_mfma_f32_16x16x32_bf16 v[40:43], v[232:235], v[216:219], v[40:43]
	v_mfma_f32_16x16x32_bf16 v[44:47], v[236:239], v[216:219], v[44:47]
	s_waitcnt lgkmcnt(0)
	v_mfma_f32_16x16x32_bf16 v[48:51], v[224:227], v[220:223], v[48:51]
	v_mfma_f32_16x16x32_bf16 v[52:55], v[228:231], v[220:223], v[52:55]
	v_mfma_f32_16x16x32_bf16 v[56:59], v[232:235], v[220:223], v[56:59]
	v_mfma_f32_16x16x32_bf16 v[60:63], v[236:239], v[220:223], v[60:63]
	s_waitcnt vmcnt(0)
	s_barrier
	ds_read_b128 v[176:179], v244 offset:0
	ds_read_b128 v[80:83], v246 offset:0
	ds_read_b128 v[84:87], v246 offset:2048
	ds_read_b128 v[88:91], v246 offset:4096
	ds_read_b128 v[92:95], v246 offset:6144
	ds_read_b128 v[180:183], v244 offset:2048
	ds_read_b128 v[184:187], v244 offset:4096
	ds_read_b128 v[188:191], v244 offset:6144
	s_waitcnt lgkmcnt(6)
	v_mfma_f32_16x16x32_bf16 v[0:3], v[80:83], v[176:179], v[0:3]
	ds_read_b128 v[208:211], v245 offset:0
	s_add_i32 m0, s81, 32768
	s_waitcnt lgkmcnt(6)
	v_mfma_f32_16x16x32_bf16 v[4:7], v[84:87], v[176:179], v[4:7]
	ds_read_b128 v[224:227], v247 offset:0
	global_load_lds_dwordx4 v240, s[76:77]
	s_waitcnt lgkmcnt(6)
	v_mfma_f32_16x16x32_bf16 v[8:11], v[88:91], v[176:179], v[8:11]
	ds_read_b128 v[228:231], v247 offset:2048
	s_add_i32 m0, s81, 36864
	s_waitcnt lgkmcnt(6)
	v_mfma_f32_16x16x32_bf16 v[12:15], v[92:95], v[176:179], v[12:15]
	ds_read_b128 v[232:235], v247 offset:4096
	global_load_lds_dwordx4 v241, s[76:77]
	s_waitcnt lgkmcnt(6)
	v_mfma_f32_16x16x32_bf16 v[16:19], v[80:83], v[180:183], v[16:19]
	ds_read_b128 v[236:239], v247 offset:6144
	s_add_i32 m0, s81, 40960
	v_mfma_f32_16x16x32_bf16 v[20:23], v[84:87], v[180:183], v[20:23]
	ds_read_b128 v[212:215], v245 offset:2048
	global_load_lds_dwordx4 v242, s[76:77]
	v_mfma_f32_16x16x32_bf16 v[24:27], v[88:91], v[180:183], v[24:27]
	ds_read_b128 v[216:219], v245 offset:4096
	s_add_i32 m0, s81, 45056
	v_mfma_f32_16x16x32_bf16 v[28:31], v[92:95], v[180:183], v[28:31]
	ds_read_b128 v[220:223], v245 offset:6144
	global_load_lds_dwordx4 v243, s[76:77]
	s_waitcnt lgkmcnt(9)
	v_mfma_f32_16x16x32_bf16 v[32:35], v[80:83], v[184:187], v[32:35]
	s_add_i32 m0, s81, 49152
	v_mfma_f32_16x16x32_bf16 v[36:39], v[84:87], v[184:187], v[36:39]
	global_load_lds_dwordx4 v240, s[78:79]
	v_mfma_f32_16x16x32_bf16 v[40:43], v[88:91], v[184:187], v[40:43]
	s_add_i32 m0, s81, 53248
	v_mfma_f32_16x16x32_bf16 v[44:47], v[92:95], v[184:187], v[44:47]
	global_load_lds_dwordx4 v241, s[78:79]
	s_waitcnt lgkmcnt(8)
	v_mfma_f32_16x16x32_bf16 v[48:51], v[80:83], v[188:191], v[48:51]
	s_add_i32 m0, s81, 57344
	v_mfma_f32_16x16x32_bf16 v[52:55], v[84:87], v[188:191], v[52:55]
	global_load_lds_dwordx4 v242, s[78:79]
	v_mfma_f32_16x16x32_bf16 v[56:59], v[88:91], v[188:191], v[56:59]
	s_add_i32 m0, s81, 61440
	v_mfma_f32_16x16x32_bf16 v[60:63], v[92:95], v[188:191], v[60:63]
	global_load_lds_dwordx4 v243, s[78:79]
	s_waitcnt lgkmcnt(6)
	v_mfma_f32_16x16x32_bf16 v[0:3], v[224:227], v[208:211], v[0:3]
	s_add_u32 s76, s76, 0x80
	s_addc_u32 s77, s77, 0
	s_waitcnt lgkmcnt(5)
	v_mfma_f32_16x16x32_bf16 v[4:7], v[228:231], v[208:211], v[4:7]
	s_waitcnt lgkmcnt(4)
	v_mfma_f32_16x16x32_bf16 v[8:11], v[232:235], v[208:211], v[8:11]
	s_add_u32 s78, s78, 0x80
	s_addc_u32 s79, s79, 0
	s_waitcnt lgkmcnt(3)
	v_mfma_f32_16x16x32_bf16 v[12:15], v[236:239], v[208:211], v[12:15]
	s_waitcnt lgkmcnt(2)
	v_mfma_f32_16x16x32_bf16 v[16:19], v[224:227], v[212:215], v[16:19]
	v_mfma_f32_16x16x32_bf16 v[20:23], v[228:231], v[212:215], v[20:23]
	v_mfma_f32_16x16x32_bf16 v[24:27], v[232:235], v[212:215], v[24:27]
	v_mfma_f32_16x16x32_bf16 v[28:31], v[236:239], v[212:215], v[28:31]
	s_waitcnt lgkmcnt(1)
	v_mfma_f32_16x16x32_bf16 v[32:35], v[224:227], v[216:219], v[32:35]
	v_mfma_f32_16x16x32_bf16 v[36:39], v[228:231], v[216:219], v[36:39]
	v_mfma_f32_16x16x32_bf16 v[40:43], v[232:235], v[216:219], v[40:43]
	v_mfma_f32_16x16x32_bf16 v[44:47], v[236:239], v[216:219], v[44:47]
	s_waitcnt lgkmcnt(0)
	v_mfma_f32_16x16x32_bf16 v[48:51], v[224:227], v[220:223], v[48:51]
	v_mfma_f32_16x16x32_bf16 v[52:55], v[228:231], v[220:223], v[52:55]
	v_mfma_f32_16x16x32_bf16 v[56:59], v[232:235], v[220:223], v[56:59]
	v_mfma_f32_16x16x32_bf16 v[60:63], v[236:239], v[220:223], v[60:63]
	s_waitcnt vmcnt(0)
	s_barrier
	ds_read_b128 v[176:179], v244 offset:32768
	ds_read_b128 v[80:83], v246 offset:32768
	ds_read_b128 v[84:87], v246 offset:34816
	ds_read_b128 v[88:91], v246 offset:36864
	ds_read_b128 v[92:95], v246 offset:38912
	ds_read_b128 v[180:183], v244 offset:34816
	ds_read_b128 v[184:187], v244 offset:36864
	ds_read_b128 v[188:191], v244 offset:38912
	s_waitcnt lgkmcnt(6)
	v_mfma_f32_16x16x32_bf16 v[0:3], v[80:83], v[176:179], v[0:3]
	ds_read_b128 v[208:211], v245 offset:32768
	s_add_i32 m0, s81, 0
	s_waitcnt lgkmcnt(6)
	v_mfma_f32_16x16x32_bf16 v[4:7], v[84:87], v[176:179], v[4:7]
	ds_read_b128 v[224:227], v247 offset:32768
	global_load_lds_dwordx4 v240, s[76:77]
	s_waitcnt lgkmcnt(6)
	v_mfma_f32_16x16x32_bf16 v[8:11], v[88:91], v[176:179], v[8:11]
	ds_read_b128 v[228:231], v247 offset:34816
	s_add_i32 m0, s81, 4096
	s_waitcnt lgkmcnt(6)
	v_mfma_f32_16x16x32_bf16 v[12:15], v[92:95], v[176:179], v[12:15]
	ds_read_b128 v[232:235], v247 offset:36864
	global_load_lds_dwordx4 v241, s[76:77]
	s_waitcnt lgkmcnt(6)
	v_mfma_f32_16x16x32_bf16 v[16:19], v[80:83], v[180:183], v[16:19]
	ds_read_b128 v[236:239], v247 offset:38912
	s_add_i32 m0, s81, 8192
	v_mfma_f32_16x16x32_bf16 v[20:23], v[84:87], v[180:183], v[20:23]
	ds_read_b128 v[212:215], v245 offset:34816
	global_load_lds_dwordx4 v242, s[76:77]
	v_mfma_f32_16x16x32_bf16 v[24:27], v[88:91], v[180:183], v[24:27]
	ds_read_b128 v[216:219], v245 offset:36864
	s_add_i32 m0, s81, 12288
	v_mfma_f32_16x16x32_bf16 v[28:31], v[92:95], v[180:183], v[28:31]
	ds_read_b128 v[220:223], v245 offset:38912
	global_load_lds_dwordx4 v243, s[76:77]
	s_waitcnt lgkmcnt(9)
	v_mfma_f32_16x16x32_bf16 v[32:35], v[80:83], v[184:187], v[32:35]
	s_add_i32 m0, s81, 16384
	v_mfma_f32_16x16x32_bf16 v[36:39], v[84:87], v[184:187], v[36:39]
	global_load_lds_dwordx4 v240, s[78:79]
	v_mfma_f32_16x16x32_bf16 v[40:43], v[88:91], v[184:187], v[40:43]
	s_add_i32 m0, s81, 20480
	v_mfma_f32_16x16x32_bf16 v[44:47], v[92:95], v[184:187], v[44:47]
	global_load_lds_dwordx4 v241, s[78:79]
	s_waitcnt lgkmcnt(8)
	v_mfma_f32_16x16x32_bf16 v[48:51], v[80:83], v[188:191], v[48:51]
	s_add_i32 m0, s81, 24576
	v_mfma_f32_16x16x32_bf16 v[52:55], v[84:87], v[188:191], v[52:55]
	global_load_lds_dwordx4 v242, s[78:79]
	v_mfma_f32_16x16x32_bf16 v[56:59], v[88:91], v[188:191], v[56:59]
	s_add_i32 m0, s81, 28672
	v_mfma_f32_16x16x32_bf16 v[60:63], v[92:95], v[188:191], v[60:63]
	global_load_lds_dwordx4 v243, s[78:79]
	s_waitcnt lgkmcnt(6)
	v_mfma_f32_16x16x32_bf16 v[0:3], v[224:227], v[208:211], v[0:3]
	s_add_u32 s76, s76, 0x80
	s_addc_u32 s77, s77, 0
	s_waitcnt lgkmcnt(5)
	v_mfma_f32_16x16x32_bf16 v[4:7], v[228:231], v[208:211], v[4:7]
	s_waitcnt lgkmcnt(4)
	v_mfma_f32_16x16x32_bf16 v[8:11], v[232:235], v[208:211], v[8:11]
	s_add_u32 s78, s78, 0x80
	s_addc_u32 s79, s79, 0
	s_waitcnt lgkmcnt(3)
	v_mfma_f32_16x16x32_bf16 v[12:15], v[236:239], v[208:211], v[12:15]
	s_waitcnt lgkmcnt(2)
	v_mfma_f32_16x16x32_bf16 v[16:19], v[224:227], v[212:215], v[16:19]
	v_mfma_f32_16x16x32_bf16 v[20:23], v[228:231], v[212:215], v[20:23]
	v_mfma_f32_16x16x32_bf16 v[24:27], v[232:235], v[212:215], v[24:27]
	v_mfma_f32_16x16x32_bf16 v[28:31], v[236:239], v[212:215], v[28:31]
	s_waitcnt lgkmcnt(1)
	v_mfma_f32_16x16x32_bf16 v[32:35], v[224:227], v[216:219], v[32:35]
	v_mfma_f32_16x16x32_bf16 v[36:39], v[228:231], v[216:219], v[36:39]
	v_mfma_f32_16x16x32_bf16 v[40:43], v[232:235], v[216:219], v[40:43]
	v_mfma_f32_16x16x32_bf16 v[44:47], v[236:239], v[216:219], v[44:47]
	s_waitcnt lgkmcnt(0)
	v_mfma_f32_16x16x32_bf16 v[48:51], v[224:227], v[220:223], v[48:51]
	v_mfma_f32_16x16x32_bf16 v[52:55], v[228:231], v[220:223], v[52:55]
	v_mfma_f32_16x16x32_bf16 v[56:59], v[232:235], v[220:223], v[56:59]
	v_mfma_f32_16x16x32_bf16 v[60:63], v[236:239], v[220:223], v[60:63]
	s_waitcnt vmcnt(0)
	s_barrier
	ds_read_b128 v[176:179], v244 offset:0
	ds_read_b128 v[80:83], v246 offset:0
	ds_read_b128 v[84:87], v246 offset:2048
	ds_read_b128 v[88:91], v246 offset:4096
	ds_read_b128 v[92:95], v246 offset:6144
	ds_read_b128 v[180:183], v244 offset:2048
	ds_read_b128 v[184:187], v244 offset:4096
	ds_read_b128 v[188:191], v244 offset:6144
	s_waitcnt lgkmcnt(6)
	v_mfma_f32_16x16x32_bf16 v[0:3], v[80:83], v[176:179], v[0:3]
	ds_read_b128 v[208:211], v245 offset:0
	s_add_i32 m0, s81, 32768
	s_waitcnt lgkmcnt(6)
	v_mfma_f32_16x16x32_bf16 v[4:7], v[84:87], v[176:179], v[4:7]
	ds_read_b128 v[224:227], v247 offset:0
	global_load_lds_dwordx4 v240, s[76:77]
	s_waitcnt lgkmcnt(6)
	v_mfma_f32_16x16x32_bf16 v[8:11], v[88:91], v[176:179], v[8:11]
	ds_read_b128 v[228:231], v247 offset:2048
	s_add_i32 m0, s81, 36864
	s_waitcnt lgkmcnt(6)
	v_mfma_f32_16x16x32_bf16 v[12:15], v[92:95], v[176:179], v[12:15]
	ds_read_b128 v[232:235], v247 offset:4096
	global_load_lds_dwordx4 v241, s[76:77]
	s_waitcnt lgkmcnt(6)
	v_mfma_f32_16x16x32_bf16 v[16:19], v[80:83], v[180:183], v[16:19]
	ds_read_b128 v[236:239], v247 offset:6144
	s_add_i32 m0, s81, 40960
	v_mfma_f32_16x16x32_bf16 v[20:23], v[84:87], v[180:183], v[20:23]
	ds_read_b128 v[212:215], v245 offset:2048
	global_load_lds_dwordx4 v242, s[76:77]
	v_mfma_f32_16x16x32_bf16 v[24:27], v[88:91], v[180:183], v[24:27]
	ds_read_b128 v[216:219], v245 offset:4096
	s_add_i32 m0, s81, 45056
	v_mfma_f32_16x16x32_bf16 v[28:31], v[92:95], v[180:183], v[28:31]
	ds_read_b128 v[220:223], v245 offset:6144
	global_load_lds_dwordx4 v243, s[76:77]
	s_waitcnt lgkmcnt(9)
	v_mfma_f32_16x16x32_bf16 v[32:35], v[80:83], v[184:187], v[32:35]
	s_add_i32 m0, s81, 49152
	v_mfma_f32_16x16x32_bf16 v[36:39], v[84:87], v[184:187], v[36:39]
	global_load_lds_dwordx4 v240, s[78:79]
	v_mfma_f32_16x16x32_bf16 v[40:43], v[88:91], v[184:187], v[40:43]
	s_add_i32 m0, s81, 53248
	v_mfma_f32_16x16x32_bf16 v[44:47], v[92:95], v[184:187], v[44:47]
	global_load_lds_dwordx4 v241, s[78:79]
	s_waitcnt lgkmcnt(8)
	v_mfma_f32_16x16x32_bf16 v[48:51], v[80:83], v[188:191], v[48:51]
	s_add_i32 m0, s81, 57344
	v_mfma_f32_16x16x32_bf16 v[52:55], v[84:87], v[188:191], v[52:55]
	global_load_lds_dwordx4 v242, s[78:79]
	v_mfma_f32_16x16x32_bf16 v[56:59], v[88:91], v[188:191], v[56:59]
	s_add_i32 m0, s81, 61440
	v_mfma_f32_16x16x32_bf16 v[60:63], v[92:95], v[188:191], v[60:63]
	global_load_lds_dwordx4 v243, s[78:79]
	s_waitcnt lgkmcnt(6)
	v_mfma_f32_16x16x32_bf16 v[0:3], v[224:227], v[208:211], v[0:3]
	s_add_u32 s76, s76, 0x80
	s_addc_u32 s77, s77, 0
	s_waitcnt lgkmcnt(5)
	v_mfma_f32_16x16x32_bf16 v[4:7], v[228:231], v[208:211], v[4:7]
	s_waitcnt lgkmcnt(4)
	v_mfma_f32_16x16x32_bf16 v[8:11], v[232:235], v[208:211], v[8:11]
	s_add_u32 s78, s78, 0x80
	s_addc_u32 s79, s79, 0
	s_waitcnt lgkmcnt(3)
	v_mfma_f32_16x16x32_bf16 v[12:15], v[236:239], v[208:211], v[12:15]
	s_waitcnt lgkmcnt(2)
	v_mfma_f32_16x16x32_bf16 v[16:19], v[224:227], v[212:215], v[16:19]
	v_add_u32_e32 v96, 0x0, v108
	v_mfma_f32_16x16x32_bf16 v[20:23], v[228:231], v[212:215], v[20:23]
	global_load_dwordx4 v[64:67], v96, s[86:87] nt
	v_mfma_f32_16x16x32_bf16 v[24:27], v[232:235], v[212:215], v[24:27]
	v_mfma_f32_16x16x32_bf16 v[28:31], v[236:239], v[212:215], v[28:31]
	s_waitcnt lgkmcnt(1)
	v_mfma_f32_16x16x32_bf16 v[32:35], v[224:227], v[216:219], v[32:35]
	v_mfma_f32_16x16x32_bf16 v[36:39], v[228:231], v[216:219], v[36:39]
	v_mfma_f32_16x16x32_bf16 v[40:43], v[232:235], v[216:219], v[40:43]
	v_mfma_f32_16x16x32_bf16 v[44:47], v[236:239], v[216:219], v[44:47]
	s_waitcnt lgkmcnt(0)
	v_mfma_f32_16x16x32_bf16 v[48:51], v[224:227], v[220:223], v[48:51]
	v_mfma_f32_16x16x32_bf16 v[52:55], v[228:231], v[220:223], v[52:55]
	v_mfma_f32_16x16x32_bf16 v[56:59], v[232:235], v[220:223], v[56:59]
	v_mfma_f32_16x16x32_bf16 v[60:63], v[236:239], v[220:223], v[60:63]
	s_waitcnt vmcnt(1)
	s_barrier
	ds_read_b128 v[176:179], v244 offset:32768
	ds_read_b128 v[80:83], v246 offset:32768
	ds_read_b128 v[84:87], v246 offset:34816
	ds_read_b128 v[88:91], v246 offset:36864
	ds_read_b128 v[92:95], v246 offset:38912
	ds_read_b128 v[180:183], v244 offset:34816
	ds_read_b128 v[184:187], v244 offset:36864
	ds_read_b128 v[188:191], v244 offset:38912
	s_waitcnt lgkmcnt(6)
	v_mfma_f32_16x16x32_bf16 v[0:3], v[80:83], v[176:179], v[0:3]
	ds_read_b128 v[208:211], v245 offset:32768
	s_add_i32 m0, s81, 0
	s_waitcnt lgkmcnt(6)
	v_mfma_f32_16x16x32_bf16 v[4:7], v[84:87], v[176:179], v[4:7]
	ds_read_b128 v[224:227], v247 offset:32768
	global_load_lds_dwordx4 v240, s[76:77]
	s_waitcnt lgkmcnt(6)
	v_mfma_f32_16x16x32_bf16 v[8:11], v[88:91], v[176:179], v[8:11]
	ds_read_b128 v[228:231], v247 offset:34816
	s_add_i32 m0, s81, 4096
	s_waitcnt lgkmcnt(6)
	v_mfma_f32_16x16x32_bf16 v[12:15], v[92:95], v[176:179], v[12:15]
	ds_read_b128 v[232:235], v247 offset:36864
	global_load_lds_dwordx4 v241, s[76:77]
	s_waitcnt lgkmcnt(6)
	v_mfma_f32_16x16x32_bf16 v[16:19], v[80:83], v[180:183], v[16:19]
	ds_read_b128 v[236:239], v247 offset:38912
	s_add_i32 m0, s81, 8192
	v_mfma_f32_16x16x32_bf16 v[20:23], v[84:87], v[180:183], v[20:23]
	ds_read_b128 v[212:215], v245 offset:34816
	global_load_lds_dwordx4 v242, s[76:77]
	v_mfma_f32_16x16x32_bf16 v[24:27], v[88:91], v[180:183], v[24:27]
	ds_read_b128 v[216:219], v245 offset:36864
	s_add_i32 m0, s81, 12288
	v_mfma_f32_16x16x32_bf16 v[28:31], v[92:95], v[180:183], v[28:31]
	ds_read_b128 v[220:223], v245 offset:38912
	global_load_lds_dwordx4 v243, s[76:77]
	s_waitcnt lgkmcnt(9)
	v_mfma_f32_16x16x32_bf16 v[32:35], v[80:83], v[184:187], v[32:35]
	s_add_i32 m0, s81, 16384
	v_mfma_f32_16x16x32_bf16 v[36:39], v[84:87], v[184:187], v[36:39]
	global_load_lds_dwordx4 v240, s[78:79]
	v_mfma_f32_16x16x32_bf16 v[40:43], v[88:91], v[184:187], v[40:43]
	s_add_i32 m0, s81, 20480
	v_mfma_f32_16x16x32_bf16 v[44:47], v[92:95], v[184:187], v[44:47]
	global_load_lds_dwordx4 v241, s[78:79]
	s_waitcnt lgkmcnt(8)
	v_mfma_f32_16x16x32_bf16 v[48:51], v[80:83], v[188:191], v[48:51]
	s_add_i32 m0, s81, 24576
	v_mfma_f32_16x16x32_bf16 v[52:55], v[84:87], v[188:191], v[52:55]
	global_load_lds_dwordx4 v242, s[78:79]
	v_mfma_f32_16x16x32_bf16 v[56:59], v[88:91], v[188:191], v[56:59]
	s_add_i32 m0, s81, 28672
	v_mfma_f32_16x16x32_bf16 v[60:63], v[92:95], v[188:191], v[60:63]
	global_load_lds_dwordx4 v243, s[78:79]
	s_waitcnt lgkmcnt(6)
	v_mfma_f32_16x16x32_bf16 v[0:3], v[224:227], v[208:211], v[0:3]
	s_add_u32 s76, s76, 0x80
	s_addc_u32 s77, s77, 0
	s_waitcnt lgkmcnt(5)
	v_mfma_f32_16x16x32_bf16 v[4:7], v[228:231], v[208:211], v[4:7]
	s_waitcnt lgkmcnt(4)
	v_mfma_f32_16x16x32_bf16 v[8:11], v[232:235], v[208:211], v[8:11]
	s_add_u32 s78, s78, 0x80
	s_addc_u32 s79, s79, 0
	s_waitcnt lgkmcnt(3)
	v_mfma_f32_16x16x32_bf16 v[12:15], v[236:239], v[208:211], v[12:15]
	s_waitcnt lgkmcnt(2)
	v_mfma_f32_16x16x32_bf16 v[16:19], v[224:227], v[212:215], v[16:19]
	v_add_u32_e32 v96, 0x8000, v108
	v_mfma_f32_16x16x32_bf16 v[20:23], v[228:231], v[212:215], v[20:23]
	global_load_dwordx4 v[68:71], v96, s[86:87] nt
	v_mfma_f32_16x16x32_bf16 v[24:27], v[232:235], v[212:215], v[24:27]
	v_mfma_f32_16x16x32_bf16 v[28:31], v[236:239], v[212:215], v[28:31]
	s_waitcnt lgkmcnt(1)
	v_mfma_f32_16x16x32_bf16 v[32:35], v[224:227], v[216:219], v[32:35]
	v_mfma_f32_16x16x32_bf16 v[36:39], v[228:231], v[216:219], v[36:39]
	v_mfma_f32_16x16x32_bf16 v[40:43], v[232:235], v[216:219], v[40:43]
	v_mfma_f32_16x16x32_bf16 v[44:47], v[236:239], v[216:219], v[44:47]
	s_waitcnt lgkmcnt(0)
	v_mfma_f32_16x16x32_bf16 v[48:51], v[224:227], v[220:223], v[48:51]
	v_mfma_f32_16x16x32_bf16 v[52:55], v[228:231], v[220:223], v[52:55]
	v_mfma_f32_16x16x32_bf16 v[56:59], v[232:235], v[220:223], v[56:59]
	v_mfma_f32_16x16x32_bf16 v[60:63], v[236:239], v[220:223], v[60:63]
	s_waitcnt vmcnt(1)
	s_barrier
	ds_read_b128 v[176:179], v244 offset:0
	ds_read_b128 v[80:83], v246 offset:0
	ds_read_b128 v[84:87], v246 offset:2048
	ds_read_b128 v[88:91], v246 offset:4096
	ds_read_b128 v[92:95], v246 offset:6144
	ds_read_b128 v[180:183], v244 offset:2048
	ds_read_b128 v[184:187], v244 offset:4096
	ds_read_b128 v[188:191], v244 offset:6144
	s_waitcnt lgkmcnt(6)
	v_mfma_f32_16x16x32_bf16 v[0:3], v[80:83], v[176:179], v[0:3]
	ds_read_b128 v[208:211], v245 offset:0
	s_add_i32 m0, s81, 32768
	s_waitcnt lgkmcnt(6)
	v_mfma_f32_16x16x32_bf16 v[4:7], v[84:87], v[176:179], v[4:7]
	ds_read_b128 v[224:227], v247 offset:0
	global_load_lds_dwordx4 v240, s[76:77]
	s_waitcnt lgkmcnt(6)
	v_mfma_f32_16x16x32_bf16 v[8:11], v[88:91], v[176:179], v[8:11]
	ds_read_b128 v[228:231], v247 offset:2048
	s_add_i32 m0, s81, 36864
	s_waitcnt lgkmcnt(6)
	v_mfma_f32_16x16x32_bf16 v[12:15], v[92:95], v[176:179], v[12:15]
	ds_read_b128 v[232:235], v247 offset:4096
	global_load_lds_dwordx4 v241, s[76:77]
	s_waitcnt lgkmcnt(6)
	v_mfma_f32_16x16x32_bf16 v[16:19], v[80:83], v[180:183], v[16:19]
	ds_read_b128 v[236:239], v247 offset:6144
	s_add_i32 m0, s81, 40960
	v_mfma_f32_16x16x32_bf16 v[20:23], v[84:87], v[180:183], v[20:23]
	ds_read_b128 v[212:215], v245 offset:2048
	global_load_lds_dwordx4 v242, s[76:77]
	v_mfma_f32_16x16x32_bf16 v[24:27], v[88:91], v[180:183], v[24:27]
	ds_read_b128 v[216:219], v245 offset:4096
	s_add_i32 m0, s81, 45056
	v_mfma_f32_16x16x32_bf16 v[28:31], v[92:95], v[180:183], v[28:31]
	ds_read_b128 v[220:223], v245 offset:6144
	global_load_lds_dwordx4 v243, s[76:77]
	s_waitcnt lgkmcnt(9)
	v_mfma_f32_16x16x32_bf16 v[32:35], v[80:83], v[184:187], v[32:35]
	s_add_i32 m0, s81, 49152
	v_mfma_f32_16x16x32_bf16 v[36:39], v[84:87], v[184:187], v[36:39]
	global_load_lds_dwordx4 v240, s[78:79]
	v_mfma_f32_16x16x32_bf16 v[40:43], v[88:91], v[184:187], v[40:43]
	s_add_i32 m0, s81, 53248
	v_mfma_f32_16x16x32_bf16 v[44:47], v[92:95], v[184:187], v[44:47]
	global_load_lds_dwordx4 v241, s[78:79]
	s_waitcnt lgkmcnt(8)
	v_mfma_f32_16x16x32_bf16 v[48:51], v[80:83], v[188:191], v[48:51]
	s_add_i32 m0, s81, 57344
	v_mfma_f32_16x16x32_bf16 v[52:55], v[84:87], v[188:191], v[52:55]
	global_load_lds_dwordx4 v242, s[78:79]
	v_mfma_f32_16x16x32_bf16 v[56:59], v[88:91], v[188:191], v[56:59]
	s_add_i32 m0, s81, 61440
	v_mfma_f32_16x16x32_bf16 v[60:63], v[92:95], v[188:191], v[60:63]
	global_load_lds_dwordx4 v243, s[78:79]
	s_waitcnt lgkmcnt(6)
	v_mfma_f32_16x16x32_bf16 v[0:3], v[224:227], v[208:211], v[0:3]
	s_add_u32 s76, s76, 0x80
	s_addc_u32 s77, s77, 0
	s_waitcnt lgkmcnt(5)
	v_mfma_f32_16x16x32_bf16 v[4:7], v[228:231], v[208:211], v[4:7]
	s_waitcnt lgkmcnt(4)
	v_mfma_f32_16x16x32_bf16 v[8:11], v[232:235], v[208:211], v[8:11]
	s_add_u32 s78, s78, 0x80
	s_addc_u32 s79, s79, 0
	s_waitcnt lgkmcnt(3)
	v_mfma_f32_16x16x32_bf16 v[12:15], v[236:239], v[208:211], v[12:15]
	s_waitcnt lgkmcnt(2)
	v_mfma_f32_16x16x32_bf16 v[16:19], v[224:227], v[212:215], v[16:19]
	v_add_u32_e32 v96, 0x10000, v108
	v_mfma_f32_16x16x32_bf16 v[20:23], v[228:231], v[212:215], v[20:23]
	global_load_dwordx4 v[192:195], v96, s[86:87] nt
	v_mfma_f32_16x16x32_bf16 v[24:27], v[232:235], v[212:215], v[24:27]
	v_mfma_f32_16x16x32_bf16 v[28:31], v[236:239], v[212:215], v[28:31]
	s_waitcnt lgkmcnt(1)
	v_mfma_f32_16x16x32_bf16 v[32:35], v[224:227], v[216:219], v[32:35]
	v_mfma_f32_16x16x32_bf16 v[36:39], v[228:231], v[216:219], v[36:39]
	v_mfma_f32_16x16x32_bf16 v[40:43], v[232:235], v[216:219], v[40:43]
	v_mfma_f32_16x16x32_bf16 v[44:47], v[236:239], v[216:219], v[44:47]
	s_waitcnt lgkmcnt(0)
	v_mfma_f32_16x16x32_bf16 v[48:51], v[224:227], v[220:223], v[48:51]
	v_mfma_f32_16x16x32_bf16 v[52:55], v[228:231], v[220:223], v[52:55]
	v_mfma_f32_16x16x32_bf16 v[56:59], v[232:235], v[220:223], v[56:59]
	v_mfma_f32_16x16x32_bf16 v[60:63], v[236:239], v[220:223], v[60:63]
	s_waitcnt vmcnt(1)
	s_barrier
	ds_read_b128 v[176:179], v244 offset:32768
	ds_read_b128 v[80:83], v246 offset:32768
	ds_read_b128 v[84:87], v246 offset:34816
	ds_read_b128 v[88:91], v246 offset:36864
	ds_read_b128 v[92:95], v246 offset:38912
	ds_read_b128 v[180:183], v244 offset:34816
	ds_read_b128 v[184:187], v244 offset:36864
	ds_read_b128 v[188:191], v244 offset:38912
	s_waitcnt lgkmcnt(6)
	v_mfma_f32_16x16x32_bf16 v[0:3], v[80:83], v[176:179], v[0:3]
	ds_read_b128 v[208:211], v245 offset:32768
	s_add_i32 m0, s81, 0
	s_waitcnt lgkmcnt(6)
	v_mfma_f32_16x16x32_bf16 v[4:7], v[84:87], v[176:179], v[4:7]
	ds_read_b128 v[224:227], v247 offset:32768
	global_load_lds_dwordx4 v240, s[76:77]
	s_waitcnt lgkmcnt(6)
	v_mfma_f32_16x16x32_bf16 v[8:11], v[88:91], v[176:179], v[8:11]
	ds_read_b128 v[228:231], v247 offset:34816
	s_add_i32 m0, s81, 4096
	s_waitcnt lgkmcnt(6)
	v_mfma_f32_16x16x32_bf16 v[12:15], v[92:95], v[176:179], v[12:15]
	ds_read_b128 v[232:235], v247 offset:36864
	global_load_lds_dwordx4 v241, s[76:77]
	s_waitcnt lgkmcnt(6)
	v_mfma_f32_16x16x32_bf16 v[16:19], v[80:83], v[180:183], v[16:19]
	ds_read_b128 v[236:239], v247 offset:38912
	s_add_i32 m0, s81, 8192
	v_mfma_f32_16x16x32_bf16 v[20:23], v[84:87], v[180:183], v[20:23]
	ds_read_b128 v[212:215], v245 offset:34816
	global_load_lds_dwordx4 v242, s[76:77]
	v_mfma_f32_16x16x32_bf16 v[24:27], v[88:91], v[180:183], v[24:27]
	ds_read_b128 v[216:219], v245 offset:36864
	s_add_i32 m0, s81, 12288
	v_mfma_f32_16x16x32_bf16 v[28:31], v[92:95], v[180:183], v[28:31]
	ds_read_b128 v[220:223], v245 offset:38912
	global_load_lds_dwordx4 v243, s[76:77]
	s_waitcnt lgkmcnt(9)
	v_mfma_f32_16x16x32_bf16 v[32:35], v[80:83], v[184:187], v[32:35]
	s_add_i32 m0, s81, 16384
	v_mfma_f32_16x16x32_bf16 v[36:39], v[84:87], v[184:187], v[36:39]
	global_load_lds_dwordx4 v240, s[78:79]
	v_mfma_f32_16x16x32_bf16 v[40:43], v[88:91], v[184:187], v[40:43]
	s_add_i32 m0, s81, 20480
	v_mfma_f32_16x16x32_bf16 v[44:47], v[92:95], v[184:187], v[44:47]
	global_load_lds_dwordx4 v241, s[78:79]
	s_waitcnt lgkmcnt(8)
	v_mfma_f32_16x16x32_bf16 v[48:51], v[80:83], v[188:191], v[48:51]
	s_add_i32 m0, s81, 24576
	v_mfma_f32_16x16x32_bf16 v[52:55], v[84:87], v[188:191], v[52:55]
	global_load_lds_dwordx4 v242, s[78:79]
	v_mfma_f32_16x16x32_bf16 v[56:59], v[88:91], v[188:191], v[56:59]
	s_add_i32 m0, s81, 28672
	v_mfma_f32_16x16x32_bf16 v[60:63], v[92:95], v[188:191], v[60:63]
	global_load_lds_dwordx4 v243, s[78:79]
	s_waitcnt lgkmcnt(6)
	v_mfma_f32_16x16x32_bf16 v[0:3], v[224:227], v[208:211], v[0:3]
	s_add_u32 s76, s76, 0x80
	s_addc_u32 s77, s77, 0
	s_waitcnt lgkmcnt(5)
	v_mfma_f32_16x16x32_bf16 v[4:7], v[228:231], v[208:211], v[4:7]
	s_waitcnt lgkmcnt(4)
	v_mfma_f32_16x16x32_bf16 v[8:11], v[232:235], v[208:211], v[8:11]
	s_add_u32 s78, s78, 0x80
	s_addc_u32 s79, s79, 0
	s_waitcnt lgkmcnt(3)
	v_mfma_f32_16x16x32_bf16 v[12:15], v[236:239], v[208:211], v[12:15]
	s_waitcnt lgkmcnt(2)
	v_mfma_f32_16x16x32_bf16 v[16:19], v[224:227], v[212:215], v[16:19]
	v_add_u32_e32 v96, 0x18000, v108
	v_mfma_f32_16x16x32_bf16 v[20:23], v[228:231], v[212:215], v[20:23]
	global_load_dwordx4 v[196:199], v96, s[86:87] nt
	v_mfma_f32_16x16x32_bf16 v[24:27], v[232:235], v[212:215], v[24:27]
	v_mfma_f32_16x16x32_bf16 v[28:31], v[236:239], v[212:215], v[28:31]
	s_waitcnt lgkmcnt(1)
	v_mfma_f32_16x16x32_bf16 v[32:35], v[224:227], v[216:219], v[32:35]
	v_mfma_f32_16x16x32_bf16 v[36:39], v[228:231], v[216:219], v[36:39]
	v_mfma_f32_16x16x32_bf16 v[40:43], v[232:235], v[216:219], v[40:43]
	v_mfma_f32_16x16x32_bf16 v[44:47], v[236:239], v[216:219], v[44:47]
	s_waitcnt lgkmcnt(0)
	v_mfma_f32_16x16x32_bf16 v[48:51], v[224:227], v[220:223], v[48:51]
	v_mfma_f32_16x16x32_bf16 v[52:55], v[228:231], v[220:223], v[52:55]
	v_mfma_f32_16x16x32_bf16 v[56:59], v[232:235], v[220:223], v[56:59]
	v_mfma_f32_16x16x32_bf16 v[60:63], v[236:239], v[220:223], v[60:63]
	s_waitcnt vmcnt(1)
	s_barrier
	ds_read_b128 v[176:179], v244 offset:0
	ds_read_b128 v[80:83], v246 offset:0
	ds_read_b128 v[84:87], v246 offset:2048
	ds_read_b128 v[88:91], v246 offset:4096
	ds_read_b128 v[92:95], v246 offset:6144
	ds_read_b128 v[180:183], v244 offset:2048
	ds_read_b128 v[184:187], v244 offset:4096
	ds_read_b128 v[188:191], v244 offset:6144
	s_waitcnt lgkmcnt(6)
	v_mfma_f32_16x16x32_bf16 v[0:3], v[80:83], v[176:179], v[0:3]
	ds_read_b128 v[208:211], v245 offset:0
	s_add_i32 m0, s81, 32768
	s_waitcnt lgkmcnt(6)
	v_mfma_f32_16x16x32_bf16 v[4:7], v[84:87], v[176:179], v[4:7]
	ds_read_b128 v[224:227], v247 offset:0
	global_load_lds_dwordx4 v240, s[76:77]
	s_waitcnt lgkmcnt(6)
	v_mfma_f32_16x16x32_bf16 v[8:11], v[88:91], v[176:179], v[8:11]
	ds_read_b128 v[228:231], v247 offset:2048
	s_add_i32 m0, s81, 36864
	s_waitcnt lgkmcnt(6)
	v_mfma_f32_16x16x32_bf16 v[12:15], v[92:95], v[176:179], v[12:15]
	ds_read_b128 v[232:235], v247 offset:4096
	global_load_lds_dwordx4 v241, s[76:77]
	s_waitcnt lgkmcnt(6)
	v_mfma_f32_16x16x32_bf16 v[16:19], v[80:83], v[180:183], v[16:19]
	ds_read_b128 v[236:239], v247 offset:6144
	s_add_i32 m0, s81, 40960
	v_mfma_f32_16x16x32_bf16 v[20:23], v[84:87], v[180:183], v[20:23]
	ds_read_b128 v[212:215], v245 offset:2048
	global_load_lds_dwordx4 v242, s[76:77]
	v_mfma_f32_16x16x32_bf16 v[24:27], v[88:91], v[180:183], v[24:27]
	ds_read_b128 v[216:219], v245 offset:4096
	s_add_i32 m0, s81, 45056
	v_mfma_f32_16x16x32_bf16 v[28:31], v[92:95], v[180:183], v[28:31]
	ds_read_b128 v[220:223], v245 offset:6144
	global_load_lds_dwordx4 v243, s[76:77]
	s_waitcnt lgkmcnt(9)
	v_mfma_f32_16x16x32_bf16 v[32:35], v[80:83], v[184:187], v[32:35]
	s_add_i32 m0, s81, 49152
	v_mfma_f32_16x16x32_bf16 v[36:39], v[84:87], v[184:187], v[36:39]
	global_load_lds_dwordx4 v240, s[78:79]
	v_mfma_f32_16x16x32_bf16 v[40:43], v[88:91], v[184:187], v[40:43]
	s_add_i32 m0, s81, 53248
	v_mfma_f32_16x16x32_bf16 v[44:47], v[92:95], v[184:187], v[44:47]
	global_load_lds_dwordx4 v241, s[78:79]
	s_waitcnt lgkmcnt(8)
	v_mfma_f32_16x16x32_bf16 v[48:51], v[80:83], v[188:191], v[48:51]
	s_add_i32 m0, s81, 57344
	v_mfma_f32_16x16x32_bf16 v[52:55], v[84:87], v[188:191], v[52:55]
	global_load_lds_dwordx4 v242, s[78:79]
	v_mfma_f32_16x16x32_bf16 v[56:59], v[88:91], v[188:191], v[56:59]
	s_add_i32 m0, s81, 61440
	v_mfma_f32_16x16x32_bf16 v[60:63], v[92:95], v[188:191], v[60:63]
	global_load_lds_dwordx4 v243, s[78:79]
	s_waitcnt lgkmcnt(6)
	v_mfma_f32_16x16x32_bf16 v[0:3], v[224:227], v[208:211], v[0:3]
	s_add_u32 s76, s76, 0x80
	s_addc_u32 s77, s77, 0
	s_waitcnt lgkmcnt(5)
	v_mfma_f32_16x16x32_bf16 v[4:7], v[228:231], v[208:211], v[4:7]
	s_waitcnt lgkmcnt(4)
	v_mfma_f32_16x16x32_bf16 v[8:11], v[232:235], v[208:211], v[8:11]
	s_add_u32 s78, s78, 0x80
	s_addc_u32 s79, s79, 0
	s_waitcnt lgkmcnt(3)
	v_mfma_f32_16x16x32_bf16 v[12:15], v[236:239], v[208:211], v[12:15]
	s_waitcnt lgkmcnt(2)
	v_mfma_f32_16x16x32_bf16 v[16:19], v[224:227], v[212:215], v[16:19]
	v_add_u32_e32 v96, 0x20000, v108
	v_mfma_f32_16x16x32_bf16 v[20:23], v[228:231], v[212:215], v[20:23]
	global_load_dwordx4 v[200:203], v96, s[86:87] nt
	v_mfma_f32_16x16x32_bf16 v[24:27], v[232:235], v[212:215], v[24:27]
	v_mfma_f32_16x16x32_bf16 v[28:31], v[236:239], v[212:215], v[28:31]
	s_waitcnt lgkmcnt(1)
	v_mfma_f32_16x16x32_bf16 v[32:35], v[224:227], v[216:219], v[32:35]
	v_mfma_f32_16x16x32_bf16 v[36:39], v[228:231], v[216:219], v[36:39]
	v_mfma_f32_16x16x32_bf16 v[40:43], v[232:235], v[216:219], v[40:43]
	v_mfma_f32_16x16x32_bf16 v[44:47], v[236:239], v[216:219], v[44:47]
	s_waitcnt lgkmcnt(0)
	v_mfma_f32_16x16x32_bf16 v[48:51], v[224:227], v[220:223], v[48:51]
	v_mfma_f32_16x16x32_bf16 v[52:55], v[228:231], v[220:223], v[52:55]
	v_mfma_f32_16x16x32_bf16 v[56:59], v[232:235], v[220:223], v[56:59]
	v_mfma_f32_16x16x32_bf16 v[60:63], v[236:239], v[220:223], v[60:63]
	s_waitcnt vmcnt(1)
	s_barrier
	ds_read_b128 v[176:179], v244 offset:32768
	ds_read_b128 v[80:83], v246 offset:32768
	ds_read_b128 v[84:87], v246 offset:34816
	ds_read_b128 v[88:91], v246 offset:36864
	ds_read_b128 v[92:95], v246 offset:38912
	ds_read_b128 v[180:183], v244 offset:34816
	ds_read_b128 v[184:187], v244 offset:36864
	ds_read_b128 v[188:191], v244 offset:38912
	s_waitcnt lgkmcnt(6)
	v_mfma_f32_16x16x32_bf16 v[0:3], v[80:83], v[176:179], v[0:3]
	ds_read_b128 v[208:211], v245 offset:32768
	s_add_i32 m0, s81, 0
	s_waitcnt lgkmcnt(6)
	v_mfma_f32_16x16x32_bf16 v[4:7], v[84:87], v[176:179], v[4:7]
	ds_read_b128 v[224:227], v247 offset:32768
	global_load_lds_dwordx4 v240, s[76:77]
	s_waitcnt lgkmcnt(6)
	v_mfma_f32_16x16x32_bf16 v[8:11], v[88:91], v[176:179], v[8:11]
	ds_read_b128 v[228:231], v247 offset:34816
	s_add_i32 m0, s81, 4096
	s_waitcnt lgkmcnt(6)
	v_mfma_f32_16x16x32_bf16 v[12:15], v[92:95], v[176:179], v[12:15]
	ds_read_b128 v[232:235], v247 offset:36864
	global_load_lds_dwordx4 v241, s[76:77]
	s_waitcnt lgkmcnt(6)
	v_mfma_f32_16x16x32_bf16 v[16:19], v[80:83], v[180:183], v[16:19]
	ds_read_b128 v[236:239], v247 offset:38912
	s_add_i32 m0, s81, 8192
	v_mfma_f32_16x16x32_bf16 v[20:23], v[84:87], v[180:183], v[20:23]
	ds_read_b128 v[212:215], v245 offset:34816
	global_load_lds_dwordx4 v242, s[76:77]
	v_mfma_f32_16x16x32_bf16 v[24:27], v[88:91], v[180:183], v[24:27]
	ds_read_b128 v[216:219], v245 offset:36864
	s_add_i32 m0, s81, 12288
	v_mfma_f32_16x16x32_bf16 v[28:31], v[92:95], v[180:183], v[28:31]
	ds_read_b128 v[220:223], v245 offset:38912
	global_load_lds_dwordx4 v243, s[76:77]
	s_waitcnt lgkmcnt(9)
	v_mfma_f32_16x16x32_bf16 v[32:35], v[80:83], v[184:187], v[32:35]
	s_add_i32 m0, s81, 16384
	v_mfma_f32_16x16x32_bf16 v[36:39], v[84:87], v[184:187], v[36:39]
	global_load_lds_dwordx4 v240, s[78:79]
	v_mfma_f32_16x16x32_bf16 v[40:43], v[88:91], v[184:187], v[40:43]
	s_add_i32 m0, s81, 20480
	v_mfma_f32_16x16x32_bf16 v[44:47], v[92:95], v[184:187], v[44:47]
	global_load_lds_dwordx4 v241, s[78:79]
	s_waitcnt lgkmcnt(8)
	v_mfma_f32_16x16x32_bf16 v[48:51], v[80:83], v[188:191], v[48:51]
	s_add_i32 m0, s81, 24576
	v_mfma_f32_16x16x32_bf16 v[52:55], v[84:87], v[188:191], v[52:55]
	global_load_lds_dwordx4 v242, s[78:79]
	v_mfma_f32_16x16x32_bf16 v[56:59], v[88:91], v[188:191], v[56:59]
	s_add_i32 m0, s81, 28672
	v_mfma_f32_16x16x32_bf16 v[60:63], v[92:95], v[188:191], v[60:63]
	global_load_lds_dwordx4 v243, s[78:79]
	s_waitcnt lgkmcnt(6)
	v_mfma_f32_16x16x32_bf16 v[0:3], v[224:227], v[208:211], v[0:3]
	s_add_u32 s76, s76, 0x80
	s_addc_u32 s77, s77, 0
	s_waitcnt lgkmcnt(5)
	v_mfma_f32_16x16x32_bf16 v[4:7], v[228:231], v[208:211], v[4:7]
	s_waitcnt lgkmcnt(4)
	v_mfma_f32_16x16x32_bf16 v[8:11], v[232:235], v[208:211], v[8:11]
	s_add_u32 s78, s78, 0x80
	s_addc_u32 s79, s79, 0
	s_waitcnt lgkmcnt(3)
	v_mfma_f32_16x16x32_bf16 v[12:15], v[236:239], v[208:211], v[12:15]
	s_waitcnt lgkmcnt(2)
	v_mfma_f32_16x16x32_bf16 v[16:19], v[224:227], v[212:215], v[16:19]
	v_add_u32_e32 v96, 0x28000, v108
	v_mfma_f32_16x16x32_bf16 v[20:23], v[228:231], v[212:215], v[20:23]
	global_load_dwordx4 v[110:113], v96, s[86:87] nt
	v_mfma_f32_16x16x32_bf16 v[24:27], v[232:235], v[212:215], v[24:27]
	v_mfma_f32_16x16x32_bf16 v[28:31], v[236:239], v[212:215], v[28:31]
	s_waitcnt lgkmcnt(1)
	v_mfma_f32_16x16x32_bf16 v[32:35], v[224:227], v[216:219], v[32:35]
	v_mfma_f32_16x16x32_bf16 v[36:39], v[228:231], v[216:219], v[36:39]
	v_mfma_f32_16x16x32_bf16 v[40:43], v[232:235], v[216:219], v[40:43]
	v_mfma_f32_16x16x32_bf16 v[44:47], v[236:239], v[216:219], v[44:47]
	s_waitcnt lgkmcnt(0)
	v_mfma_f32_16x16x32_bf16 v[48:51], v[224:227], v[220:223], v[48:51]
	v_mfma_f32_16x16x32_bf16 v[52:55], v[228:231], v[220:223], v[52:55]
	v_mfma_f32_16x16x32_bf16 v[56:59], v[232:235], v[220:223], v[56:59]
	v_mfma_f32_16x16x32_bf16 v[60:63], v[236:239], v[220:223], v[60:63]
	s_waitcnt vmcnt(1)
	s_barrier
	ds_read_b128 v[176:179], v244 offset:0
	ds_read_b128 v[80:83], v246 offset:0
	ds_read_b128 v[84:87], v246 offset:2048
	ds_read_b128 v[88:91], v246 offset:4096
	ds_read_b128 v[92:95], v246 offset:6144
	ds_read_b128 v[180:183], v244 offset:2048
	ds_read_b128 v[184:187], v244 offset:4096
	ds_read_b128 v[188:191], v244 offset:6144
	s_waitcnt lgkmcnt(6)
	v_mfma_f32_16x16x32_bf16 v[0:3], v[80:83], v[176:179], v[0:3]
	ds_read_b128 v[208:211], v245 offset:0
	s_add_i32 m0, s81, 32768
	s_waitcnt lgkmcnt(6)
	v_mfma_f32_16x16x32_bf16 v[4:7], v[84:87], v[176:179], v[4:7]
	ds_read_b128 v[224:227], v247 offset:0
	global_load_lds_dwordx4 v240, s[76:77]
	s_waitcnt lgkmcnt(6)
	v_mfma_f32_16x16x32_bf16 v[8:11], v[88:91], v[176:179], v[8:11]
	ds_read_b128 v[228:231], v247 offset:2048
	s_add_i32 m0, s81, 36864
	s_waitcnt lgkmcnt(6)
	v_mfma_f32_16x16x32_bf16 v[12:15], v[92:95], v[176:179], v[12:15]
	ds_read_b128 v[232:235], v247 offset:4096
	global_load_lds_dwordx4 v241, s[76:77]
	s_waitcnt lgkmcnt(6)
	v_mfma_f32_16x16x32_bf16 v[16:19], v[80:83], v[180:183], v[16:19]
	ds_read_b128 v[236:239], v247 offset:6144
	s_add_i32 m0, s81, 40960
	v_mfma_f32_16x16x32_bf16 v[20:23], v[84:87], v[180:183], v[20:23]
	ds_read_b128 v[212:215], v245 offset:2048
	global_load_lds_dwordx4 v242, s[76:77]
	v_mfma_f32_16x16x32_bf16 v[24:27], v[88:91], v[180:183], v[24:27]
	ds_read_b128 v[216:219], v245 offset:4096
	s_add_i32 m0, s81, 45056
	v_mfma_f32_16x16x32_bf16 v[28:31], v[92:95], v[180:183], v[28:31]
	ds_read_b128 v[220:223], v245 offset:6144
	global_load_lds_dwordx4 v243, s[76:77]
	s_waitcnt lgkmcnt(9)
	v_mfma_f32_16x16x32_bf16 v[32:35], v[80:83], v[184:187], v[32:35]
	s_add_i32 m0, s81, 49152
	v_mfma_f32_16x16x32_bf16 v[36:39], v[84:87], v[184:187], v[36:39]
	global_load_lds_dwordx4 v240, s[78:79]
	v_mfma_f32_16x16x32_bf16 v[40:43], v[88:91], v[184:187], v[40:43]
	s_add_i32 m0, s81, 53248
	v_mfma_f32_16x16x32_bf16 v[44:47], v[92:95], v[184:187], v[44:47]
	global_load_lds_dwordx4 v241, s[78:79]
	s_waitcnt lgkmcnt(8)
	v_mfma_f32_16x16x32_bf16 v[48:51], v[80:83], v[188:191], v[48:51]
	s_add_i32 m0, s81, 57344
	v_mfma_f32_16x16x32_bf16 v[52:55], v[84:87], v[188:191], v[52:55]
	global_load_lds_dwordx4 v242, s[78:79]
	v_mfma_f32_16x16x32_bf16 v[56:59], v[88:91], v[188:191], v[56:59]
	s_add_i32 m0, s81, 61440
	v_mfma_f32_16x16x32_bf16 v[60:63], v[92:95], v[188:191], v[60:63]
	global_load_lds_dwordx4 v243, s[78:79]
	s_waitcnt lgkmcnt(6)
	v_mfma_f32_16x16x32_bf16 v[0:3], v[224:227], v[208:211], v[0:3]
	s_add_u32 s76, s76, 0x80
	s_addc_u32 s77, s77, 0
	s_waitcnt lgkmcnt(5)
	v_mfma_f32_16x16x32_bf16 v[4:7], v[228:231], v[208:211], v[4:7]
	s_waitcnt lgkmcnt(4)
	v_mfma_f32_16x16x32_bf16 v[8:11], v[232:235], v[208:211], v[8:11]
	s_add_u32 s78, s78, 0x80
	s_addc_u32 s79, s79, 0
	s_waitcnt lgkmcnt(3)
	v_mfma_f32_16x16x32_bf16 v[12:15], v[236:239], v[208:211], v[12:15]
	s_waitcnt lgkmcnt(2)
	v_mfma_f32_16x16x32_bf16 v[16:19], v[224:227], v[212:215], v[16:19]
	v_add_u32_e32 v96, 0x30000, v108
	v_mfma_f32_16x16x32_bf16 v[20:23], v[228:231], v[212:215], v[20:23]
	global_load_dwordx4 v[116:119], v96, s[86:87] nt
	v_mfma_f32_16x16x32_bf16 v[24:27], v[232:235], v[212:215], v[24:27]
	v_mfma_f32_16x16x32_bf16 v[28:31], v[236:239], v[212:215], v[28:31]
	s_waitcnt lgkmcnt(1)
	v_mfma_f32_16x16x32_bf16 v[32:35], v[224:227], v[216:219], v[32:35]
	v_mfma_f32_16x16x32_bf16 v[36:39], v[228:231], v[216:219], v[36:39]
	v_mfma_f32_16x16x32_bf16 v[40:43], v[232:235], v[216:219], v[40:43]
	v_mfma_f32_16x16x32_bf16 v[44:47], v[236:239], v[216:219], v[44:47]
	s_waitcnt lgkmcnt(0)
	v_mfma_f32_16x16x32_bf16 v[48:51], v[224:227], v[220:223], v[48:51]
	v_mfma_f32_16x16x32_bf16 v[52:55], v[228:231], v[220:223], v[52:55]
	v_mfma_f32_16x16x32_bf16 v[56:59], v[232:235], v[220:223], v[56:59]
	v_mfma_f32_16x16x32_bf16 v[60:63], v[236:239], v[220:223], v[60:63]
	s_waitcnt vmcnt(1)
	s_barrier
	ds_read_b128 v[176:179], v244 offset:32768
	ds_read_b128 v[80:83], v246 offset:32768
	ds_read_b128 v[84:87], v246 offset:34816
	ds_read_b128 v[88:91], v246 offset:36864
	ds_read_b128 v[92:95], v246 offset:38912
	ds_read_b128 v[180:183], v244 offset:34816
	ds_read_b128 v[184:187], v244 offset:36864
	ds_read_b128 v[188:191], v244 offset:38912
	s_waitcnt lgkmcnt(6)
	v_mfma_f32_16x16x32_bf16 v[0:3], v[80:83], v[176:179], v[0:3]
	ds_read_b128 v[208:211], v245 offset:32768
	s_add_i32 m0, s81, 0
	s_waitcnt lgkmcnt(6)
	v_mfma_f32_16x16x32_bf16 v[4:7], v[84:87], v[176:179], v[4:7]
	ds_read_b128 v[224:227], v247 offset:32768
	global_load_lds_dwordx4 v240, s[76:77]
	s_waitcnt lgkmcnt(6)
	v_mfma_f32_16x16x32_bf16 v[8:11], v[88:91], v[176:179], v[8:11]
	ds_read_b128 v[228:231], v247 offset:34816
	s_add_i32 m0, s81, 4096
	s_waitcnt lgkmcnt(6)
	v_mfma_f32_16x16x32_bf16 v[12:15], v[92:95], v[176:179], v[12:15]
	ds_read_b128 v[232:235], v247 offset:36864
	global_load_lds_dwordx4 v241, s[76:77]
	s_waitcnt lgkmcnt(6)
	v_mfma_f32_16x16x32_bf16 v[16:19], v[80:83], v[180:183], v[16:19]
	ds_read_b128 v[236:239], v247 offset:38912
	s_add_i32 m0, s81, 8192
	v_mfma_f32_16x16x32_bf16 v[20:23], v[84:87], v[180:183], v[20:23]
	ds_read_b128 v[212:215], v245 offset:34816
	global_load_lds_dwordx4 v242, s[76:77]
	v_mfma_f32_16x16x32_bf16 v[24:27], v[88:91], v[180:183], v[24:27]
	ds_read_b128 v[216:219], v245 offset:36864
	s_add_i32 m0, s81, 12288
	v_mfma_f32_16x16x32_bf16 v[28:31], v[92:95], v[180:183], v[28:31]
	ds_read_b128 v[220:223], v245 offset:38912
	global_load_lds_dwordx4 v243, s[76:77]
	s_waitcnt lgkmcnt(9)
	v_mfma_f32_16x16x32_bf16 v[32:35], v[80:83], v[184:187], v[32:35]
	s_add_i32 m0, s81, 16384
	v_mfma_f32_16x16x32_bf16 v[36:39], v[84:87], v[184:187], v[36:39]
	global_load_lds_dwordx4 v240, s[78:79]
	v_mfma_f32_16x16x32_bf16 v[40:43], v[88:91], v[184:187], v[40:43]
	s_add_i32 m0, s81, 20480
	v_mfma_f32_16x16x32_bf16 v[44:47], v[92:95], v[184:187], v[44:47]
	global_load_lds_dwordx4 v241, s[78:79]
	s_waitcnt lgkmcnt(8)
	v_mfma_f32_16x16x32_bf16 v[48:51], v[80:83], v[188:191], v[48:51]
	s_add_i32 m0, s81, 24576
	v_mfma_f32_16x16x32_bf16 v[52:55], v[84:87], v[188:191], v[52:55]
	global_load_lds_dwordx4 v242, s[78:79]
	v_mfma_f32_16x16x32_bf16 v[56:59], v[88:91], v[188:191], v[56:59]
	s_add_i32 m0, s81, 28672
	v_mfma_f32_16x16x32_bf16 v[60:63], v[92:95], v[188:191], v[60:63]
	global_load_lds_dwordx4 v243, s[78:79]
	s_waitcnt lgkmcnt(6)
	v_mfma_f32_16x16x32_bf16 v[0:3], v[224:227], v[208:211], v[0:3]
	s_add_u32 s76, s76, 0x80
	s_addc_u32 s77, s77, 0
	s_waitcnt lgkmcnt(5)
	v_mfma_f32_16x16x32_bf16 v[4:7], v[228:231], v[208:211], v[4:7]
	s_waitcnt lgkmcnt(4)
	v_mfma_f32_16x16x32_bf16 v[8:11], v[232:235], v[208:211], v[8:11]
	s_add_u32 s78, s78, 0x80
	s_addc_u32 s79, s79, 0
	s_waitcnt lgkmcnt(3)
	v_mfma_f32_16x16x32_bf16 v[12:15], v[236:239], v[208:211], v[12:15]
	s_waitcnt lgkmcnt(2)
	v_mfma_f32_16x16x32_bf16 v[16:19], v[224:227], v[212:215], v[16:19]
	v_add_u32_e32 v96, 0x38000, v108
	v_mfma_f32_16x16x32_bf16 v[20:23], v[228:231], v[212:215], v[20:23]
	global_load_dwordx4 v[120:123], v96, s[86:87] nt
	v_mfma_f32_16x16x32_bf16 v[24:27], v[232:235], v[212:215], v[24:27]
	v_mfma_f32_16x16x32_bf16 v[28:31], v[236:239], v[212:215], v[28:31]
	s_waitcnt lgkmcnt(1)
	v_mfma_f32_16x16x32_bf16 v[32:35], v[224:227], v[216:219], v[32:35]
	v_mfma_f32_16x16x32_bf16 v[36:39], v[228:231], v[216:219], v[36:39]
	v_mfma_f32_16x16x32_bf16 v[40:43], v[232:235], v[216:219], v[40:43]
	v_mfma_f32_16x16x32_bf16 v[44:47], v[236:239], v[216:219], v[44:47]
	s_waitcnt lgkmcnt(0)
	v_mfma_f32_16x16x32_bf16 v[48:51], v[224:227], v[220:223], v[48:51]
	v_mfma_f32_16x16x32_bf16 v[52:55], v[228:231], v[220:223], v[52:55]
	v_mfma_f32_16x16x32_bf16 v[56:59], v[232:235], v[220:223], v[56:59]
	v_mfma_f32_16x16x32_bf16 v[60:63], v[236:239], v[220:223], v[60:63]
	s_waitcnt vmcnt(1)
	s_barrier
	ds_read_b128 v[176:179], v244 offset:0
	ds_read_b128 v[80:83], v246 offset:0
	ds_read_b128 v[84:87], v246 offset:2048
	ds_read_b128 v[88:91], v246 offset:4096
	ds_read_b128 v[92:95], v246 offset:6144
	ds_read_b128 v[180:183], v244 offset:2048
	ds_read_b128 v[184:187], v244 offset:4096
	ds_read_b128 v[188:191], v244 offset:6144
	s_waitcnt lgkmcnt(6)
	v_mfma_f32_16x16x32_bf16 v[0:3], v[80:83], v[176:179], v[0:3]
	ds_read_b128 v[208:211], v245 offset:0
	s_add_i32 m0, s81, 32768
	s_waitcnt lgkmcnt(6)
	v_mfma_f32_16x16x32_bf16 v[4:7], v[84:87], v[176:179], v[4:7]
	ds_read_b128 v[224:227], v247 offset:0
	global_load_lds_dwordx4 v240, s[76:77]
	s_waitcnt lgkmcnt(6)
	v_mfma_f32_16x16x32_bf16 v[8:11], v[88:91], v[176:179], v[8:11]
	ds_read_b128 v[228:231], v247 offset:2048
	s_add_i32 m0, s81, 36864
	s_waitcnt lgkmcnt(6)
	v_mfma_f32_16x16x32_bf16 v[12:15], v[92:95], v[176:179], v[12:15]
	ds_read_b128 v[232:235], v247 offset:4096
	global_load_lds_dwordx4 v241, s[76:77]
	s_waitcnt lgkmcnt(6)
	v_mfma_f32_16x16x32_bf16 v[16:19], v[80:83], v[180:183], v[16:19]
	ds_read_b128 v[236:239], v247 offset:6144
	s_add_i32 m0, s81, 40960
	v_mfma_f32_16x16x32_bf16 v[20:23], v[84:87], v[180:183], v[20:23]
	ds_read_b128 v[212:215], v245 offset:2048
	global_load_lds_dwordx4 v242, s[76:77]
	v_mfma_f32_16x16x32_bf16 v[24:27], v[88:91], v[180:183], v[24:27]
	ds_read_b128 v[216:219], v245 offset:4096
	s_add_i32 m0, s81, 45056
	v_mfma_f32_16x16x32_bf16 v[28:31], v[92:95], v[180:183], v[28:31]
	ds_read_b128 v[220:223], v245 offset:6144
	global_load_lds_dwordx4 v243, s[76:77]
	s_waitcnt lgkmcnt(9)
	v_mfma_f32_16x16x32_bf16 v[32:35], v[80:83], v[184:187], v[32:35]
	s_add_i32 m0, s81, 49152
	v_mfma_f32_16x16x32_bf16 v[36:39], v[84:87], v[184:187], v[36:39]
	global_load_lds_dwordx4 v240, s[78:79]
	v_mfma_f32_16x16x32_bf16 v[40:43], v[88:91], v[184:187], v[40:43]
	s_add_i32 m0, s81, 53248
	v_mfma_f32_16x16x32_bf16 v[44:47], v[92:95], v[184:187], v[44:47]
	global_load_lds_dwordx4 v241, s[78:79]
	s_waitcnt lgkmcnt(8)
	v_mfma_f32_16x16x32_bf16 v[48:51], v[80:83], v[188:191], v[48:51]
	s_add_i32 m0, s81, 57344
	v_mfma_f32_16x16x32_bf16 v[52:55], v[84:87], v[188:191], v[52:55]
	global_load_lds_dwordx4 v242, s[78:79]
	v_mfma_f32_16x16x32_bf16 v[56:59], v[88:91], v[188:191], v[56:59]
	s_add_i32 m0, s81, 61440
	v_mfma_f32_16x16x32_bf16 v[60:63], v[92:95], v[188:191], v[60:63]
	global_load_lds_dwordx4 v243, s[78:79]
	s_waitcnt lgkmcnt(6)
	v_mfma_f32_16x16x32_bf16 v[0:3], v[224:227], v[208:211], v[0:3]
	s_add_u32 s76, s76, 0x80
	s_addc_u32 s77, s77, 0
	s_waitcnt lgkmcnt(5)
	v_mfma_f32_16x16x32_bf16 v[4:7], v[228:231], v[208:211], v[4:7]
	s_waitcnt lgkmcnt(4)
	v_mfma_f32_16x16x32_bf16 v[8:11], v[232:235], v[208:211], v[8:11]
	s_add_u32 s78, s78, 0x80
	s_addc_u32 s79, s79, 0
	s_waitcnt lgkmcnt(3)
	v_mfma_f32_16x16x32_bf16 v[12:15], v[236:239], v[208:211], v[12:15]
	s_waitcnt lgkmcnt(2)
	v_mfma_f32_16x16x32_bf16 v[16:19], v[224:227], v[212:215], v[16:19]
	v_mfma_f32_16x16x32_bf16 v[20:23], v[228:231], v[212:215], v[20:23]
	v_mfma_f32_16x16x32_bf16 v[24:27], v[232:235], v[212:215], v[24:27]
	v_mfma_f32_16x16x32_bf16 v[28:31], v[236:239], v[212:215], v[28:31]
	s_waitcnt lgkmcnt(1)
	v_mfma_f32_16x16x32_bf16 v[32:35], v[224:227], v[216:219], v[32:35]
	v_mfma_f32_16x16x32_bf16 v[36:39], v[228:231], v[216:219], v[36:39]
	v_mfma_f32_16x16x32_bf16 v[40:43], v[232:235], v[216:219], v[40:43]
	v_mfma_f32_16x16x32_bf16 v[44:47], v[236:239], v[216:219], v[44:47]
	s_waitcnt lgkmcnt(0)
	v_mfma_f32_16x16x32_bf16 v[48:51], v[224:227], v[220:223], v[48:51]
	v_mfma_f32_16x16x32_bf16 v[52:55], v[228:231], v[220:223], v[52:55]
	v_mfma_f32_16x16x32_bf16 v[56:59], v[232:235], v[220:223], v[56:59]
	v_mfma_f32_16x16x32_bf16 v[60:63], v[236:239], v[220:223], v[60:63]
	s_waitcnt vmcnt(0)
	s_barrier
	ds_read_b128 v[176:179], v244 offset:32768
	ds_read_b128 v[80:83], v246 offset:32768
	ds_read_b128 v[84:87], v246 offset:34816
	ds_read_b128 v[88:91], v246 offset:36864
	ds_read_b128 v[92:95], v246 offset:38912
	ds_read_b128 v[180:183], v244 offset:34816
	ds_read_b128 v[184:187], v244 offset:36864
	ds_read_b128 v[188:191], v244 offset:38912
	s_waitcnt lgkmcnt(6)
	v_mfma_f32_16x16x32_bf16 v[0:3], v[80:83], v[176:179], v[0:3]
	ds_read_b128 v[208:211], v245 offset:32768
	s_waitcnt lgkmcnt(6)
	v_mfma_f32_16x16x32_bf16 v[4:7], v[84:87], v[176:179], v[4:7]
	ds_read_b128 v[224:227], v247 offset:32768
	s_waitcnt lgkmcnt(6)
	v_mfma_f32_16x16x32_bf16 v[8:11], v[88:91], v[176:179], v[8:11]
	ds_read_b128 v[228:231], v247 offset:34816
	s_waitcnt lgkmcnt(6)
	v_mfma_f32_16x16x32_bf16 v[12:15], v[92:95], v[176:179], v[12:15]
	ds_read_b128 v[232:235], v247 offset:36864
	s_waitcnt lgkmcnt(6)
	v_mfma_f32_16x16x32_bf16 v[16:19], v[80:83], v[180:183], v[16:19]
	ds_read_b128 v[236:239], v247 offset:38912
	v_mfma_f32_16x16x32_bf16 v[20:23], v[84:87], v[180:183], v[20:23]
	ds_read_b128 v[212:215], v245 offset:34816
	v_mfma_f32_16x16x32_bf16 v[24:27], v[88:91], v[180:183], v[24:27]
	ds_read_b128 v[216:219], v245 offset:36864
	v_mfma_f32_16x16x32_bf16 v[28:31], v[92:95], v[180:183], v[28:31]
	ds_read_b128 v[220:223], v245 offset:38912
	s_waitcnt lgkmcnt(9)
	v_mfma_f32_16x16x32_bf16 v[32:35], v[80:83], v[184:187], v[32:35]
	v_mfma_f32_16x16x32_bf16 v[36:39], v[84:87], v[184:187], v[36:39]
	v_mfma_f32_16x16x32_bf16 v[40:43], v[88:91], v[184:187], v[40:43]
	v_mfma_f32_16x16x32_bf16 v[44:47], v[92:95], v[184:187], v[44:47]
	s_waitcnt lgkmcnt(8)
	v_mfma_f32_16x16x32_bf16 v[48:51], v[80:83], v[188:191], v[48:51]
	v_mfma_f32_16x16x32_bf16 v[52:55], v[84:87], v[188:191], v[52:55]
	v_mfma_f32_16x16x32_bf16 v[56:59], v[88:91], v[188:191], v[56:59]
	v_mfma_f32_16x16x32_bf16 v[60:63], v[92:95], v[188:191], v[60:63]
	s_waitcnt lgkmcnt(6)
	v_mfma_f32_16x16x32_bf16 v[0:3], v[224:227], v[208:211], v[0:3]
	s_waitcnt lgkmcnt(5)
	v_mfma_f32_16x16x32_bf16 v[4:7], v[228:231], v[208:211], v[4:7]
	s_waitcnt lgkmcnt(4)
	v_mfma_f32_16x16x32_bf16 v[8:11], v[232:235], v[208:211], v[8:11]
	s_waitcnt lgkmcnt(3)
	v_mfma_f32_16x16x32_bf16 v[12:15], v[236:239], v[208:211], v[12:15]
	s_waitcnt lgkmcnt(2)
	v_mfma_f32_16x16x32_bf16 v[16:19], v[224:227], v[212:215], v[16:19]
	v_mfma_f32_16x16x32_bf16 v[20:23], v[228:231], v[212:215], v[20:23]
	v_mfma_f32_16x16x32_bf16 v[24:27], v[232:235], v[212:215], v[24:27]
	v_mfma_f32_16x16x32_bf16 v[28:31], v[236:239], v[212:215], v[28:31]
	s_waitcnt lgkmcnt(1)
	v_mfma_f32_16x16x32_bf16 v[32:35], v[224:227], v[216:219], v[32:35]
	v_mfma_f32_16x16x32_bf16 v[36:39], v[228:231], v[216:219], v[36:39]
	v_mfma_f32_16x16x32_bf16 v[40:43], v[232:235], v[216:219], v[40:43]
	v_mfma_f32_16x16x32_bf16 v[44:47], v[236:239], v[216:219], v[44:47]
	s_waitcnt lgkmcnt(0)
	v_mfma_f32_16x16x32_bf16 v[48:51], v[224:227], v[220:223], v[48:51]
	v_mfma_f32_16x16x32_bf16 v[52:55], v[228:231], v[220:223], v[52:55]
	v_mfma_f32_16x16x32_bf16 v[56:59], v[232:235], v[220:223], v[56:59]
	v_mfma_f32_16x16x32_bf16 v[60:63], v[236:239], v[220:223], v[60:63]
.Lot_stage:
	s_barrier
	ds_write_b128 v248, v[0:3] offset:0
	ds_write_b128 v248, v[4:7] offset:64
	ds_write_b128 v248, v[8:11] offset:128
	ds_write_b128 v248, v[12:15] offset:192
	ds_write_b128 v248, v[16:19] offset:8448
	ds_write_b128 v248, v[20:23] offset:8512
	ds_write_b128 v248, v[24:27] offset:8576
	ds_write_b128 v248, v[28:31] offset:8640
	ds_write_b128 v248, v[32:35] offset:16896
	ds_write_b128 v248, v[36:39] offset:16960
	ds_write_b128 v248, v[40:43] offset:17024
	ds_write_b128 v248, v[44:47] offset:17088
	ds_write_b128 v248, v[48:51] offset:25344
	ds_write_b128 v248, v[52:55] offset:25408
	ds_write_b128 v248, v[56:59] offset:25472
	ds_write_b128 v248, v[60:63] offset:25536
	global_load_dwordx4 v[208:211], v114, s[90:91]
	global_load_dwordx4 v[212:215], v114, s[90:91] offset:16
	s_cmp_eq_u64 s[52:53], 0
	s_cbranch_scc0 .Lot_epi_l1
	v_add_u32_e32 v96, 0x70000, v102
	global_load_dwordx4 v[216:219], v96, s[86:87] nt
	global_load_dwordx4 v[220:223], v96, s[86:87] offset:16 nt
	s_waitcnt lgkmcnt(0)
	s_barrier
	ds_read_b128 v[0:3], v124 offset:0
	ds_read_b128 v[4:7], v124 offset:16
	ds_read_b128 v[8:11], v124 offset:8448
	ds_read_b128 v[12:15], v124 offset:8464
	ds_read_b128 v[16:19], v124 offset:16896
	ds_read_b128 v[20:23], v124 offset:16912
	ds_read_b128 v[24:27], v124 offset:25344
	ds_read_b128 v[28:31], v124 offset:25360
	ds_read_b128 v[32:35], v124 offset:33792
	ds_read_b128 v[36:39], v124 offset:33808
	ds_read_b128 v[40:43], v124 offset:42240
	ds_read_b128 v[44:47], v124 offset:42256
	ds_read_b128 v[48:51], v124 offset:50688
	ds_read_b128 v[52:55], v124 offset:50704
	ds_read_b128 v[56:59], v124 offset:59136
	ds_read_b128 v[60:63], v124 offset:59152
	s_waitcnt vmcnt(2)
	s_waitcnt lgkmcnt(14)
	v_fma_f32 v0, v208, v0, v64
	v_fma_f32 v1, v209, v1, v65
	v_fma_f32 v2, v210, v2, v66
	v_fma_f32 v3, v211, v3, v67
	v_fma_f32 v4, v212, v4, v68
	v_fma_f32 v5, v213, v5, v69
	v_fma_f32 v6, v214, v6, v70
	v_fma_f32 v7, v215, v7, v71
	v_cvt_pk_bf16_f32 v0, v0, v1
	v_cvt_pk_bf16_f32 v1, v2, v3
	v_cvt_pk_bf16_f32 v2, v4, v5
	v_cvt_pk_bf16_f32 v3, v6, v7
	v_add_u32_e32 v96, 0, v108
	global_store_dwordx4 v96, v[0:3], s[88:89]
	s_waitcnt vmcnt(3)
	s_waitcnt lgkmcnt(12)
	v_fma_f32 v8, v208, v8, v74
	v_fma_f32 v9, v209, v9, v75
	v_fma_f32 v10, v210, v10, v76
	v_fma_f32 v11, v211, v11, v77
	v_fma_f32 v12, v212, v12, v98
	v_fma_f32 v13, v213, v13, v99
	v_fma_f32 v14, v214, v14, v100
	v_fma_f32 v15, v215, v15, v101
	v_cvt_pk_bf16_f32 v8, v8, v9
	v_cvt_pk_bf16_f32 v9, v10, v11
	v_cvt_pk_bf16_f32 v10, v12, v13
	v_cvt_pk_bf16_f32 v11, v14, v15
	v_add_u32_e32 v96, 32768, v108
	global_store_dwordx4 v96, v[8:11], s[88:89]
	s_waitcnt vmcnt(4)
	s_waitcnt lgkmcnt(10)
	v_fma_f32 v16, v208, v16, v104
	v_fma_f32 v17, v209, v17, v105
	v_fma_f32 v18, v210, v18, v106
	v_fma_f32 v19, v211, v19, v107
	v_fma_f32 v20, v212, v20, v110
	v_fma_f32 v21, v213, v21, v111
	v_fma_f32 v22, v214, v22, v112
	v_fma_f32 v23, v215, v23, v113
	v_cvt_pk_bf16_f32 v16, v16, v17
	v_cvt_pk_bf16_f32 v17, v18, v19
	v_cvt_pk_bf16_f32 v18, v20, v21
	v_cvt_pk_bf16_f32 v19, v22, v23
	v_add_u32_e32 v96, 65536, v108
	global_store_dwordx4 v96, v[16:19], s[88:89]
	s_waitcnt vmcnt(5)
	s_waitcnt lgkmcnt(8)
	v_fma_f32 v24, v208, v24, v116
	v_fma_f32 v25, v209, v25, v117
	v_fma_f32 v26, v210, v26, v118
	v_fma_f32 v27, v211, v27, v119
	v_fma_f32 v28, v212, v28, v120
	v_fma_f32 v29, v213, v29, v121
	v_fma_f32 v30, v214, v30, v122
	v_fma_f32 v31, v215, v31, v123
	v_cvt_pk_bf16_f32 v24, v24, v25
	v_cvt_pk_bf16_f32 v25, v26, v27
	v_cvt_pk_bf16_f32 v26, v28, v29
	v_cvt_pk_bf16_f32 v27, v30, v31
	v_add_u32_e32 v96, 98304, v108
	global_store_dwordx4 v96, v[24:27], s[88:89]
	s_waitcnt vmcnt(6)
	s_waitcnt lgkmcnt(6)
	v_fma_f32 v32, v208, v32, v126
	v_fma_f32 v33, v209, v33, v127
	v_fma_f32 v34, v210, v34, v128
	v_fma_f32 v35, v211, v35, v129
	v_fma_f32 v36, v212, v36, v168
	v_fma_f32 v37, v213, v37, v169
	v_fma_f32 v38, v214, v38, v170
	v_fma_f32 v39, v215, v39, v171
	v_cvt_pk_bf16_f32 v32, v32, v33
	v_cvt_pk_bf16_f32 v33, v34, v35
	v_cvt_pk_bf16_f32 v34, v36, v37
	v_cvt_pk_bf16_f32 v35, v38, v39
	v_add_u32_e32 v96, 131072, v108
	global_store_dwordx4 v96, v[32:35], s[88:89]
	s_waitcnt vmcnt(7)
	s_waitcnt lgkmcnt(4)
	v_fma_f32 v40, v208, v40, v192
	v_fma_f32 v41, v209, v41, v193
	v_fma_f32 v42, v210, v42, v194
	v_fma_f32 v43, v211, v43, v195
	v_fma_f32 v44, v212, v44, v196
	v_fma_f32 v45, v213, v45, v197
	v_fma_f32 v46, v214, v46, v198
	v_fma_f32 v47, v215, v47, v199
	v_cvt_pk_bf16_f32 v40, v40, v41
	v_cvt_pk_bf16_f32 v41, v42, v43
	v_cvt_pk_bf16_f32 v42, v44, v45
	v_cvt_pk_bf16_f32 v43, v46, v47
	v_add_u32_e32 v96, 163840, v108
	global_store_dwordx4 v96, v[40:43], s[88:89]
	s_waitcnt vmcnt(8)
	s_waitcnt lgkmcnt(2)
	v_fma_f32 v48, v208, v48, v200
	v_fma_f32 v49, v209, v49, v201
	v_fma_f32 v50, v210, v50, v202
	v_fma_f32 v51, v211, v51, v203
	v_fma_f32 v52, v212, v52, v250
	v_fma_f32 v53, v213, v53, v251
	v_fma_f32 v54, v214, v54, v252
	v_fma_f32 v55, v215, v55, v253
	v_cvt_pk_bf16_f32 v48, v48, v49
	v_cvt_pk_bf16_f32 v49, v50, v51
	v_cvt_pk_bf16_f32 v50, v52, v53
	v_cvt_pk_bf16_f32 v51, v54, v55
	v_add_u32_e32 v96, 196608, v108
	global_store_dwordx4 v96, v[48:51], s[88:89]
	s_waitcnt vmcnt(7)
	s_waitcnt lgkmcnt(0)
	v_fma_f32 v56, v208, v56, v216
	v_fma_f32 v57, v209, v57, v217
	v_fma_f32 v58, v210, v58, v218
	v_fma_f32 v59, v211, v59, v219
	v_fma_f32 v60, v212, v60, v220
	v_fma_f32 v61, v213, v61, v221
	v_fma_f32 v62, v214, v62, v222
	v_fma_f32 v63, v215, v63, v223
	v_cvt_pk_bf16_f32 v56, v56, v57
	v_cvt_pk_bf16_f32 v57, v58, v59
	v_cvt_pk_bf16_f32 v58, v60, v61
	v_cvt_pk_bf16_f32 v59, v62, v63
	v_add_u32_e32 v96, 229376, v108
	global_store_dwordx4 v96, v[56:59], s[88:89]
	s_branch .LBB0_624
